# v11 + trailing half's deferred re-offset barrier moved after its first load segment of the peeled iteration (runs concurrently with leading half's)
# baseline (speedup 1.0000x reference)
; #define PG8_STAGE(bufoff, gbase, voff) do { _Pragma("unroll") for (int _i = 0; _i < 2; ++_i) \
;         __builtin_amdgcn_global_load_lds((const unsigned*)((const char*)(gbase) + (voff)[_i]), (PG8_LAS unsigned*)(lds + (bufoff) + ldsw + _i * 8192), 16, 0, 0); } while (0)
; #define PG8_LDA(dst, b, h) do { _Pragma("unroll") for (int m = 0; m < 4; ++m) _Pragma("unroll") for (int k = 0; k < 2; ++k) dst[m][k] = *(const PG8_LAS bf16x8*)(lds + PG8_SA(b, h) + aoff + m * 2048 + k * 1024); } while (0)
; #define PG8_LDB(dst, b, h) do { _Pragma("unroll") for (int n = 0; n < 2; ++n) _Pragma("unroll") for (int k = 0; k < 2; ++k) dst[n][k] = *(const PG8_LAS bf16x8*)(lds + PG8_SB(b, h) + boff + n * 2048 + k * 1024); } while (0)
; #define PG8_MMA(ai, bj, At, Bt) do { __builtin_amdgcn_s_setprio(1); _Pragma("unroll") for (int m = 0; m < 4; ++m) _Pragma("unroll") for (int n = 0; n < 2; ++n) _Pragma("unroll") for (int k = 0; k < 2; ++k) \
;         acc[ai][bj][m][n] = __builtin_amdgcn_mfma_f32_16x16x32_bf16(Bt[n][k], At[m][k], acc[ai][bj][m][n], 0, 0, 0); __builtin_amdgcn_s_setprio(0); } while (0)
; #define PG8_WAIT_V(n) asm volatile("s_waitcnt vmcnt(" #n ")" ::: "memory")
; template <class Epi, class Sched, bool ALIGN_EPI = false, bool SP2 = false>
; __device__ __forceinline__ void gemm_phase(PG8_LAS unsigned char* lds, const Gemm g, const Sched& S, const Epi& E, int tid_in) {
;     ...
;         const char* nA = has_next ? (const char*)g.A + (size_t)nxt.pm * tstep : cA; const char* nB = has_next ? (const char*)g.Bt + (size_t)nxt.pn * tstepB : cB;
;         for (int t = 0; t < nt; t += 2) {
;             const bool last = (t == nt - 2);
;             const char* a1 = cA + (size_t)(t + 1) * kstep;
;             const char* a2 = last ? nA : cA + (size_t)(t + 2) * kstep; const char* b2 = last ? nB : cB + (size_t)(t + 2) * kstep;
;             const char* a3 = a2 + kstep; const char* b3 = b2 + kstep;
;             if (last && has_next) S.a_ready(nxt);
;             if constexpr (SP2) {
;             PG8_LDB(B0, 0, 0); PG8_LDB(B1, 0, 1); PG8_SCHED; PG8_LDA(At, 0, 0); PG8_STAGE(PG8_SA(1, 1), a1 + hstep, voffA);
;             PG8_WAIT_V(8); PG8_WAIT_L(0); PG8_BAR; PG8_MMA(0, 0, At, B0); PG8_MMA(0, 1, At, B1); PG8_BAR; PG8_SCHED;
;             PG8_LDA(At, 0, 1); PG8_STAGE(PG8_SB(0, 0), b2, voffB); PG8_STAGE(PG8_SB(0, 1), b2 + hstepB, voffB); PG8_STAGE(PG8_SA(0, 0), a2, voffA);
.LBB0_79:
	s_ashr_i32 s41, s40, 31
	s_lshl_b64 s[26:27], s[40:41], 20
	s_add_u32 s42, s28, s26
	s_addc_u32 s43, s29, s27
	s_and_b64 s[26:27], s[6:7], exec
	s_cselect_b32 s41, s43, s49
	s_cselect_b32 s70, s42, s48
	s_ashr_i32 s39, s38, 31
	s_lshl_b64 s[26:27], s[38:39], 20
	s_add_u32 s44, s36, s26
	s_addc_u32 s45, s37, s27
	s_and_b64 s[26:27], s[6:7], exec
	s_cselect_b32 s39, s45, s51
	s_cselect_b32 s71, s44, s50
	s_add_u32 s48, s48, 0x80080
	s_addc_u32 s49, s49, 0
	s_add_u32 s74, s50, 0x100
	s_addc_u32 s75, s51, 0
	s_mov_b32 s76, -2
	ds_read_b128 v[156:159], v150
	ds_read_b128 v[160:163], v150 offset:1024
	ds_read_b128 v[164:167], v150 offset:2048
	ds_read_b128 v[168:171], v150 offset:3072
	ds_read_b128 v[172:175], v151
	ds_read_b128 v[176:179], v151 offset:1024
	ds_read_b128 v[180:183], v151 offset:2048
	ds_read_b128 v[184:187], v151 offset:3072
	s_add_u32 s26, s48, 0xfff80080
	s_addc_u32 s27, s49, -1
	s_cmp_eq_u32 s76, 28
	s_cselect_b32 s53, s41, s27
	s_cselect_b32 s52, s70, s26
	s_cselect_b32 s51, s39, s75
	s_cselect_b32 s50, s71, s74
	s_add_i32 m0, s47, 0xc000
	ds_read_b128 v[188:191], v152
	ds_read_b128 v[192:195], v152 offset:1024
	ds_read_b128 v[196:199], v152 offset:2048
	ds_read_b128 v[200:203], v152 offset:3072
	ds_read_b128 v[212:215], v152 offset:4096
	ds_read_b128 v[216:219], v152 offset:5120
	ds_read_b128 v[220:223], v152 offset:6144
	ds_read_b128 v[224:227], v152 offset:7168
	global_load_lds_dwordx4 v138, s[48:49]
	s_add_i32 m0, s47, 0xe000
	s_nop 0
	global_load_lds_dwordx4 v140, s[48:49]
	s_waitcnt vmcnt(8)
	s_waitcnt lgkmcnt(0)
	s_cmp_eq_u32 s98, 1
	s_cbranch_scc0 .Lkb_skip_0
	s_mov_b32 s98, 0
	s_barrier
.Lkb_skip_0:
	s_barrier
	s_setprio 1
	s_waitcnt lgkmcnt(0)
	v_mfma_f32_16x16x32_bf16 v[124:127], v[156:159], v[188:191], 0
	v_mfma_f32_16x16x32_bf16 v[120:123], v[164:167], v[188:191], 0
	v_mfma_f32_16x16x32_bf16 v[108:111], v[156:159], v[196:199], 0
	v_mfma_f32_16x16x32_bf16 v[104:107], v[164:167], v[196:199], 0
	v_mfma_f32_16x16x32_bf16 v[92:95], v[156:159], v[212:215], 0
	v_mfma_f32_16x16x32_bf16 v[88:91], v[164:167], v[212:215], 0
	v_mfma_f32_16x16x32_bf16 v[76:79], v[156:159], v[220:223], 0
	v_mfma_f32_16x16x32_bf16 v[72:75], v[164:167], v[220:223], 0
	v_mfma_f32_16x16x32_bf16 v[124:127], v[160:163], v[192:195], v[124:127]
	v_mfma_f32_16x16x32_bf16 v[120:123], v[168:171], v[192:195], v[120:123]
	v_mfma_f32_16x16x32_bf16 v[108:111], v[160:163], v[200:203], v[108:111]
	v_mfma_f32_16x16x32_bf16 v[104:107], v[168:171], v[200:203], v[104:107]
	v_mfma_f32_16x16x32_bf16 v[92:95], v[160:163], v[216:219], v[92:95]
	v_mfma_f32_16x16x32_bf16 v[88:91], v[168:171], v[216:219], v[88:91]
	v_mfma_f32_16x16x32_bf16 v[76:79], v[160:163], v[224:227], v[76:79]
	v_mfma_f32_16x16x32_bf16 v[72:75], v[168:171], v[224:227], v[72:75]
	s_setprio 0
	s_setprio 1
	v_mfma_f32_16x16x32_bf16 v[116:119], v[172:175], v[188:191], 0
	v_mfma_f32_16x16x32_bf16 v[112:115], v[180:183], v[188:191], 0
	v_mfma_f32_16x16x32_bf16 v[100:103], v[172:175], v[196:199], 0
	v_mfma_f32_16x16x32_bf16 v[96:99], v[180:183], v[196:199], 0
	v_mfma_f32_16x16x32_bf16 v[84:87], v[172:175], v[212:215], 0
	v_mfma_f32_16x16x32_bf16 v[80:83], v[180:183], v[212:215], 0
	v_mfma_f32_16x16x32_bf16 v[68:71], v[172:175], v[220:223], 0
	v_mfma_f32_16x16x32_bf16 v[64:67], v[180:183], v[220:223], 0
	v_mfma_f32_16x16x32_bf16 v[116:119], v[176:179], v[192:195], v[116:119]
	v_mfma_f32_16x16x32_bf16 v[112:115], v[184:187], v[192:195], v[112:115]
	v_mfma_f32_16x16x32_bf16 v[100:103], v[176:179], v[200:203], v[100:103]
	v_mfma_f32_16x16x32_bf16 v[96:99], v[184:187], v[200:203], v[96:99]
	v_mfma_f32_16x16x32_bf16 v[84:87], v[176:179], v[216:219], v[84:87]
	v_mfma_f32_16x16x32_bf16 v[80:83], v[184:187], v[216:219], v[80:83]
	v_mfma_f32_16x16x32_bf16 v[68:71], v[176:179], v[224:227], v[68:71]
	v_mfma_f32_16x16x32_bf16 v[64:67], v[184:187], v[224:227], v[64:67]
	s_setprio 0
	s_barrier
	s_add_i32 s26, s67, s54
	s_mov_b32 m0, s26
	ds_read_b128 v[188:191], v152 offset:16384
	ds_read_b128 v[192:195], v152 offset:17408
	ds_read_b128 v[196:199], v152 offset:18432
	ds_read_b128 v[200:203], v152 offset:19456
	ds_read_b128 v[212:215], v152 offset:20480
	ds_read_b128 v[216:219], v152 offset:21504
	ds_read_b128 v[220:223], v152 offset:22528
	ds_read_b128 v[224:227], v152 offset:23552
	global_load_lds_dwordx4 v132, s[50:51]
	s_add_i32 m0, s26, 0x2000
	s_add_u32 s26, s50, 0x20000
	s_addc_u32 s27, s51, 0
	s_add_i32 s33, s68, s54
	global_load_lds_dwordx4 v128, s[50:51]
	s_mov_b32 m0, s33
	s_nop 0
	global_load_lds_dwordx4 v132, s[26:27]
	s_add_i32 m0, s33, 0x2000
	s_nop 0
	global_load_lds_dwordx4 v128, s[26:27]
	s_mov_b32 m0, s47
	s_nop 0
	global_load_lds_dwordx4 v134, s[52:53]
	s_mov_b32 m0, s56
	s_nop 0
	global_load_lds_dwordx4 v130, s[52:53]
	s_waitcnt vmcnt(8)
	s_waitcnt lgkmcnt(0)
	s_barrier
; #define PG8_STAGE(bufoff, gbase, voff) do { _Pragma("unroll") for (int _i = 0; _i < 2; ++_i) \
;         __builtin_amdgcn_global_load_lds((const unsigned*)((const char*)(gbase) + (voff)[_i]), (PG8_LAS unsigned*)(lds + (bufoff) + ldsw + _i * 8192), 16, 0, 0); } while (0)
; #define PG8_LDA(dst, b, h) do { _Pragma("unroll") for (int m = 0; m < 4; ++m) _Pragma("unroll") for (int k = 0; k < 2; ++k) dst[m][k] = *(const PG8_LAS bf16x8*)(lds + PG8_SA(b, h) + aoff + m * 2048 + k * 1024); } while (0)
; #define PG8_LDB(dst, b, h) do { _Pragma("unroll") for (int n = 0; n < 2; ++n) _Pragma("unroll") for (int k = 0; k < 2; ++k) dst[n][k] = *(const PG8_LAS bf16x8*)(lds + PG8_SB(b, h) + boff + n * 2048 + k * 1024); } while (0)
; #define PG8_MMA(ai, bj, At, Bt) do { __builtin_amdgcn_s_setprio(1); _Pragma("unroll") for (int m = 0; m < 4; ++m) _Pragma("unroll") for (int n = 0; n < 2; ++n) _Pragma("unroll") for (int k = 0; k < 2; ++k) \
;         acc[ai][bj][m][n] = __builtin_amdgcn_mfma_f32_16x16x32_bf16(Bt[n][k], At[m][k], acc[ai][bj][m][n], 0, 0, 0); __builtin_amdgcn_s_setprio(0); } while (0)
; #define PG8_WAIT_V(n) asm volatile("s_waitcnt vmcnt(" #n ")" ::: "memory")
; #define PG8_WAIT_L(n) asm volatile("s_waitcnt lgkmcnt(" #n ")" ::: "memory")
; #define PG8_BAR __builtin_amdgcn_s_barrier()
; #define PG8_SCHED __builtin_amdgcn_sched_barrier(0)
; template <class Epi, class Sched, bool ALIGN_EPI = false, bool SP2 = false>
; __device__ __forceinline__ void gemm_phase(PG8_LAS unsigned char* lds, const Gemm g, const Sched& S, const Epi& E, int tid_in) {
;     ...
;             PG8_WAIT_V(8); PG8_WAIT_L(0); PG8_BAR; PG8_MMA(0, 0, At, B0); PG8_MMA(0, 1, At, B1); PG8_BAR; PG8_SCHED;
;             PG8_LDA(At, 0, 1); PG8_STAGE(PG8_SB(0, 0), b2, voffB); PG8_STAGE(PG8_SB(0, 1), b2 + hstepB, voffB); PG8_STAGE(PG8_SA(0, 0), a2, voffA);
;             PG8_WAIT_V(8); PG8_WAIT_L(0); PG8_BAR; PG8_MMA(1, 0, At, B0); PG8_MMA(1, 1, At, B1); PG8_BAR; PG8_SCHED;
;             PG8_LDB(B0, 1, 0); PG8_LDB(B1, 1, 1); PG8_SCHED; PG8_LDA(At, 1, 0); PG8_STAGE(PG8_SA(0, 1), a2 + hstep, voffA);
;             PG8_WAIT_V(8); PG8_WAIT_L(0); PG8_BAR; PG8_MMA(0, 0, At, B0); PG8_MMA(0, 1, At, B1); PG8_BAR; PG8_SCHED;
;             PG8_LDA(At, 1, 1); PG8_STAGE(PG8_SB(1, 0), b3, voffB); PG8_STAGE(PG8_SB(1, 1), b3 + hstepB, voffB); PG8_STAGE(PG8_SA(1, 0), a3, voffA);
	s_setprio 1
	s_waitcnt lgkmcnt(0)
	v_mfma_f32_16x16x32_bf16 v[60:63], v[156:159], v[188:191], 0
	v_mfma_f32_16x16x32_bf16 v[56:59], v[164:167], v[188:191], 0
	v_mfma_f32_16x16x32_bf16 v[44:47], v[156:159], v[196:199], 0
	v_mfma_f32_16x16x32_bf16 v[40:43], v[164:167], v[196:199], 0
	v_mfma_f32_16x16x32_bf16 v[28:31], v[156:159], v[212:215], 0
	v_mfma_f32_16x16x32_bf16 v[24:27], v[164:167], v[212:215], 0
	v_mfma_f32_16x16x32_bf16 v[12:15], v[156:159], v[220:223], 0
	v_mfma_f32_16x16x32_bf16 v[8:11], v[164:167], v[220:223], 0
	v_mfma_f32_16x16x32_bf16 v[60:63], v[160:163], v[192:195], v[60:63]
	v_mfma_f32_16x16x32_bf16 v[56:59], v[168:171], v[192:195], v[56:59]
	v_mfma_f32_16x16x32_bf16 v[44:47], v[160:163], v[200:203], v[44:47]
	v_mfma_f32_16x16x32_bf16 v[40:43], v[168:171], v[200:203], v[40:43]
	v_mfma_f32_16x16x32_bf16 v[28:31], v[160:163], v[216:219], v[28:31]
	v_mfma_f32_16x16x32_bf16 v[24:27], v[168:171], v[216:219], v[24:27]
	v_mfma_f32_16x16x32_bf16 v[12:15], v[160:163], v[224:227], v[12:15]
	v_mfma_f32_16x16x32_bf16 v[8:11], v[168:171], v[224:227], v[8:11]
	s_setprio 0
	s_setprio 1
	v_mfma_f32_16x16x32_bf16 v[52:55], v[172:175], v[188:191], 0
	v_mfma_f32_16x16x32_bf16 v[48:51], v[180:183], v[188:191], 0
	v_mfma_f32_16x16x32_bf16 v[36:39], v[172:175], v[196:199], 0
	v_mfma_f32_16x16x32_bf16 v[32:35], v[180:183], v[196:199], 0
	v_mfma_f32_16x16x32_bf16 v[20:23], v[172:175], v[212:215], 0
	v_mfma_f32_16x16x32_bf16 v[16:19], v[180:183], v[212:215], 0
	v_mfma_f32_16x16x32_bf16 v[4:7], v[172:175], v[220:223], 0
	v_mfma_f32_16x16x32_bf16 v[0:3], v[180:183], v[220:223], 0
	v_mfma_f32_16x16x32_bf16 v[52:55], v[176:179], v[192:195], v[52:55]
	v_mfma_f32_16x16x32_bf16 v[48:51], v[184:187], v[192:195], v[48:51]
	v_mfma_f32_16x16x32_bf16 v[36:39], v[176:179], v[200:203], v[36:39]
	v_mfma_f32_16x16x32_bf16 v[32:35], v[184:187], v[200:203], v[32:35]
	v_mfma_f32_16x16x32_bf16 v[20:23], v[176:179], v[216:219], v[20:23]
	v_mfma_f32_16x16x32_bf16 v[16:19], v[184:187], v[216:219], v[16:19]
	v_mfma_f32_16x16x32_bf16 v[4:7], v[176:179], v[224:227], v[4:7]
	v_mfma_f32_16x16x32_bf16 v[0:3], v[184:187], v[224:227], v[0:3]
	s_setprio 0
	s_barrier
	s_add_i32 s33, 0, 0x18000
	v_add_u32_e32 v155, s33, v146
	s_add_i32 s77, 0, 0x1c000
	ds_read_b128 v[156:159], v155
	ds_read_b128 v[160:163], v155 offset:1024
	ds_read_b128 v[164:167], v155 offset:2048
	ds_read_b128 v[168:171], v155 offset:3072
	v_add_u32_e32 v155, s77, v146
	ds_read_b128 v[172:175], v155
	ds_read_b128 v[176:179], v155 offset:1024
	ds_read_b128 v[180:183], v155 offset:2048
	ds_read_b128 v[184:187], v155 offset:3072
	s_add_u32 s26, s52, 0x80000
	s_addc_u32 s27, s53, 0
	s_mov_b32 m0, s57
	ds_read_b128 v[188:191], v152 offset:32768
	ds_read_b128 v[192:195], v152 offset:33792
	ds_read_b128 v[196:199], v152 offset:34816
	ds_read_b128 v[200:203], v152 offset:35840
	ds_read_b128 v[212:215], v152 offset:36864
	ds_read_b128 v[216:219], v152 offset:37888
	ds_read_b128 v[220:223], v152 offset:38912
	ds_read_b128 v[224:227], v152 offset:39936
	global_load_lds_dwordx4 v134, s[26:27]
	s_mov_b32 m0, s58
	s_nop 0
	global_load_lds_dwordx4 v130, s[26:27]
	s_waitcnt vmcnt(8)
	s_waitcnt lgkmcnt(0)
	s_barrier
	s_setprio 1
	s_waitcnt lgkmcnt(0)
	v_mfma_f32_16x16x32_bf16 v[124:127], v[156:159], v[188:191], v[124:127]
	v_mfma_f32_16x16x32_bf16 v[120:123], v[164:167], v[188:191], v[120:123]
	v_mfma_f32_16x16x32_bf16 v[108:111], v[156:159], v[196:199], v[108:111]
	v_mfma_f32_16x16x32_bf16 v[104:107], v[164:167], v[196:199], v[104:107]
	v_mfma_f32_16x16x32_bf16 v[92:95], v[156:159], v[212:215], v[92:95]
	v_mfma_f32_16x16x32_bf16 v[88:91], v[164:167], v[212:215], v[88:91]
	v_mfma_f32_16x16x32_bf16 v[76:79], v[156:159], v[220:223], v[76:79]
	v_mfma_f32_16x16x32_bf16 v[72:75], v[164:167], v[220:223], v[72:75]
	v_mfma_f32_16x16x32_bf16 v[124:127], v[160:163], v[192:195], v[124:127]
	v_mfma_f32_16x16x32_bf16 v[120:123], v[168:171], v[192:195], v[120:123]
	v_mfma_f32_16x16x32_bf16 v[108:111], v[160:163], v[200:203], v[108:111]
	v_mfma_f32_16x16x32_bf16 v[104:107], v[168:171], v[200:203], v[104:107]
	v_mfma_f32_16x16x32_bf16 v[92:95], v[160:163], v[216:219], v[92:95]
	v_mfma_f32_16x16x32_bf16 v[88:91], v[168:171], v[216:219], v[88:91]
	v_mfma_f32_16x16x32_bf16 v[76:79], v[160:163], v[224:227], v[76:79]
	v_mfma_f32_16x16x32_bf16 v[72:75], v[168:171], v[224:227], v[72:75]
	s_setprio 0
	s_setprio 1
	v_mfma_f32_16x16x32_bf16 v[116:119], v[172:175], v[188:191], v[116:119]
	v_mfma_f32_16x16x32_bf16 v[112:115], v[180:183], v[188:191], v[112:115]
	v_mfma_f32_16x16x32_bf16 v[100:103], v[172:175], v[196:199], v[100:103]
	v_mfma_f32_16x16x32_bf16 v[96:99], v[180:183], v[196:199], v[96:99]
	v_mfma_f32_16x16x32_bf16 v[84:87], v[172:175], v[212:215], v[84:87]
	v_mfma_f32_16x16x32_bf16 v[80:83], v[180:183], v[212:215], v[80:83]
	v_mfma_f32_16x16x32_bf16 v[68:71], v[172:175], v[220:223], v[68:71]
	v_mfma_f32_16x16x32_bf16 v[64:67], v[180:183], v[220:223], v[64:67]
	v_mfma_f32_16x16x32_bf16 v[116:119], v[176:179], v[192:195], v[116:119]
	v_mfma_f32_16x16x32_bf16 v[112:115], v[184:187], v[192:195], v[112:115]
	v_mfma_f32_16x16x32_bf16 v[100:103], v[176:179], v[200:203], v[100:103]
	v_mfma_f32_16x16x32_bf16 v[96:99], v[184:187], v[200:203], v[96:99]
	v_mfma_f32_16x16x32_bf16 v[84:87], v[176:179], v[216:219], v[84:87]
	v_mfma_f32_16x16x32_bf16 v[80:83], v[184:187], v[216:219], v[80:83]
	v_mfma_f32_16x16x32_bf16 v[68:71], v[176:179], v[224:227], v[68:71]
	v_mfma_f32_16x16x32_bf16 v[64:67], v[184:187], v[224:227], v[64:67]
	s_setprio 0
	s_barrier
; #define PG8_STAGE(bufoff, gbase, voff) do { _Pragma("unroll") for (int _i = 0; _i < 2; ++_i) \
;         __builtin_amdgcn_global_load_lds((const unsigned*)((const char*)(gbase) + (voff)[_i]), (PG8_LAS unsigned*)(lds + (bufoff) + ldsw + _i * 8192), 16, 0, 0); } while (0)
; #define PG8_LDA(dst, b, h) do { _Pragma("unroll") for (int m = 0; m < 4; ++m) _Pragma("unroll") for (int k = 0; k < 2; ++k) dst[m][k] = *(const PG8_LAS bf16x8*)(lds + PG8_SA(b, h) + aoff + m * 2048 + k * 1024); } while (0)
; #define PG8_MMA(ai, bj, At, Bt) do { __builtin_amdgcn_s_setprio(1); _Pragma("unroll") for (int m = 0; m < 4; ++m) _Pragma("unroll") for (int n = 0; n < 2; ++n) _Pragma("unroll") for (int k = 0; k < 2; ++k) \
;         acc[ai][bj][m][n] = __builtin_amdgcn_mfma_f32_16x16x32_bf16(Bt[n][k], At[m][k], acc[ai][bj][m][n], 0, 0, 0); __builtin_amdgcn_s_setprio(0); } while (0)
; #define PG8_WAIT_V(n) asm volatile("s_waitcnt vmcnt(" #n ")" ::: "memory")
; #define PG8_WAIT_L(n) asm volatile("s_waitcnt lgkmcnt(" #n ")" ::: "memory")
; #define PG8_BAR __builtin_amdgcn_s_barrier()
; #define PG8_SCHED __builtin_amdgcn_sched_barrier(0)
; template <class Epi, class Sched, bool ALIGN_EPI = false, bool SP2 = false>
; __device__ __forceinline__ void gemm_phase(PG8_LAS unsigned char* lds, const Gemm g, const Sched& S, const Epi& E, int tid_in) {
;     ...
;             PG8_LDA(At, 1, 1); PG8_STAGE(PG8_SB(1, 0), b3, voffB); PG8_STAGE(PG8_SB(1, 1), b3 + hstepB, voffB); PG8_STAGE(PG8_SA(1, 0), a3, voffA);
;             PG8_WAIT_V(8); PG8_WAIT_L(0); PG8_BAR; PG8_MMA(1, 0, At, B0); PG8_MMA(1, 1, At, B1); PG8_BAR; PG8_SCHED;
	s_add_i32 s26, s33, s54
	s_add_i32 m0, s26, 0xffffff80
	ds_read_b128 v[188:191], v152 offset:49152
	ds_read_b128 v[192:195], v152 offset:50176
	ds_read_b128 v[196:199], v152 offset:51200
	ds_read_b128 v[200:203], v152 offset:52224
	ds_read_b128 v[212:215], v152 offset:53248
	ds_read_b128 v[216:219], v152 offset:54272
	ds_read_b128 v[220:223], v152 offset:55296
	ds_read_b128 v[224:227], v152 offset:56320
	global_load_lds_dwordx4 v132, s[50:51] offset:128
	s_add_i32 m0, s26, 0x1f80
	s_add_u32 s26, s50, 0x20080
	s_addc_u32 s27, s51, 0
	s_add_i32 s33, s77, s54
	global_load_lds_dwordx4 v128, s[50:51] offset:128
	s_mov_b32 m0, s33
	s_nop 0
	global_load_lds_dwordx4 v132, s[26:27]
	s_add_i32 m0, s33, 0x2000
	s_nop 0
	global_load_lds_dwordx4 v128, s[26:27]
	s_add_i32 m0, s61, 0xffffff80
	s_nop 0
	global_load_lds_dwordx4 v134, s[52:53] offset:128
	s_add_i32 m0, s62, 0xffffff80
	s_nop 0
	global_load_lds_dwordx4 v130, s[52:53] offset:128
	s_waitcnt vmcnt(8)
	s_waitcnt lgkmcnt(0)
	s_barrier
	s_setprio 1
	s_waitcnt lgkmcnt(0)
	v_mfma_f32_16x16x32_bf16 v[60:63], v[156:159], v[188:191], v[60:63]
	v_mfma_f32_16x16x32_bf16 v[56:59], v[164:167], v[188:191], v[56:59]
	v_mfma_f32_16x16x32_bf16 v[44:47], v[156:159], v[196:199], v[44:47]
	v_mfma_f32_16x16x32_bf16 v[40:43], v[164:167], v[196:199], v[40:43]
	v_mfma_f32_16x16x32_bf16 v[28:31], v[156:159], v[212:215], v[28:31]
	v_mfma_f32_16x16x32_bf16 v[24:27], v[164:167], v[212:215], v[24:27]
	v_mfma_f32_16x16x32_bf16 v[12:15], v[156:159], v[220:223], v[12:15]
	v_mfma_f32_16x16x32_bf16 v[8:11], v[164:167], v[220:223], v[8:11]
	v_mfma_f32_16x16x32_bf16 v[60:63], v[160:163], v[192:195], v[60:63]
	v_mfma_f32_16x16x32_bf16 v[56:59], v[168:171], v[192:195], v[56:59]
	v_mfma_f32_16x16x32_bf16 v[44:47], v[160:163], v[200:203], v[44:47]
	v_mfma_f32_16x16x32_bf16 v[40:43], v[168:171], v[200:203], v[40:43]
	v_mfma_f32_16x16x32_bf16 v[28:31], v[160:163], v[216:219], v[28:31]
	v_mfma_f32_16x16x32_bf16 v[24:27], v[168:171], v[216:219], v[24:27]
	v_mfma_f32_16x16x32_bf16 v[12:15], v[160:163], v[224:227], v[12:15]
	v_mfma_f32_16x16x32_bf16 v[8:11], v[168:171], v[224:227], v[8:11]
	s_setprio 0
	s_setprio 1
	v_mfma_f32_16x16x32_bf16 v[52:55], v[172:175], v[188:191], v[52:55]
	v_mfma_f32_16x16x32_bf16 v[48:51], v[180:183], v[188:191], v[48:51]
	v_mfma_f32_16x16x32_bf16 v[36:39], v[172:175], v[196:199], v[36:39]
	v_mfma_f32_16x16x32_bf16 v[32:35], v[180:183], v[196:199], v[32:35]
	v_mfma_f32_16x16x32_bf16 v[20:23], v[172:175], v[212:215], v[20:23]
	v_mfma_f32_16x16x32_bf16 v[16:19], v[180:183], v[212:215], v[16:19]
	v_mfma_f32_16x16x32_bf16 v[4:7], v[172:175], v[220:223], v[4:7]
	v_mfma_f32_16x16x32_bf16 v[0:3], v[180:183], v[220:223], v[0:3]
	v_mfma_f32_16x16x32_bf16 v[52:55], v[176:179], v[192:195], v[52:55]
	v_mfma_f32_16x16x32_bf16 v[48:51], v[184:187], v[192:195], v[48:51]
	v_mfma_f32_16x16x32_bf16 v[36:39], v[176:179], v[200:203], v[36:39]
	v_mfma_f32_16x16x32_bf16 v[32:35], v[184:187], v[200:203], v[32:35]
	v_mfma_f32_16x16x32_bf16 v[20:23], v[176:179], v[216:219], v[20:23]
	v_mfma_f32_16x16x32_bf16 v[16:19], v[184:187], v[216:219], v[16:19]
	v_mfma_f32_16x16x32_bf16 v[4:7], v[176:179], v[224:227], v[4:7]
	v_mfma_f32_16x16x32_bf16 v[0:3], v[184:187], v[224:227], v[0:3]
	s_setprio 0
	s_barrier
	s_add_i32 s76, s76, 2
	s_add_u32 s48, s48, 0x100
	s_addc_u32 s49, s49, 0
	s_add_u32 s74, s74, 0x100
	s_addc_u32 s75, s75, 0
	s_cmp_gt_u32 s76, 29

; #define PG8_STAGE(bufoff, gbase, voff) do { _Pragma("unroll") for (int _i = 0; _i < 2; ++_i) \
;         __builtin_amdgcn_global_load_lds((const unsigned*)((const char*)(gbase) + (voff)[_i]), (PG8_LAS unsigned*)(lds + (bufoff) + ldsw + _i * 8192), 16, 0, 0); } while (0)
; #define PG8_LDA(dst, b, h) do { _Pragma("unroll") for (int m = 0; m < 4; ++m) _Pragma("unroll") for (int k = 0; k < 2; ++k) dst[m][k] = *(const PG8_LAS bf16x8*)(lds + PG8_SA(b, h) + aoff + m * 2048 + k * 1024); } while (0)
; #define PG8_LDB(dst, b, h) do { _Pragma("unroll") for (int n = 0; n < 2; ++n) _Pragma("unroll") for (int k = 0; k < 2; ++k) dst[n][k] = *(const PG8_LAS bf16x8*)(lds + PG8_SB(b, h) + boff + n * 2048 + k * 1024); } while (0)
; #define PG8_MMA(ai, bj, At, Bt) do { __builtin_amdgcn_s_setprio(1); _Pragma("unroll") for (int m = 0; m < 4; ++m) _Pragma("unroll") for (int n = 0; n < 2; ++n) _Pragma("unroll") for (int k = 0; k < 2; ++k) \
;         acc[ai][bj][m][n] = __builtin_amdgcn_mfma_f32_16x16x32_bf16(Bt[n][k], At[m][k], acc[ai][bj][m][n], 0, 0, 0); __builtin_amdgcn_s_setprio(0); } while (0)
; #define PG8_WAIT_V(n) asm volatile("s_waitcnt vmcnt(" #n ")" ::: "memory")
; template <class Epi, class Sched, bool ALIGN_EPI = false, bool SP2 = false>
; __device__ __forceinline__ void gemm_phase(PG8_LAS unsigned char* lds, const Gemm g, const Sched& S, const Epi& E, int tid_in) {
;     ...
;         const char* nA = has_next ? (const char*)g.A + (size_t)nxt.pm * tstep : cA; const char* nB = has_next ? (const char*)g.Bt + (size_t)nxt.pn * tstepB : cB;
;         for (int t = 0; t < nt; t += 2) {
;             const bool last = (t == nt - 2);
;             const char* a1 = cA + (size_t)(t + 1) * kstep;
;             const char* a2 = last ? nA : cA + (size_t)(t + 2) * kstep; const char* b2 = last ? nB : cB + (size_t)(t + 2) * kstep;
;             const char* a3 = a2 + kstep; const char* b3 = b2 + kstep;
;             if (last && has_next) S.a_ready(nxt);
;             if constexpr (SP2) {
;             PG8_LDB(B0, 0, 0); PG8_LDB(B1, 0, 1); PG8_SCHED; PG8_LDA(At, 0, 0); PG8_STAGE(PG8_SA(1, 1), a1 + hstep, voffA);
;             PG8_WAIT_V(8); PG8_WAIT_L(0); PG8_BAR; PG8_MMA(0, 0, At, B0); PG8_MMA(0, 1, At, B1); PG8_BAR; PG8_SCHED;
;             PG8_LDA(At, 0, 1); PG8_STAGE(PG8_SB(0, 0), b2, voffB); PG8_STAGE(PG8_SB(0, 1), b2 + hstepB, voffB); PG8_STAGE(PG8_SA(0, 0), a2, voffA);
.LBB0_291:
	s_ashr_i32 s49, s48, 31
	s_lshl_b64 s[26:27], s[48:49], 20
	s_add_u32 s50, s28, s26
	s_addc_u32 s51, s29, s27
	s_and_b64 s[26:27], s[10:11], exec
	s_cselect_b32 s49, s51, s59
	s_cselect_b32 s55, s50, s58
	s_ashr_i32 s47, s46, 31
	s_lshl_b64 s[26:27], s[46:47], 20
	s_add_u32 s52, s64, s26
	s_addc_u32 s53, s65, s27
	s_and_b64 s[26:27], s[10:11], exec
	s_cselect_b32 s47, s53, s61
	s_cselect_b32 s75, s52, s60
	s_add_u32 s58, s58, 0x80080
	s_addc_u32 s59, s59, 0
	s_add_u32 s76, s60, 0x100
	s_addc_u32 s77, s61, 0
	s_mov_b32 s79, -2
	s_waitcnt lgkmcnt(0)
	ds_read_b128 v[146:149], v153
	ds_read_b128 v[158:161], v153 offset:1024
	ds_read_b128 v[162:165], v153 offset:2048
	ds_read_b128 v[166:169], v153 offset:3072
	ds_read_b128 v[170:173], v154
	ds_read_b128 v[174:177], v154 offset:1024
	ds_read_b128 v[178:181], v154 offset:2048
	ds_read_b128 v[182:185], v154 offset:3072
	s_add_u32 s26, s58, 0xfff80080
	s_addc_u32 s27, s59, -1
	s_cmp_eq_u32 s79, 28
	s_cselect_b32 s63, s49, s27
	s_cselect_b32 s62, s55, s26
	s_cselect_b32 s61, s47, s77
	s_cselect_b32 s60, s75, s76
	s_add_i32 m0, s57, 0xc000
	ds_read_b128 v[186:189], v155
	ds_read_b128 v[190:193], v155 offset:1024
	ds_read_b128 v[194:197], v155 offset:2048
	ds_read_b128 v[198:201], v155 offset:3072
	ds_read_b128 v[202:205], v155 offset:4096
	ds_read_b128 v[206:209], v155 offset:5120
	ds_read_b128 v[212:215], v155 offset:6144
	ds_read_b128 v[216:219], v155 offset:7168
	global_load_lds_dwordx4 v138, s[58:59]
	s_add_i32 m0, s57, 0xe000
	s_nop 0
	global_load_lds_dwordx4 v140, s[58:59]
	s_waitcnt vmcnt(8)
	s_waitcnt lgkmcnt(0)
	s_cmp_eq_u32 s98, 1
	s_cbranch_scc0 .Lkb_skip_1
	s_mov_b32 s98, 0
	s_barrier
.Lkb_skip_1:
	s_barrier
	s_setprio 1
	s_waitcnt lgkmcnt(0)
	v_mfma_f32_16x16x32_bf16 v[124:127], v[146:149], v[186:189], 0
	v_mfma_f32_16x16x32_bf16 v[120:123], v[162:165], v[186:189], 0
	v_mfma_f32_16x16x32_bf16 v[108:111], v[146:149], v[194:197], 0
	v_mfma_f32_16x16x32_bf16 v[104:107], v[162:165], v[194:197], 0
	v_mfma_f32_16x16x32_bf16 v[92:95], v[146:149], v[202:205], 0
	v_mfma_f32_16x16x32_bf16 v[88:91], v[162:165], v[202:205], 0
	v_mfma_f32_16x16x32_bf16 v[76:79], v[146:149], v[212:215], 0
	v_mfma_f32_16x16x32_bf16 v[72:75], v[162:165], v[212:215], 0
	v_mfma_f32_16x16x32_bf16 v[124:127], v[158:161], v[190:193], v[124:127]
	v_mfma_f32_16x16x32_bf16 v[120:123], v[166:169], v[190:193], v[120:123]
	v_mfma_f32_16x16x32_bf16 v[108:111], v[158:161], v[198:201], v[108:111]
	v_mfma_f32_16x16x32_bf16 v[104:107], v[166:169], v[198:201], v[104:107]
	v_mfma_f32_16x16x32_bf16 v[92:95], v[158:161], v[206:209], v[92:95]
	v_mfma_f32_16x16x32_bf16 v[88:91], v[166:169], v[206:209], v[88:91]
	v_mfma_f32_16x16x32_bf16 v[76:79], v[158:161], v[216:219], v[76:79]
	v_mfma_f32_16x16x32_bf16 v[72:75], v[166:169], v[216:219], v[72:75]
	s_setprio 0
	s_setprio 1
	v_mfma_f32_16x16x32_bf16 v[116:119], v[170:173], v[186:189], 0
	v_mfma_f32_16x16x32_bf16 v[112:115], v[178:181], v[186:189], 0
	v_mfma_f32_16x16x32_bf16 v[100:103], v[170:173], v[194:197], 0
	v_mfma_f32_16x16x32_bf16 v[96:99], v[178:181], v[194:197], 0
	v_mfma_f32_16x16x32_bf16 v[84:87], v[170:173], v[202:205], 0
	v_mfma_f32_16x16x32_bf16 v[80:83], v[178:181], v[202:205], 0
	v_mfma_f32_16x16x32_bf16 v[68:71], v[170:173], v[212:215], 0
	v_mfma_f32_16x16x32_bf16 v[64:67], v[178:181], v[212:215], 0
	v_mfma_f32_16x16x32_bf16 v[116:119], v[174:177], v[190:193], v[116:119]
	v_mfma_f32_16x16x32_bf16 v[112:115], v[182:185], v[190:193], v[112:115]
	v_mfma_f32_16x16x32_bf16 v[100:103], v[174:177], v[198:201], v[100:103]
	v_mfma_f32_16x16x32_bf16 v[96:99], v[182:185], v[198:201], v[96:99]
	v_mfma_f32_16x16x32_bf16 v[84:87], v[174:177], v[206:209], v[84:87]
	v_mfma_f32_16x16x32_bf16 v[80:83], v[182:185], v[206:209], v[80:83]
	v_mfma_f32_16x16x32_bf16 v[68:71], v[174:177], v[216:219], v[68:71]
	v_mfma_f32_16x16x32_bf16 v[64:67], v[182:185], v[216:219], v[64:67]
	s_setprio 0
	s_barrier
	s_add_i32 s26, s73, s66
	s_mov_b32 m0, s26
	ds_read_b128 v[186:189], v155 offset:16384
	ds_read_b128 v[190:193], v155 offset:17408
	ds_read_b128 v[194:197], v155 offset:18432
	ds_read_b128 v[198:201], v155 offset:19456
	ds_read_b128 v[202:205], v155 offset:20480
	ds_read_b128 v[206:209], v155 offset:21504
	ds_read_b128 v[212:215], v155 offset:22528
	ds_read_b128 v[216:219], v155 offset:23552
	global_load_lds_dwordx4 v130, s[60:61]
	s_add_i32 m0, s26, 0x2000
	s_add_u32 s26, s60, 0x20000
	s_addc_u32 s27, s61, 0
	s_add_i32 s33, s74, s66
	global_load_lds_dwordx4 v134, s[60:61]
	s_mov_b32 m0, s33
	s_nop 0
	global_load_lds_dwordx4 v130, s[26:27]
	s_add_i32 m0, s33, 0x2000
	s_nop 0
	global_load_lds_dwordx4 v134, s[26:27]
	s_mov_b32 m0, s57
	s_nop 0
	global_load_lds_dwordx4 v128, s[62:63]
	s_mov_b32 m0, s67
	s_nop 0
	global_load_lds_dwordx4 v132, s[62:63]
	s_waitcnt vmcnt(8)
	s_waitcnt lgkmcnt(0)
	s_barrier
; #define PG8_STAGE(bufoff, gbase, voff) do { _Pragma("unroll") for (int _i = 0; _i < 2; ++_i) \
;         __builtin_amdgcn_global_load_lds((const unsigned*)((const char*)(gbase) + (voff)[_i]), (PG8_LAS unsigned*)(lds + (bufoff) + ldsw + _i * 8192), 16, 0, 0); } while (0)
; #define PG8_LDA(dst, b, h) do { _Pragma("unroll") for (int m = 0; m < 4; ++m) _Pragma("unroll") for (int k = 0; k < 2; ++k) dst[m][k] = *(const PG8_LAS bf16x8*)(lds + PG8_SA(b, h) + aoff + m * 2048 + k * 1024); } while (0)
; #define PG8_LDB(dst, b, h) do { _Pragma("unroll") for (int n = 0; n < 2; ++n) _Pragma("unroll") for (int k = 0; k < 2; ++k) dst[n][k] = *(const PG8_LAS bf16x8*)(lds + PG8_SB(b, h) + boff + n * 2048 + k * 1024); } while (0)
; #define PG8_MMA(ai, bj, At, Bt) do { __builtin_amdgcn_s_setprio(1); _Pragma("unroll") for (int m = 0; m < 4; ++m) _Pragma("unroll") for (int n = 0; n < 2; ++n) _Pragma("unroll") for (int k = 0; k < 2; ++k) \
;         acc[ai][bj][m][n] = __builtin_amdgcn_mfma_f32_16x16x32_bf16(Bt[n][k], At[m][k], acc[ai][bj][m][n], 0, 0, 0); __builtin_amdgcn_s_setprio(0); } while (0)
; #define PG8_WAIT_V(n) asm volatile("s_waitcnt vmcnt(" #n ")" ::: "memory")
; #define PG8_WAIT_L(n) asm volatile("s_waitcnt lgkmcnt(" #n ")" ::: "memory")
; #define PG8_BAR __builtin_amdgcn_s_barrier()
; #define PG8_SCHED __builtin_amdgcn_sched_barrier(0)
; template <class Epi, class Sched, bool ALIGN_EPI = false, bool SP2 = false>
; __device__ __forceinline__ void gemm_phase(PG8_LAS unsigned char* lds, const Gemm g, const Sched& S, const Epi& E, int tid_in) {
;     ...
;             PG8_WAIT_V(8); PG8_WAIT_L(0); PG8_BAR; PG8_MMA(0, 0, At, B0); PG8_MMA(0, 1, At, B1); PG8_BAR; PG8_SCHED;
;             PG8_LDA(At, 0, 1); PG8_STAGE(PG8_SB(0, 0), b2, voffB); PG8_STAGE(PG8_SB(0, 1), b2 + hstepB, voffB); PG8_STAGE(PG8_SA(0, 0), a2, voffA);
;             PG8_WAIT_V(8); PG8_WAIT_L(0); PG8_BAR; PG8_MMA(1, 0, At, B0); PG8_MMA(1, 1, At, B1); PG8_BAR; PG8_SCHED;
;             PG8_LDB(B0, 1, 0); PG8_LDB(B1, 1, 1); PG8_SCHED; PG8_LDA(At, 1, 0); PG8_STAGE(PG8_SA(0, 1), a2 + hstep, voffA);
;             PG8_WAIT_V(8); PG8_WAIT_L(0); PG8_BAR; PG8_MMA(0, 0, At, B0); PG8_MMA(0, 1, At, B1); PG8_BAR; PG8_SCHED;
;             PG8_LDA(At, 1, 1); PG8_STAGE(PG8_SB(1, 0), b3, voffB); PG8_STAGE(PG8_SB(1, 1), b3 + hstepB, voffB); PG8_STAGE(PG8_SA(1, 0), a3, voffA);
	s_setprio 1
	s_waitcnt lgkmcnt(0)
	v_mfma_f32_16x16x32_bf16 v[60:63], v[146:149], v[186:189], 0
	v_mfma_f32_16x16x32_bf16 v[56:59], v[162:165], v[186:189], 0
	v_mfma_f32_16x16x32_bf16 v[44:47], v[146:149], v[194:197], 0
	v_mfma_f32_16x16x32_bf16 v[40:43], v[162:165], v[194:197], 0
	v_mfma_f32_16x16x32_bf16 v[28:31], v[146:149], v[202:205], 0
	v_mfma_f32_16x16x32_bf16 v[24:27], v[162:165], v[202:205], 0
	v_mfma_f32_16x16x32_bf16 v[12:15], v[146:149], v[212:215], 0
	v_mfma_f32_16x16x32_bf16 v[8:11], v[162:165], v[212:215], 0
	v_mfma_f32_16x16x32_bf16 v[60:63], v[158:161], v[190:193], v[60:63]
	v_mfma_f32_16x16x32_bf16 v[56:59], v[166:169], v[190:193], v[56:59]
	v_mfma_f32_16x16x32_bf16 v[44:47], v[158:161], v[198:201], v[44:47]
	v_mfma_f32_16x16x32_bf16 v[40:43], v[166:169], v[198:201], v[40:43]
	v_mfma_f32_16x16x32_bf16 v[28:31], v[158:161], v[206:209], v[28:31]
	v_mfma_f32_16x16x32_bf16 v[24:27], v[166:169], v[206:209], v[24:27]
	v_mfma_f32_16x16x32_bf16 v[12:15], v[158:161], v[216:219], v[12:15]
	v_mfma_f32_16x16x32_bf16 v[8:11], v[166:169], v[216:219], v[8:11]
	s_setprio 0
	s_setprio 1
	v_mfma_f32_16x16x32_bf16 v[52:55], v[170:173], v[186:189], 0
	v_mfma_f32_16x16x32_bf16 v[48:51], v[178:181], v[186:189], 0
	v_mfma_f32_16x16x32_bf16 v[36:39], v[170:173], v[194:197], 0
	v_mfma_f32_16x16x32_bf16 v[32:35], v[178:181], v[194:197], 0
	v_mfma_f32_16x16x32_bf16 v[20:23], v[170:173], v[202:205], 0
	v_mfma_f32_16x16x32_bf16 v[16:19], v[178:181], v[202:205], 0
	v_mfma_f32_16x16x32_bf16 v[4:7], v[170:173], v[212:215], 0
	v_mfma_f32_16x16x32_bf16 v[0:3], v[178:181], v[212:215], 0
	v_mfma_f32_16x16x32_bf16 v[52:55], v[174:177], v[190:193], v[52:55]
	v_mfma_f32_16x16x32_bf16 v[48:51], v[182:185], v[190:193], v[48:51]
	v_mfma_f32_16x16x32_bf16 v[36:39], v[174:177], v[198:201], v[36:39]
	v_mfma_f32_16x16x32_bf16 v[32:35], v[182:185], v[198:201], v[32:35]
	v_mfma_f32_16x16x32_bf16 v[20:23], v[174:177], v[206:209], v[20:23]
	v_mfma_f32_16x16x32_bf16 v[16:19], v[182:185], v[206:209], v[16:19]
	v_mfma_f32_16x16x32_bf16 v[4:7], v[174:177], v[216:219], v[4:7]
	v_mfma_f32_16x16x32_bf16 v[0:3], v[182:185], v[216:219], v[0:3]
	s_setprio 0
	s_barrier
	s_add_i32 s33, 0, 0x18000
	s_add_i32 s84, 0, 0x1c000
	v_add_u32_e32 v166, s33, v137
	v_add_u32_e32 v182, s84, v137
	ds_read_b128 v[146:149], v166
	ds_read_b128 v[158:161], v166 offset:1024
	ds_read_b128 v[162:165], v166 offset:2048
	ds_read_b128 v[166:169], v166 offset:3072
	ds_read_b128 v[170:173], v182
	ds_read_b128 v[174:177], v182 offset:1024
	ds_read_b128 v[178:181], v182 offset:2048
	ds_read_b128 v[182:185], v182 offset:3072
	s_add_u32 s26, s62, 0x80000
	s_addc_u32 s27, s63, 0
	s_mov_b32 m0, s68
	ds_read_b128 v[186:189], v155 offset:32768
	ds_read_b128 v[190:193], v155 offset:33792
	ds_read_b128 v[194:197], v155 offset:34816
	ds_read_b128 v[198:201], v155 offset:35840
	ds_read_b128 v[202:205], v155 offset:36864
	ds_read_b128 v[206:209], v155 offset:37888
	ds_read_b128 v[212:215], v155 offset:38912
	ds_read_b128 v[216:219], v155 offset:39936
	global_load_lds_dwordx4 v128, s[26:27]
	s_mov_b32 m0, s69
	s_nop 0
	global_load_lds_dwordx4 v132, s[26:27]
	s_waitcnt vmcnt(8)
	s_waitcnt lgkmcnt(0)
	s_barrier
	s_setprio 1
	s_waitcnt lgkmcnt(0)
	v_mfma_f32_16x16x32_bf16 v[124:127], v[146:149], v[186:189], v[124:127]
	v_mfma_f32_16x16x32_bf16 v[120:123], v[162:165], v[186:189], v[120:123]
	v_mfma_f32_16x16x32_bf16 v[108:111], v[146:149], v[194:197], v[108:111]
	v_mfma_f32_16x16x32_bf16 v[104:107], v[162:165], v[194:197], v[104:107]
	v_mfma_f32_16x16x32_bf16 v[92:95], v[146:149], v[202:205], v[92:95]
	v_mfma_f32_16x16x32_bf16 v[88:91], v[162:165], v[202:205], v[88:91]
	v_mfma_f32_16x16x32_bf16 v[76:79], v[146:149], v[212:215], v[76:79]
	v_mfma_f32_16x16x32_bf16 v[72:75], v[162:165], v[212:215], v[72:75]
	v_mfma_f32_16x16x32_bf16 v[124:127], v[158:161], v[190:193], v[124:127]
	v_mfma_f32_16x16x32_bf16 v[120:123], v[166:169], v[190:193], v[120:123]
	v_mfma_f32_16x16x32_bf16 v[108:111], v[158:161], v[198:201], v[108:111]
	v_mfma_f32_16x16x32_bf16 v[104:107], v[166:169], v[198:201], v[104:107]
	v_mfma_f32_16x16x32_bf16 v[92:95], v[158:161], v[206:209], v[92:95]
	v_mfma_f32_16x16x32_bf16 v[88:91], v[166:169], v[206:209], v[88:91]
	v_mfma_f32_16x16x32_bf16 v[76:79], v[158:161], v[216:219], v[76:79]
	v_mfma_f32_16x16x32_bf16 v[72:75], v[166:169], v[216:219], v[72:75]
	s_setprio 0
	s_setprio 1
	v_mfma_f32_16x16x32_bf16 v[116:119], v[170:173], v[186:189], v[116:119]
	v_mfma_f32_16x16x32_bf16 v[112:115], v[178:181], v[186:189], v[112:115]
	v_mfma_f32_16x16x32_bf16 v[100:103], v[170:173], v[194:197], v[100:103]
	v_mfma_f32_16x16x32_bf16 v[96:99], v[178:181], v[194:197], v[96:99]
	v_mfma_f32_16x16x32_bf16 v[84:87], v[170:173], v[202:205], v[84:87]
	v_mfma_f32_16x16x32_bf16 v[80:83], v[178:181], v[202:205], v[80:83]
	v_mfma_f32_16x16x32_bf16 v[68:71], v[170:173], v[212:215], v[68:71]
	v_mfma_f32_16x16x32_bf16 v[64:67], v[178:181], v[212:215], v[64:67]
	v_mfma_f32_16x16x32_bf16 v[116:119], v[174:177], v[190:193], v[116:119]
	v_mfma_f32_16x16x32_bf16 v[112:115], v[182:185], v[190:193], v[112:115]
	v_mfma_f32_16x16x32_bf16 v[100:103], v[174:177], v[198:201], v[100:103]
	v_mfma_f32_16x16x32_bf16 v[96:99], v[182:185], v[198:201], v[96:99]
	v_mfma_f32_16x16x32_bf16 v[84:87], v[174:177], v[206:209], v[84:87]
	v_mfma_f32_16x16x32_bf16 v[80:83], v[182:185], v[206:209], v[80:83]
	v_mfma_f32_16x16x32_bf16 v[68:71], v[174:177], v[216:219], v[68:71]
	v_mfma_f32_16x16x32_bf16 v[64:67], v[182:185], v[216:219], v[64:67]
	s_setprio 0
	s_barrier
; #define PG8_STAGE(bufoff, gbase, voff) do { _Pragma("unroll") for (int _i = 0; _i < 2; ++_i) \
;         __builtin_amdgcn_global_load_lds((const unsigned*)((const char*)(gbase) + (voff)[_i]), (PG8_LAS unsigned*)(lds + (bufoff) + ldsw + _i * 8192), 16, 0, 0); } while (0)
; #define PG8_LDA(dst, b, h) do { _Pragma("unroll") for (int m = 0; m < 4; ++m) _Pragma("unroll") for (int k = 0; k < 2; ++k) dst[m][k] = *(const PG8_LAS bf16x8*)(lds + PG8_SA(b, h) + aoff + m * 2048 + k * 1024); } while (0)
; #define PG8_MMA(ai, bj, At, Bt) do { __builtin_amdgcn_s_setprio(1); _Pragma("unroll") for (int m = 0; m < 4; ++m) _Pragma("unroll") for (int n = 0; n < 2; ++n) _Pragma("unroll") for (int k = 0; k < 2; ++k) \
;         acc[ai][bj][m][n] = __builtin_amdgcn_mfma_f32_16x16x32_bf16(Bt[n][k], At[m][k], acc[ai][bj][m][n], 0, 0, 0); __builtin_amdgcn_s_setprio(0); } while (0)
; #define PG8_WAIT_V(n) asm volatile("s_waitcnt vmcnt(" #n ")" ::: "memory")
; #define PG8_WAIT_L(n) asm volatile("s_waitcnt lgkmcnt(" #n ")" ::: "memory")
; #define PG8_BAR __builtin_amdgcn_s_barrier()
; #define PG8_SCHED __builtin_amdgcn_sched_barrier(0)
; template <class Epi, class Sched, bool ALIGN_EPI = false, bool SP2 = false>
; __device__ __forceinline__ void gemm_phase(PG8_LAS unsigned char* lds, const Gemm g, const Sched& S, const Epi& E, int tid_in) {
;     ...
;             PG8_LDA(At, 1, 1); PG8_STAGE(PG8_SB(1, 0), b3, voffB); PG8_STAGE(PG8_SB(1, 1), b3 + hstepB, voffB); PG8_STAGE(PG8_SA(1, 0), a3, voffA);
;             PG8_WAIT_V(8); PG8_WAIT_L(0); PG8_BAR; PG8_MMA(1, 0, At, B0); PG8_MMA(1, 1, At, B1); PG8_BAR; PG8_SCHED;
	s_add_i32 s26, s33, s66
	s_add_i32 m0, s26, 0xffffff80
	ds_read_b128 v[186:189], v155 offset:49152
	ds_read_b128 v[190:193], v155 offset:50176
	ds_read_b128 v[194:197], v155 offset:51200
	ds_read_b128 v[198:201], v155 offset:52224
	ds_read_b128 v[202:205], v155 offset:53248
	ds_read_b128 v[206:209], v155 offset:54272
	ds_read_b128 v[212:215], v155 offset:55296
	ds_read_b128 v[216:219], v155 offset:56320
	global_load_lds_dwordx4 v130, s[60:61] offset:128
	s_add_i32 m0, s26, 0x1f80
	s_add_u32 s26, s60, 0x20080
	s_addc_u32 s27, s61, 0
	s_add_i32 s33, s84, s66
	global_load_lds_dwordx4 v134, s[60:61] offset:128
	s_mov_b32 m0, s33
	s_nop 0
	global_load_lds_dwordx4 v130, s[26:27]
	s_add_i32 m0, s33, 0x2000
	s_nop 0
	global_load_lds_dwordx4 v134, s[26:27]
	s_add_i32 m0, s71, 0xffffff80
	s_nop 0
	global_load_lds_dwordx4 v128, s[62:63] offset:128
	s_add_i32 m0, s72, 0xffffff80
	s_nop 0
	global_load_lds_dwordx4 v132, s[62:63] offset:128
	s_waitcnt vmcnt(8)
	s_waitcnt lgkmcnt(0)
	s_barrier
	s_setprio 1
	s_waitcnt lgkmcnt(0)
	v_mfma_f32_16x16x32_bf16 v[60:63], v[146:149], v[186:189], v[60:63]
	v_mfma_f32_16x16x32_bf16 v[56:59], v[162:165], v[186:189], v[56:59]
	v_mfma_f32_16x16x32_bf16 v[44:47], v[146:149], v[194:197], v[44:47]
	v_mfma_f32_16x16x32_bf16 v[40:43], v[162:165], v[194:197], v[40:43]
	v_mfma_f32_16x16x32_bf16 v[28:31], v[146:149], v[202:205], v[28:31]
	v_mfma_f32_16x16x32_bf16 v[24:27], v[162:165], v[202:205], v[24:27]
	v_mfma_f32_16x16x32_bf16 v[12:15], v[146:149], v[212:215], v[12:15]
	v_mfma_f32_16x16x32_bf16 v[8:11], v[162:165], v[212:215], v[8:11]
	v_mfma_f32_16x16x32_bf16 v[60:63], v[158:161], v[190:193], v[60:63]
	v_mfma_f32_16x16x32_bf16 v[56:59], v[166:169], v[190:193], v[56:59]
	v_mfma_f32_16x16x32_bf16 v[44:47], v[158:161], v[198:201], v[44:47]
	v_mfma_f32_16x16x32_bf16 v[40:43], v[166:169], v[198:201], v[40:43]
	v_mfma_f32_16x16x32_bf16 v[28:31], v[158:161], v[206:209], v[28:31]
	v_mfma_f32_16x16x32_bf16 v[24:27], v[166:169], v[206:209], v[24:27]
	v_mfma_f32_16x16x32_bf16 v[12:15], v[158:161], v[216:219], v[12:15]
	v_mfma_f32_16x16x32_bf16 v[8:11], v[166:169], v[216:219], v[8:11]
	s_setprio 0
	s_setprio 1
	v_mfma_f32_16x16x32_bf16 v[52:55], v[170:173], v[186:189], v[52:55]
	v_mfma_f32_16x16x32_bf16 v[48:51], v[178:181], v[186:189], v[48:51]
	v_mfma_f32_16x16x32_bf16 v[36:39], v[170:173], v[194:197], v[36:39]
	v_mfma_f32_16x16x32_bf16 v[32:35], v[178:181], v[194:197], v[32:35]
	v_mfma_f32_16x16x32_bf16 v[20:23], v[170:173], v[202:205], v[20:23]
	v_mfma_f32_16x16x32_bf16 v[16:19], v[178:181], v[202:205], v[16:19]
	v_mfma_f32_16x16x32_bf16 v[4:7], v[170:173], v[212:215], v[4:7]
	v_mfma_f32_16x16x32_bf16 v[0:3], v[178:181], v[212:215], v[0:3]
	v_mfma_f32_16x16x32_bf16 v[52:55], v[174:177], v[190:193], v[52:55]
	v_mfma_f32_16x16x32_bf16 v[48:51], v[182:185], v[190:193], v[48:51]
	v_mfma_f32_16x16x32_bf16 v[36:39], v[174:177], v[198:201], v[36:39]
	v_mfma_f32_16x16x32_bf16 v[32:35], v[182:185], v[198:201], v[32:35]
	v_mfma_f32_16x16x32_bf16 v[20:23], v[174:177], v[206:209], v[20:23]
	v_mfma_f32_16x16x32_bf16 v[16:19], v[182:185], v[206:209], v[16:19]
	v_mfma_f32_16x16x32_bf16 v[4:7], v[174:177], v[216:219], v[4:7]
	v_mfma_f32_16x16x32_bf16 v[0:3], v[182:185], v[216:219], v[0:3]
	s_setprio 0
	s_barrier
	s_add_i32 s79, s79, 2
	s_add_u32 s58, s58, 0x100
	s_addc_u32 s59, s59, 0
	s_add_u32 s76, s76, 0x100
	s_addc_u32 s77, s77, 0
	s_cmp_gt_u32 s79, 29

; #define PG8_STAGE(bufoff, gbase, voff) do { _Pragma("unroll") for (int _i = 0; _i < 2; ++_i) \
;         __builtin_amdgcn_global_load_lds((const unsigned*)((const char*)(gbase) + (voff)[_i]), (PG8_LAS unsigned*)(lds + (bufoff) + ldsw + _i * 8192), 16, 0, 0); } while (0)
; #define PG8_LDA(dst, b, h) do { _Pragma("unroll") for (int m = 0; m < 4; ++m) _Pragma("unroll") for (int k = 0; k < 2; ++k) dst[m][k] = *(const PG8_LAS bf16x8*)(lds + PG8_SA(b, h) + aoff + m * 2048 + k * 1024); } while (0)
; #define PG8_LDB(dst, b, h) do { _Pragma("unroll") for (int n = 0; n < 2; ++n) _Pragma("unroll") for (int k = 0; k < 2; ++k) dst[n][k] = *(const PG8_LAS bf16x8*)(lds + PG8_SB(b, h) + boff + n * 2048 + k * 1024); } while (0)
; #define PG8_MMA(ai, bj, At, Bt) do { __builtin_amdgcn_s_setprio(1); _Pragma("unroll") for (int m = 0; m < 4; ++m) _Pragma("unroll") for (int n = 0; n < 2; ++n) _Pragma("unroll") for (int k = 0; k < 2; ++k) \
;         acc[ai][bj][m][n] = __builtin_amdgcn_mfma_f32_16x16x32_bf16(Bt[n][k], At[m][k], acc[ai][bj][m][n], 0, 0, 0); __builtin_amdgcn_s_setprio(0); } while (0)
; #define PG8_WAIT_V(n) asm volatile("s_waitcnt vmcnt(" #n ")" ::: "memory")
; template <class Epi, class Sched, bool ALIGN_EPI = false, bool SP2 = false>
; __device__ __forceinline__ void gemm_phase(PG8_LAS unsigned char* lds, const Gemm g, const Sched& S, const Epi& E, int tid_in) {
;     ...
;         const char* nA = has_next ? (const char*)g.A + (size_t)nxt.pm * tstep : cA; const char* nB = has_next ? (const char*)g.Bt + (size_t)nxt.pn * tstepB : cB;
;         for (int t = 0; t < nt; t += 2) {
;             const bool last = (t == nt - 2);
;             const char* a1 = cA + (size_t)(t + 1) * kstep;
;             const char* a2 = last ? nA : cA + (size_t)(t + 2) * kstep; const char* b2 = last ? nB : cB + (size_t)(t + 2) * kstep;
;             const char* a3 = a2 + kstep; const char* b3 = b2 + kstep;
;             if (last && has_next) S.a_ready(nxt);
;             if constexpr (SP2) {
;             PG8_LDB(B0, 0, 0); PG8_LDB(B1, 0, 1); PG8_SCHED; PG8_LDA(At, 0, 0); PG8_STAGE(PG8_SA(1, 1), a1 + hstep, voffA);
;             PG8_WAIT_V(8); PG8_WAIT_L(0); PG8_BAR; PG8_MMA(0, 0, At, B0); PG8_MMA(0, 1, At, B1); PG8_BAR; PG8_SCHED;
;             PG8_LDA(At, 0, 1); PG8_STAGE(PG8_SB(0, 0), b2, voffB); PG8_STAGE(PG8_SB(0, 1), b2 + hstepB, voffB); PG8_STAGE(PG8_SA(0, 0), a2, voffA);
.LBB0_393:
	s_ashr_i32 s45, s44, 31
	s_lshl_b64 s[26:27], s[44:45], 20
	s_add_u32 s46, s38, s26
	s_addc_u32 s47, s39, s27
	s_and_b64 s[26:27], s[8:9], exec
	s_cselect_b32 s45, s47, s53
	s_cselect_b32 s72, s46, s52
	s_ashr_i32 s43, s42, 31
	s_lshl_b64 s[26:27], s[42:43], 20
	s_add_u32 s48, s58, s26
	s_addc_u32 s49, s59, s27
	s_and_b64 s[26:27], s[8:9], exec
	s_cselect_b32 s43, s49, s55
	s_cselect_b32 s73, s48, s54
	s_add_u32 s52, s52, 0x80080
	s_addc_u32 s53, s53, 0
	s_add_u32 s74, s54, 0x100
	s_addc_u32 s75, s55, 0
	s_mov_b32 s76, -2
	ds_read_b128 v[156:159], v150
	ds_read_b128 v[160:163], v150 offset:1024
	ds_read_b128 v[164:167], v150 offset:2048
	ds_read_b128 v[168:171], v150 offset:3072
	ds_read_b128 v[172:175], v151
	ds_read_b128 v[176:179], v151 offset:1024
	ds_read_b128 v[180:183], v151 offset:2048
	ds_read_b128 v[184:187], v151 offset:3072
	s_add_u32 s26, s52, 0xfff80080
	s_addc_u32 s27, s53, -1
	s_cmp_eq_u32 s76, 28
	s_cselect_b32 s57, s45, s27
	s_cselect_b32 s56, s72, s26
	s_cselect_b32 s55, s43, s75
	s_cselect_b32 s54, s73, s74
	s_add_i32 m0, s51, 0xc000
	ds_read_b128 v[188:191], v152
	ds_read_b128 v[192:195], v152 offset:1024
	ds_read_b128 v[196:199], v152 offset:2048
	ds_read_b128 v[200:203], v152 offset:3072
	ds_read_b128 v[204:207], v152 offset:4096
	ds_read_b128 v[212:215], v152 offset:5120
	ds_read_b128 v[216:219], v152 offset:6144
	ds_read_b128 v[220:223], v152 offset:7168
	global_load_lds_dwordx4 v138, s[52:53]
	s_add_i32 m0, s51, 0xe000
	s_nop 0
	global_load_lds_dwordx4 v140, s[52:53]
	s_waitcnt vmcnt(8)
	s_waitcnt lgkmcnt(0)
	s_cmp_eq_u32 s98, 1
	s_cbranch_scc0 .Lkb_skip_2
	s_mov_b32 s98, 0
	s_barrier
.Lkb_skip_2:
	s_barrier
	s_setprio 1
	s_waitcnt lgkmcnt(0)
	v_mfma_f32_16x16x32_bf16 v[124:127], v[156:159], v[188:191], 0
	v_mfma_f32_16x16x32_bf16 v[120:123], v[164:167], v[188:191], 0
	v_mfma_f32_16x16x32_bf16 v[108:111], v[156:159], v[196:199], 0
	v_mfma_f32_16x16x32_bf16 v[104:107], v[164:167], v[196:199], 0
	v_mfma_f32_16x16x32_bf16 v[92:95], v[156:159], v[204:207], 0
	v_mfma_f32_16x16x32_bf16 v[88:91], v[164:167], v[204:207], 0
	v_mfma_f32_16x16x32_bf16 v[76:79], v[156:159], v[216:219], 0
	v_mfma_f32_16x16x32_bf16 v[72:75], v[164:167], v[216:219], 0
	v_mfma_f32_16x16x32_bf16 v[124:127], v[160:163], v[192:195], v[124:127]
	v_mfma_f32_16x16x32_bf16 v[120:123], v[168:171], v[192:195], v[120:123]
	v_mfma_f32_16x16x32_bf16 v[108:111], v[160:163], v[200:203], v[108:111]
	v_mfma_f32_16x16x32_bf16 v[104:107], v[168:171], v[200:203], v[104:107]
	v_mfma_f32_16x16x32_bf16 v[92:95], v[160:163], v[212:215], v[92:95]
	v_mfma_f32_16x16x32_bf16 v[88:91], v[168:171], v[212:215], v[88:91]
	v_mfma_f32_16x16x32_bf16 v[76:79], v[160:163], v[220:223], v[76:79]
	v_mfma_f32_16x16x32_bf16 v[72:75], v[168:171], v[220:223], v[72:75]
	s_setprio 0
	s_setprio 1
	v_mfma_f32_16x16x32_bf16 v[116:119], v[172:175], v[188:191], 0
	v_mfma_f32_16x16x32_bf16 v[112:115], v[180:183], v[188:191], 0
	v_mfma_f32_16x16x32_bf16 v[100:103], v[172:175], v[196:199], 0
	v_mfma_f32_16x16x32_bf16 v[96:99], v[180:183], v[196:199], 0
	v_mfma_f32_16x16x32_bf16 v[84:87], v[172:175], v[204:207], 0
	v_mfma_f32_16x16x32_bf16 v[80:83], v[180:183], v[204:207], 0
	v_mfma_f32_16x16x32_bf16 v[68:71], v[172:175], v[216:219], 0
	v_mfma_f32_16x16x32_bf16 v[64:67], v[180:183], v[216:219], 0
	v_mfma_f32_16x16x32_bf16 v[116:119], v[176:179], v[192:195], v[116:119]
	v_mfma_f32_16x16x32_bf16 v[112:115], v[184:187], v[192:195], v[112:115]
	v_mfma_f32_16x16x32_bf16 v[100:103], v[176:179], v[200:203], v[100:103]
	v_mfma_f32_16x16x32_bf16 v[96:99], v[184:187], v[200:203], v[96:99]
	v_mfma_f32_16x16x32_bf16 v[84:87], v[176:179], v[212:215], v[84:87]
	v_mfma_f32_16x16x32_bf16 v[80:83], v[184:187], v[212:215], v[80:83]
	v_mfma_f32_16x16x32_bf16 v[68:71], v[176:179], v[220:223], v[68:71]
	v_mfma_f32_16x16x32_bf16 v[64:67], v[184:187], v[220:223], v[64:67]
	s_setprio 0
	s_barrier
	s_add_i32 s26, s68, s60
	s_mov_b32 m0, s26
	ds_read_b128 v[188:191], v152 offset:16384
	ds_read_b128 v[192:195], v152 offset:17408
	ds_read_b128 v[196:199], v152 offset:18432
	ds_read_b128 v[200:203], v152 offset:19456
	ds_read_b128 v[204:207], v152 offset:20480
	ds_read_b128 v[212:215], v152 offset:21504
	ds_read_b128 v[216:219], v152 offset:22528
	ds_read_b128 v[220:223], v152 offset:23552
	global_load_lds_dwordx4 v130, s[54:55]
	s_add_i32 m0, s26, 0x2000
	s_add_u32 s26, s54, 0x20000
	s_addc_u32 s27, s55, 0
	s_add_i32 s33, s69, s60
	global_load_lds_dwordx4 v134, s[54:55]
	s_mov_b32 m0, s33
	s_nop 0
	global_load_lds_dwordx4 v130, s[26:27]
	s_add_i32 m0, s33, 0x2000
	s_nop 0
	global_load_lds_dwordx4 v134, s[26:27]
	s_mov_b32 m0, s51
	s_nop 0
	global_load_lds_dwordx4 v128, s[56:57]
	s_mov_b32 m0, s61
	s_nop 0
	global_load_lds_dwordx4 v132, s[56:57]
	s_waitcnt vmcnt(8)
	s_waitcnt lgkmcnt(0)
	s_barrier
; #define PG8_STAGE(bufoff, gbase, voff) do { _Pragma("unroll") for (int _i = 0; _i < 2; ++_i) \
;         __builtin_amdgcn_global_load_lds((const unsigned*)((const char*)(gbase) + (voff)[_i]), (PG8_LAS unsigned*)(lds + (bufoff) + ldsw + _i * 8192), 16, 0, 0); } while (0)
; #define PG8_LDA(dst, b, h) do { _Pragma("unroll") for (int m = 0; m < 4; ++m) _Pragma("unroll") for (int k = 0; k < 2; ++k) dst[m][k] = *(const PG8_LAS bf16x8*)(lds + PG8_SA(b, h) + aoff + m * 2048 + k * 1024); } while (0)
; #define PG8_LDB(dst, b, h) do { _Pragma("unroll") for (int n = 0; n < 2; ++n) _Pragma("unroll") for (int k = 0; k < 2; ++k) dst[n][k] = *(const PG8_LAS bf16x8*)(lds + PG8_SB(b, h) + boff + n * 2048 + k * 1024); } while (0)
; #define PG8_MMA(ai, bj, At, Bt) do { __builtin_amdgcn_s_setprio(1); _Pragma("unroll") for (int m = 0; m < 4; ++m) _Pragma("unroll") for (int n = 0; n < 2; ++n) _Pragma("unroll") for (int k = 0; k < 2; ++k) \
;         acc[ai][bj][m][n] = __builtin_amdgcn_mfma_f32_16x16x32_bf16(Bt[n][k], At[m][k], acc[ai][bj][m][n], 0, 0, 0); __builtin_amdgcn_s_setprio(0); } while (0)
; #define PG8_WAIT_V(n) asm volatile("s_waitcnt vmcnt(" #n ")" ::: "memory")
; #define PG8_WAIT_L(n) asm volatile("s_waitcnt lgkmcnt(" #n ")" ::: "memory")
; #define PG8_BAR __builtin_amdgcn_s_barrier()
; #define PG8_SCHED __builtin_amdgcn_sched_barrier(0)
; template <class Epi, class Sched, bool ALIGN_EPI = false, bool SP2 = false>
; __device__ __forceinline__ void gemm_phase(PG8_LAS unsigned char* lds, const Gemm g, const Sched& S, const Epi& E, int tid_in) {
;     ...
;             PG8_WAIT_V(8); PG8_WAIT_L(0); PG8_BAR; PG8_MMA(0, 0, At, B0); PG8_MMA(0, 1, At, B1); PG8_BAR; PG8_SCHED;
;             PG8_LDA(At, 0, 1); PG8_STAGE(PG8_SB(0, 0), b2, voffB); PG8_STAGE(PG8_SB(0, 1), b2 + hstepB, voffB); PG8_STAGE(PG8_SA(0, 0), a2, voffA);
;             PG8_WAIT_V(8); PG8_WAIT_L(0); PG8_BAR; PG8_MMA(1, 0, At, B0); PG8_MMA(1, 1, At, B1); PG8_BAR; PG8_SCHED;
;             PG8_LDB(B0, 1, 0); PG8_LDB(B1, 1, 1); PG8_SCHED; PG8_LDA(At, 1, 0); PG8_STAGE(PG8_SA(0, 1), a2 + hstep, voffA);
;             PG8_WAIT_V(8); PG8_WAIT_L(0); PG8_BAR; PG8_MMA(0, 0, At, B0); PG8_MMA(0, 1, At, B1); PG8_BAR; PG8_SCHED;
;             PG8_LDA(At, 1, 1); PG8_STAGE(PG8_SB(1, 0), b3, voffB); PG8_STAGE(PG8_SB(1, 1), b3 + hstepB, voffB); PG8_STAGE(PG8_SA(1, 0), a3, voffA);
	s_setprio 1
	s_waitcnt lgkmcnt(0)
	v_mfma_f32_16x16x32_bf16 v[60:63], v[156:159], v[188:191], 0
	v_mfma_f32_16x16x32_bf16 v[56:59], v[164:167], v[188:191], 0
	v_mfma_f32_16x16x32_bf16 v[44:47], v[156:159], v[196:199], 0
	v_mfma_f32_16x16x32_bf16 v[40:43], v[164:167], v[196:199], 0
	v_mfma_f32_16x16x32_bf16 v[28:31], v[156:159], v[204:207], 0
	v_mfma_f32_16x16x32_bf16 v[24:27], v[164:167], v[204:207], 0
	v_mfma_f32_16x16x32_bf16 v[12:15], v[156:159], v[216:219], 0
	v_mfma_f32_16x16x32_bf16 v[8:11], v[164:167], v[216:219], 0
	v_mfma_f32_16x16x32_bf16 v[60:63], v[160:163], v[192:195], v[60:63]
	v_mfma_f32_16x16x32_bf16 v[56:59], v[168:171], v[192:195], v[56:59]
	v_mfma_f32_16x16x32_bf16 v[44:47], v[160:163], v[200:203], v[44:47]
	v_mfma_f32_16x16x32_bf16 v[40:43], v[168:171], v[200:203], v[40:43]
	v_mfma_f32_16x16x32_bf16 v[28:31], v[160:163], v[212:215], v[28:31]
	v_mfma_f32_16x16x32_bf16 v[24:27], v[168:171], v[212:215], v[24:27]
	v_mfma_f32_16x16x32_bf16 v[12:15], v[160:163], v[220:223], v[12:15]
	v_mfma_f32_16x16x32_bf16 v[8:11], v[168:171], v[220:223], v[8:11]
	s_setprio 0
	s_setprio 1
	v_mfma_f32_16x16x32_bf16 v[52:55], v[172:175], v[188:191], 0
	v_mfma_f32_16x16x32_bf16 v[48:51], v[180:183], v[188:191], 0
	v_mfma_f32_16x16x32_bf16 v[36:39], v[172:175], v[196:199], 0
	v_mfma_f32_16x16x32_bf16 v[32:35], v[180:183], v[196:199], 0
	v_mfma_f32_16x16x32_bf16 v[20:23], v[172:175], v[204:207], 0
	v_mfma_f32_16x16x32_bf16 v[16:19], v[180:183], v[204:207], 0
	v_mfma_f32_16x16x32_bf16 v[4:7], v[172:175], v[216:219], 0
	v_mfma_f32_16x16x32_bf16 v[0:3], v[180:183], v[216:219], 0
	v_mfma_f32_16x16x32_bf16 v[52:55], v[176:179], v[192:195], v[52:55]
	v_mfma_f32_16x16x32_bf16 v[48:51], v[184:187], v[192:195], v[48:51]
	v_mfma_f32_16x16x32_bf16 v[36:39], v[176:179], v[200:203], v[36:39]
	v_mfma_f32_16x16x32_bf16 v[32:35], v[184:187], v[200:203], v[32:35]
	v_mfma_f32_16x16x32_bf16 v[20:23], v[176:179], v[212:215], v[20:23]
	v_mfma_f32_16x16x32_bf16 v[16:19], v[184:187], v[212:215], v[16:19]
	v_mfma_f32_16x16x32_bf16 v[4:7], v[176:179], v[220:223], v[4:7]
	v_mfma_f32_16x16x32_bf16 v[0:3], v[184:187], v[220:223], v[0:3]
	s_setprio 0
	s_barrier
	s_add_i32 s33, 0, 0x18000
	v_add_u32_e32 v155, s33, v146
	s_add_i32 s77, 0, 0x1c000
	ds_read_b128 v[156:159], v155
	ds_read_b128 v[160:163], v155 offset:1024
	ds_read_b128 v[164:167], v155 offset:2048
	ds_read_b128 v[168:171], v155 offset:3072
	v_add_u32_e32 v155, s77, v146
	ds_read_b128 v[172:175], v155
	ds_read_b128 v[176:179], v155 offset:1024
	ds_read_b128 v[180:183], v155 offset:2048
	ds_read_b128 v[184:187], v155 offset:3072
	s_add_u32 s26, s56, 0x80000
	s_addc_u32 s27, s57, 0
	s_mov_b32 m0, s62
	ds_read_b128 v[188:191], v152 offset:32768
	ds_read_b128 v[192:195], v152 offset:33792
	ds_read_b128 v[196:199], v152 offset:34816
	ds_read_b128 v[200:203], v152 offset:35840
	ds_read_b128 v[204:207], v152 offset:36864
	ds_read_b128 v[212:215], v152 offset:37888
	ds_read_b128 v[216:219], v152 offset:38912
	ds_read_b128 v[220:223], v152 offset:39936
	global_load_lds_dwordx4 v128, s[26:27]
	s_mov_b32 m0, s63
	s_nop 0
	global_load_lds_dwordx4 v132, s[26:27]
	s_waitcnt vmcnt(8)
	s_waitcnt lgkmcnt(0)
	s_barrier
	s_setprio 1
	s_waitcnt lgkmcnt(0)
	v_mfma_f32_16x16x32_bf16 v[124:127], v[156:159], v[188:191], v[124:127]
	v_mfma_f32_16x16x32_bf16 v[120:123], v[164:167], v[188:191], v[120:123]
	v_mfma_f32_16x16x32_bf16 v[108:111], v[156:159], v[196:199], v[108:111]
	v_mfma_f32_16x16x32_bf16 v[104:107], v[164:167], v[196:199], v[104:107]
	v_mfma_f32_16x16x32_bf16 v[92:95], v[156:159], v[204:207], v[92:95]
	v_mfma_f32_16x16x32_bf16 v[88:91], v[164:167], v[204:207], v[88:91]
	v_mfma_f32_16x16x32_bf16 v[76:79], v[156:159], v[216:219], v[76:79]
	v_mfma_f32_16x16x32_bf16 v[72:75], v[164:167], v[216:219], v[72:75]
	v_mfma_f32_16x16x32_bf16 v[124:127], v[160:163], v[192:195], v[124:127]
	v_mfma_f32_16x16x32_bf16 v[120:123], v[168:171], v[192:195], v[120:123]
	v_mfma_f32_16x16x32_bf16 v[108:111], v[160:163], v[200:203], v[108:111]
	v_mfma_f32_16x16x32_bf16 v[104:107], v[168:171], v[200:203], v[104:107]
	v_mfma_f32_16x16x32_bf16 v[92:95], v[160:163], v[212:215], v[92:95]
	v_mfma_f32_16x16x32_bf16 v[88:91], v[168:171], v[212:215], v[88:91]
	v_mfma_f32_16x16x32_bf16 v[76:79], v[160:163], v[220:223], v[76:79]
	v_mfma_f32_16x16x32_bf16 v[72:75], v[168:171], v[220:223], v[72:75]
	s_setprio 0
	s_setprio 1
	v_mfma_f32_16x16x32_bf16 v[116:119], v[172:175], v[188:191], v[116:119]
	v_mfma_f32_16x16x32_bf16 v[112:115], v[180:183], v[188:191], v[112:115]
	v_mfma_f32_16x16x32_bf16 v[100:103], v[172:175], v[196:199], v[100:103]
	v_mfma_f32_16x16x32_bf16 v[96:99], v[180:183], v[196:199], v[96:99]
	v_mfma_f32_16x16x32_bf16 v[84:87], v[172:175], v[204:207], v[84:87]
	v_mfma_f32_16x16x32_bf16 v[80:83], v[180:183], v[204:207], v[80:83]
	v_mfma_f32_16x16x32_bf16 v[68:71], v[172:175], v[216:219], v[68:71]
	v_mfma_f32_16x16x32_bf16 v[64:67], v[180:183], v[216:219], v[64:67]
	v_mfma_f32_16x16x32_bf16 v[116:119], v[176:179], v[192:195], v[116:119]
	v_mfma_f32_16x16x32_bf16 v[112:115], v[184:187], v[192:195], v[112:115]
	v_mfma_f32_16x16x32_bf16 v[100:103], v[176:179], v[200:203], v[100:103]
	v_mfma_f32_16x16x32_bf16 v[96:99], v[184:187], v[200:203], v[96:99]
	v_mfma_f32_16x16x32_bf16 v[84:87], v[176:179], v[212:215], v[84:87]
	v_mfma_f32_16x16x32_bf16 v[80:83], v[184:187], v[212:215], v[80:83]
	v_mfma_f32_16x16x32_bf16 v[68:71], v[176:179], v[220:223], v[68:71]
	v_mfma_f32_16x16x32_bf16 v[64:67], v[184:187], v[220:223], v[64:67]
	s_setprio 0
	s_barrier
; #define PG8_STAGE(bufoff, gbase, voff) do { _Pragma("unroll") for (int _i = 0; _i < 2; ++_i) \
;         __builtin_amdgcn_global_load_lds((const unsigned*)((const char*)(gbase) + (voff)[_i]), (PG8_LAS unsigned*)(lds + (bufoff) + ldsw + _i * 8192), 16, 0, 0); } while (0)
; #define PG8_LDA(dst, b, h) do { _Pragma("unroll") for (int m = 0; m < 4; ++m) _Pragma("unroll") for (int k = 0; k < 2; ++k) dst[m][k] = *(const PG8_LAS bf16x8*)(lds + PG8_SA(b, h) + aoff + m * 2048 + k * 1024); } while (0)
; #define PG8_MMA(ai, bj, At, Bt) do { __builtin_amdgcn_s_setprio(1); _Pragma("unroll") for (int m = 0; m < 4; ++m) _Pragma("unroll") for (int n = 0; n < 2; ++n) _Pragma("unroll") for (int k = 0; k < 2; ++k) \
;         acc[ai][bj][m][n] = __builtin_amdgcn_mfma_f32_16x16x32_bf16(Bt[n][k], At[m][k], acc[ai][bj][m][n], 0, 0, 0); __builtin_amdgcn_s_setprio(0); } while (0)
; #define PG8_WAIT_V(n) asm volatile("s_waitcnt vmcnt(" #n ")" ::: "memory")
; #define PG8_WAIT_L(n) asm volatile("s_waitcnt lgkmcnt(" #n ")" ::: "memory")
; #define PG8_BAR __builtin_amdgcn_s_barrier()
; #define PG8_SCHED __builtin_amdgcn_sched_barrier(0)
; template <class Epi, class Sched, bool ALIGN_EPI = false, bool SP2 = false>
; __device__ __forceinline__ void gemm_phase(PG8_LAS unsigned char* lds, const Gemm g, const Sched& S, const Epi& E, int tid_in) {
;     ...
;             PG8_LDA(At, 1, 1); PG8_STAGE(PG8_SB(1, 0), b3, voffB); PG8_STAGE(PG8_SB(1, 1), b3 + hstepB, voffB); PG8_STAGE(PG8_SA(1, 0), a3, voffA);
;             PG8_WAIT_V(8); PG8_WAIT_L(0); PG8_BAR; PG8_MMA(1, 0, At, B0); PG8_MMA(1, 1, At, B1); PG8_BAR; PG8_SCHED;
	s_add_i32 s26, s33, s60
	s_add_i32 m0, s26, 0xffffff80
	ds_read_b128 v[188:191], v152 offset:49152
	ds_read_b128 v[192:195], v152 offset:50176
	ds_read_b128 v[196:199], v152 offset:51200
	ds_read_b128 v[200:203], v152 offset:52224
	ds_read_b128 v[204:207], v152 offset:53248
	ds_read_b128 v[212:215], v152 offset:54272
	ds_read_b128 v[216:219], v152 offset:55296
	ds_read_b128 v[220:223], v152 offset:56320
	global_load_lds_dwordx4 v130, s[54:55] offset:128
	s_add_i32 m0, s26, 0x1f80
	s_add_u32 s26, s54, 0x20080
	s_addc_u32 s27, s55, 0
	s_add_i32 s33, s77, s60
	global_load_lds_dwordx4 v134, s[54:55] offset:128
	s_mov_b32 m0, s33
	s_nop 0
	global_load_lds_dwordx4 v130, s[26:27]
	s_add_i32 m0, s33, 0x2000
	s_nop 0
	global_load_lds_dwordx4 v134, s[26:27]
	s_add_i32 m0, s66, 0xffffff80
	s_nop 0
	global_load_lds_dwordx4 v128, s[56:57] offset:128
	s_add_i32 m0, s67, 0xffffff80
	s_nop 0
	global_load_lds_dwordx4 v132, s[56:57] offset:128
	s_waitcnt vmcnt(8)
	s_waitcnt lgkmcnt(0)
	s_barrier
	s_setprio 1
	s_waitcnt lgkmcnt(0)
	v_mfma_f32_16x16x32_bf16 v[60:63], v[156:159], v[188:191], v[60:63]
	v_mfma_f32_16x16x32_bf16 v[56:59], v[164:167], v[188:191], v[56:59]
	v_mfma_f32_16x16x32_bf16 v[44:47], v[156:159], v[196:199], v[44:47]
	v_mfma_f32_16x16x32_bf16 v[40:43], v[164:167], v[196:199], v[40:43]
	v_mfma_f32_16x16x32_bf16 v[28:31], v[156:159], v[204:207], v[28:31]
	v_mfma_f32_16x16x32_bf16 v[24:27], v[164:167], v[204:207], v[24:27]
	v_mfma_f32_16x16x32_bf16 v[12:15], v[156:159], v[216:219], v[12:15]
	v_mfma_f32_16x16x32_bf16 v[8:11], v[164:167], v[216:219], v[8:11]
	v_mfma_f32_16x16x32_bf16 v[60:63], v[160:163], v[192:195], v[60:63]
	v_mfma_f32_16x16x32_bf16 v[56:59], v[168:171], v[192:195], v[56:59]
	v_mfma_f32_16x16x32_bf16 v[44:47], v[160:163], v[200:203], v[44:47]
	v_mfma_f32_16x16x32_bf16 v[40:43], v[168:171], v[200:203], v[40:43]
	v_mfma_f32_16x16x32_bf16 v[28:31], v[160:163], v[212:215], v[28:31]
	v_mfma_f32_16x16x32_bf16 v[24:27], v[168:171], v[212:215], v[24:27]
	v_mfma_f32_16x16x32_bf16 v[12:15], v[160:163], v[220:223], v[12:15]
	v_mfma_f32_16x16x32_bf16 v[8:11], v[168:171], v[220:223], v[8:11]
	s_setprio 0
	s_setprio 1
	v_mfma_f32_16x16x32_bf16 v[52:55], v[172:175], v[188:191], v[52:55]
	v_mfma_f32_16x16x32_bf16 v[48:51], v[180:183], v[188:191], v[48:51]
	v_mfma_f32_16x16x32_bf16 v[36:39], v[172:175], v[196:199], v[36:39]
	v_mfma_f32_16x16x32_bf16 v[32:35], v[180:183], v[196:199], v[32:35]
	v_mfma_f32_16x16x32_bf16 v[20:23], v[172:175], v[204:207], v[20:23]
	v_mfma_f32_16x16x32_bf16 v[16:19], v[180:183], v[204:207], v[16:19]
	v_mfma_f32_16x16x32_bf16 v[4:7], v[172:175], v[216:219], v[4:7]
	v_mfma_f32_16x16x32_bf16 v[0:3], v[180:183], v[216:219], v[0:3]
	v_mfma_f32_16x16x32_bf16 v[52:55], v[176:179], v[192:195], v[52:55]
	v_mfma_f32_16x16x32_bf16 v[48:51], v[184:187], v[192:195], v[48:51]
	v_mfma_f32_16x16x32_bf16 v[36:39], v[176:179], v[200:203], v[36:39]
	v_mfma_f32_16x16x32_bf16 v[32:35], v[184:187], v[200:203], v[32:35]
	v_mfma_f32_16x16x32_bf16 v[20:23], v[176:179], v[212:215], v[20:23]
	v_mfma_f32_16x16x32_bf16 v[16:19], v[184:187], v[212:215], v[16:19]
	v_mfma_f32_16x16x32_bf16 v[4:7], v[176:179], v[220:223], v[4:7]
	v_mfma_f32_16x16x32_bf16 v[0:3], v[184:187], v[220:223], v[0:3]
	s_setprio 0
	s_barrier
	s_add_i32 s76, s76, 2
	s_add_u32 s52, s52, 0x100
	s_addc_u32 s53, s53, 0
	s_add_u32 s74, s74, 0x100
	s_addc_u32 s75, s75, 0
	s_cmp_gt_u32 s76, 29

; #define PG8_STAGE(bufoff, gbase, voff) do { _Pragma("unroll") for (int _i = 0; _i < 2; ++_i) \
;         __builtin_amdgcn_global_load_lds((const unsigned*)((const char*)(gbase) + (voff)[_i]), (PG8_LAS unsigned*)(lds + (bufoff) + ldsw + _i * 8192), 16, 0, 0); } while (0)
; #define PG8_LDA(dst, b, h) do { _Pragma("unroll") for (int m = 0; m < 4; ++m) _Pragma("unroll") for (int k = 0; k < 2; ++k) dst[m][k] = *(const PG8_LAS bf16x8*)(lds + PG8_SA(b, h) + aoff + m * 2048 + k * 1024); } while (0)
; #define PG8_LDB(dst, b, h) do { _Pragma("unroll") for (int n = 0; n < 2; ++n) _Pragma("unroll") for (int k = 0; k < 2; ++k) dst[n][k] = *(const PG8_LAS bf16x8*)(lds + PG8_SB(b, h) + boff + n * 2048 + k * 1024); } while (0)
; #define PG8_MMA(ai, bj, At, Bt) do { __builtin_amdgcn_s_setprio(1); _Pragma("unroll") for (int m = 0; m < 4; ++m) _Pragma("unroll") for (int n = 0; n < 2; ++n) _Pragma("unroll") for (int k = 0; k < 2; ++k) \
;         acc[ai][bj][m][n] = __builtin_amdgcn_mfma_f32_16x16x32_bf16(Bt[n][k], At[m][k], acc[ai][bj][m][n], 0, 0, 0); __builtin_amdgcn_s_setprio(0); } while (0)
; #define PG8_WAIT_V(n) asm volatile("s_waitcnt vmcnt(" #n ")" ::: "memory")
; template <class Epi, class Sched, bool ALIGN_EPI = false, bool SP2 = false>
; __device__ __forceinline__ void gemm_phase(PG8_LAS unsigned char* lds, const Gemm g, const Sched& S, const Epi& E, int tid_in) {
;     ...
;         const char* nA = has_next ? (const char*)g.A + (size_t)nxt.pm * tstep : cA; const char* nB = has_next ? (const char*)g.Bt + (size_t)nxt.pn * tstepB : cB;
;         for (int t = 0; t < nt; t += 2) {
;             const bool last = (t == nt - 2);
;             const char* a1 = cA + (size_t)(t + 1) * kstep;
;             const char* a2 = last ? nA : cA + (size_t)(t + 2) * kstep; const char* b2 = last ? nB : cB + (size_t)(t + 2) * kstep;
;             const char* a3 = a2 + kstep; const char* b3 = b2 + kstep;
;             if (last && has_next) S.a_ready(nxt);
;             if constexpr (SP2) {
;             PG8_LDB(B0, 0, 0); PG8_LDB(B1, 0, 1); PG8_SCHED; PG8_LDA(At, 0, 0); PG8_STAGE(PG8_SA(1, 1), a1 + hstep, voffA);
;             PG8_WAIT_V(8); PG8_WAIT_L(0); PG8_BAR; PG8_MMA(0, 0, At, B0); PG8_MMA(0, 1, At, B1); PG8_BAR; PG8_SCHED;
;             PG8_LDA(At, 0, 1); PG8_STAGE(PG8_SB(0, 0), b2, voffB); PG8_STAGE(PG8_SB(0, 1), b2 + hstepB, voffB); PG8_STAGE(PG8_SA(0, 0), a2, voffA);
.LBB0_473:
	s_ashr_i32 s49, s48, 31
	s_lshl_b64 s[26:27], s[48:49], 22
	s_add_u32 s52, s62, s26
	s_addc_u32 s53, s63, s27
	s_and_b64 s[12:13], s[12:13], exec
	s_cselect_b32 s49, s53, s59
	s_cselect_b32 s75, s52, s58
	s_add_u32 s76, s58, 0x100
	s_addc_u32 s77, s59, 0
	s_mov_b32 s79, -2
	s_waitcnt lgkmcnt(0)
	ds_read_b128 v[146:149], v153
	ds_read_b128 v[158:161], v153 offset:1024
	ds_read_b128 v[162:165], v153 offset:2048
	ds_read_b128 v[166:169], v153 offset:3072
	ds_read_b128 v[170:173], v154
	ds_read_b128 v[174:177], v154 offset:1024
	ds_read_b128 v[178:181], v154 offset:2048
	ds_read_b128 v[182:185], v154 offset:3072
	s_add_u32 s12, s56, 0x100
	s_addc_u32 s13, s57, 0
	s_cmpk_eq_i32 s79, 0x7c
	s_cselect_b32 s61, s51, s13
	s_cselect_b32 s60, s50, s12
	s_cselect_b32 s59, s49, s77
	s_cselect_b32 s58, s75, s76
	s_add_i32 m0, s55, 0xc000
	ds_read_b128 v[186:189], v155
	ds_read_b128 v[190:193], v155 offset:1024
	ds_read_b128 v[194:197], v155 offset:2048
	ds_read_b128 v[198:201], v155 offset:3072
	ds_read_b128 v[202:205], v155 offset:4096
	ds_read_b128 v[206:209], v155 offset:5120
	ds_read_b128 v[212:215], v155 offset:6144
	ds_read_b128 v[216:219], v155 offset:7168
	global_load_lds_dwordx4 v138, s[56:57]
	s_add_i32 m0, s55, 0xe000
	s_nop 0
	global_load_lds_dwordx4 v140, s[56:57]
	s_waitcnt vmcnt(8)
	s_waitcnt lgkmcnt(0)
	s_cmp_eq_u32 s98, 1
	s_cbranch_scc0 .Lkb_skip_3
	s_mov_b32 s98, 0
	s_barrier
.Lkb_skip_3:
	s_barrier
	s_setprio 1
	s_waitcnt lgkmcnt(0)
	v_mfma_f32_16x16x32_bf16 v[124:127], v[146:149], v[186:189], 0
	v_mfma_f32_16x16x32_bf16 v[120:123], v[162:165], v[186:189], 0
	v_mfma_f32_16x16x32_bf16 v[108:111], v[146:149], v[194:197], 0
	v_mfma_f32_16x16x32_bf16 v[104:107], v[162:165], v[194:197], 0
	v_mfma_f32_16x16x32_bf16 v[92:95], v[146:149], v[202:205], 0
	v_mfma_f32_16x16x32_bf16 v[88:91], v[162:165], v[202:205], 0
	v_mfma_f32_16x16x32_bf16 v[76:79], v[146:149], v[212:215], 0
	v_mfma_f32_16x16x32_bf16 v[72:75], v[162:165], v[212:215], 0
	v_mfma_f32_16x16x32_bf16 v[124:127], v[158:161], v[190:193], v[124:127]
	v_mfma_f32_16x16x32_bf16 v[120:123], v[166:169], v[190:193], v[120:123]
	v_mfma_f32_16x16x32_bf16 v[108:111], v[158:161], v[198:201], v[108:111]
	v_mfma_f32_16x16x32_bf16 v[104:107], v[166:169], v[198:201], v[104:107]
	v_mfma_f32_16x16x32_bf16 v[92:95], v[158:161], v[206:209], v[92:95]
	v_mfma_f32_16x16x32_bf16 v[88:91], v[166:169], v[206:209], v[88:91]
	v_mfma_f32_16x16x32_bf16 v[76:79], v[158:161], v[216:219], v[76:79]
	v_mfma_f32_16x16x32_bf16 v[72:75], v[166:169], v[216:219], v[72:75]
	s_setprio 0
	s_setprio 1
	v_mfma_f32_16x16x32_bf16 v[116:119], v[170:173], v[186:189], 0
	v_mfma_f32_16x16x32_bf16 v[112:115], v[178:181], v[186:189], 0
	v_mfma_f32_16x16x32_bf16 v[100:103], v[170:173], v[194:197], 0
	v_mfma_f32_16x16x32_bf16 v[96:99], v[178:181], v[194:197], 0
	v_mfma_f32_16x16x32_bf16 v[84:87], v[170:173], v[202:205], 0
	v_mfma_f32_16x16x32_bf16 v[80:83], v[178:181], v[202:205], 0
	v_mfma_f32_16x16x32_bf16 v[68:71], v[170:173], v[212:215], 0
	v_mfma_f32_16x16x32_bf16 v[64:67], v[178:181], v[212:215], 0
	v_mfma_f32_16x16x32_bf16 v[116:119], v[174:177], v[190:193], v[116:119]
	v_mfma_f32_16x16x32_bf16 v[112:115], v[182:185], v[190:193], v[112:115]
	v_mfma_f32_16x16x32_bf16 v[100:103], v[174:177], v[198:201], v[100:103]
	v_mfma_f32_16x16x32_bf16 v[96:99], v[182:185], v[198:201], v[96:99]
	v_mfma_f32_16x16x32_bf16 v[84:87], v[174:177], v[206:209], v[84:87]
	v_mfma_f32_16x16x32_bf16 v[80:83], v[182:185], v[206:209], v[80:83]
	v_mfma_f32_16x16x32_bf16 v[68:71], v[174:177], v[216:219], v[68:71]
	v_mfma_f32_16x16x32_bf16 v[64:67], v[182:185], v[216:219], v[64:67]
	s_setprio 0
	s_barrier
	s_add_i32 s26, s71, s64
	s_mov_b32 m0, s26
	ds_read_b128 v[186:189], v155 offset:16384
	ds_read_b128 v[190:193], v155 offset:17408
	ds_read_b128 v[194:197], v155 offset:18432
	ds_read_b128 v[198:201], v155 offset:19456
	ds_read_b128 v[202:205], v155 offset:20480
	ds_read_b128 v[206:209], v155 offset:21504
	ds_read_b128 v[212:215], v155 offset:22528
	ds_read_b128 v[216:219], v155 offset:23552
	global_load_lds_dwordx4 v130, s[58:59]
	s_add_i32 m0, s26, 0x2000
	s_add_u32 s26, s58, 0x80000
	s_addc_u32 s27, s59, 0
	s_add_i32 s33, s72, s64
	global_load_lds_dwordx4 v134, s[58:59]
	s_mov_b32 m0, s33
	s_nop 0
	global_load_lds_dwordx4 v130, s[26:27]
	s_add_i32 m0, s33, 0x2000
	s_nop 0
	global_load_lds_dwordx4 v134, s[26:27]
	s_mov_b32 m0, s55
	s_nop 0
	global_load_lds_dwordx4 v128, s[60:61]
	s_mov_b32 m0, s65
	s_nop 0
	global_load_lds_dwordx4 v132, s[60:61]
	s_waitcnt vmcnt(8)
	s_waitcnt lgkmcnt(0)
	s_barrier
; #define PG8_STAGE(bufoff, gbase, voff) do { _Pragma("unroll") for (int _i = 0; _i < 2; ++_i) \
;         __builtin_amdgcn_global_load_lds((const unsigned*)((const char*)(gbase) + (voff)[_i]), (PG8_LAS unsigned*)(lds + (bufoff) + ldsw + _i * 8192), 16, 0, 0); } while (0)
; #define PG8_LDA(dst, b, h) do { _Pragma("unroll") for (int m = 0; m < 4; ++m) _Pragma("unroll") for (int k = 0; k < 2; ++k) dst[m][k] = *(const PG8_LAS bf16x8*)(lds + PG8_SA(b, h) + aoff + m * 2048 + k * 1024); } while (0)
; #define PG8_LDB(dst, b, h) do { _Pragma("unroll") for (int n = 0; n < 2; ++n) _Pragma("unroll") for (int k = 0; k < 2; ++k) dst[n][k] = *(const PG8_LAS bf16x8*)(lds + PG8_SB(b, h) + boff + n * 2048 + k * 1024); } while (0)
; #define PG8_MMA(ai, bj, At, Bt) do { __builtin_amdgcn_s_setprio(1); _Pragma("unroll") for (int m = 0; m < 4; ++m) _Pragma("unroll") for (int n = 0; n < 2; ++n) _Pragma("unroll") for (int k = 0; k < 2; ++k) \
;         acc[ai][bj][m][n] = __builtin_amdgcn_mfma_f32_16x16x32_bf16(Bt[n][k], At[m][k], acc[ai][bj][m][n], 0, 0, 0); __builtin_amdgcn_s_setprio(0); } while (0)
; #define PG8_WAIT_V(n) asm volatile("s_waitcnt vmcnt(" #n ")" ::: "memory")
; #define PG8_WAIT_L(n) asm volatile("s_waitcnt lgkmcnt(" #n ")" ::: "memory")
; #define PG8_BAR __builtin_amdgcn_s_barrier()
; #define PG8_SCHED __builtin_amdgcn_sched_barrier(0)
; template <class Epi, class Sched, bool ALIGN_EPI = false, bool SP2 = false>
; __device__ __forceinline__ void gemm_phase(PG8_LAS unsigned char* lds, const Gemm g, const Sched& S, const Epi& E, int tid_in) {
;     ...
;             PG8_WAIT_V(8); PG8_WAIT_L(0); PG8_BAR; PG8_MMA(0, 0, At, B0); PG8_MMA(0, 1, At, B1); PG8_BAR; PG8_SCHED;
;             PG8_LDA(At, 0, 1); PG8_STAGE(PG8_SB(0, 0), b2, voffB); PG8_STAGE(PG8_SB(0, 1), b2 + hstepB, voffB); PG8_STAGE(PG8_SA(0, 0), a2, voffA);
;             PG8_WAIT_V(8); PG8_WAIT_L(0); PG8_BAR; PG8_MMA(1, 0, At, B0); PG8_MMA(1, 1, At, B1); PG8_BAR; PG8_SCHED;
;             PG8_LDB(B0, 1, 0); PG8_LDB(B1, 1, 1); PG8_SCHED; PG8_LDA(At, 1, 0); PG8_STAGE(PG8_SA(0, 1), a2 + hstep, voffA);
;             PG8_WAIT_V(8); PG8_WAIT_L(0); PG8_BAR; PG8_MMA(0, 0, At, B0); PG8_MMA(0, 1, At, B1); PG8_BAR; PG8_SCHED;
;             PG8_LDA(At, 1, 1); PG8_STAGE(PG8_SB(1, 0), b3, voffB); PG8_STAGE(PG8_SB(1, 1), b3 + hstepB, voffB); PG8_STAGE(PG8_SA(1, 0), a3, voffA);
	s_setprio 1
	s_waitcnt lgkmcnt(0)
	v_mfma_f32_16x16x32_bf16 v[60:63], v[146:149], v[186:189], 0
	v_mfma_f32_16x16x32_bf16 v[56:59], v[162:165], v[186:189], 0
	v_mfma_f32_16x16x32_bf16 v[44:47], v[146:149], v[194:197], 0
	v_mfma_f32_16x16x32_bf16 v[40:43], v[162:165], v[194:197], 0
	v_mfma_f32_16x16x32_bf16 v[28:31], v[146:149], v[202:205], 0
	v_mfma_f32_16x16x32_bf16 v[24:27], v[162:165], v[202:205], 0
	v_mfma_f32_16x16x32_bf16 v[12:15], v[146:149], v[212:215], 0
	v_mfma_f32_16x16x32_bf16 v[8:11], v[162:165], v[212:215], 0
	v_mfma_f32_16x16x32_bf16 v[60:63], v[158:161], v[190:193], v[60:63]
	v_mfma_f32_16x16x32_bf16 v[56:59], v[166:169], v[190:193], v[56:59]
	v_mfma_f32_16x16x32_bf16 v[44:47], v[158:161], v[198:201], v[44:47]
	v_mfma_f32_16x16x32_bf16 v[40:43], v[166:169], v[198:201], v[40:43]
	v_mfma_f32_16x16x32_bf16 v[28:31], v[158:161], v[206:209], v[28:31]
	v_mfma_f32_16x16x32_bf16 v[24:27], v[166:169], v[206:209], v[24:27]
	v_mfma_f32_16x16x32_bf16 v[12:15], v[158:161], v[216:219], v[12:15]
	v_mfma_f32_16x16x32_bf16 v[8:11], v[166:169], v[216:219], v[8:11]
	s_setprio 0
	s_setprio 1
	v_mfma_f32_16x16x32_bf16 v[52:55], v[170:173], v[186:189], 0
	v_mfma_f32_16x16x32_bf16 v[48:51], v[178:181], v[186:189], 0
	v_mfma_f32_16x16x32_bf16 v[36:39], v[170:173], v[194:197], 0
	v_mfma_f32_16x16x32_bf16 v[32:35], v[178:181], v[194:197], 0
	v_mfma_f32_16x16x32_bf16 v[20:23], v[170:173], v[202:205], 0
	v_mfma_f32_16x16x32_bf16 v[16:19], v[178:181], v[202:205], 0
	v_mfma_f32_16x16x32_bf16 v[4:7], v[170:173], v[212:215], 0
	v_mfma_f32_16x16x32_bf16 v[0:3], v[178:181], v[212:215], 0
	v_mfma_f32_16x16x32_bf16 v[52:55], v[174:177], v[190:193], v[52:55]
	v_mfma_f32_16x16x32_bf16 v[48:51], v[182:185], v[190:193], v[48:51]
	v_mfma_f32_16x16x32_bf16 v[36:39], v[174:177], v[198:201], v[36:39]
	v_mfma_f32_16x16x32_bf16 v[32:35], v[182:185], v[198:201], v[32:35]
	v_mfma_f32_16x16x32_bf16 v[20:23], v[174:177], v[206:209], v[20:23]
	v_mfma_f32_16x16x32_bf16 v[16:19], v[182:185], v[206:209], v[16:19]
	v_mfma_f32_16x16x32_bf16 v[4:7], v[174:177], v[216:219], v[4:7]
	v_mfma_f32_16x16x32_bf16 v[0:3], v[182:185], v[216:219], v[0:3]
	s_setprio 0
	s_barrier
	s_add_i32 s33, 0, 0x18000
	s_add_i32 s56, 0, 0x1c000
	v_add_u32_e32 v166, s33, v137
	v_add_u32_e32 v182, s56, v137
	ds_read_b128 v[146:149], v166
	ds_read_b128 v[158:161], v166 offset:1024
	ds_read_b128 v[162:165], v166 offset:2048
	ds_read_b128 v[166:169], v166 offset:3072
	ds_read_b128 v[170:173], v182
	ds_read_b128 v[174:177], v182 offset:1024
	ds_read_b128 v[178:181], v182 offset:2048
	ds_read_b128 v[182:185], v182 offset:3072
	s_add_u32 s26, s60, 0x204000
	s_addc_u32 s27, s61, 0
	s_mov_b32 m0, s66
	ds_read_b128 v[186:189], v155 offset:32768
	ds_read_b128 v[190:193], v155 offset:33792
	ds_read_b128 v[194:197], v155 offset:34816
	ds_read_b128 v[198:201], v155 offset:35840
	ds_read_b128 v[202:205], v155 offset:36864
	ds_read_b128 v[206:209], v155 offset:37888
	ds_read_b128 v[212:215], v155 offset:38912
	ds_read_b128 v[216:219], v155 offset:39936
	global_load_lds_dwordx4 v128, s[26:27]
	s_mov_b32 m0, s67
	s_nop 0
	global_load_lds_dwordx4 v132, s[26:27]
	s_waitcnt vmcnt(8)
	s_waitcnt lgkmcnt(0)
	s_barrier
	s_setprio 1
	s_waitcnt lgkmcnt(0)
	v_mfma_f32_16x16x32_bf16 v[124:127], v[146:149], v[186:189], v[124:127]
	v_mfma_f32_16x16x32_bf16 v[120:123], v[162:165], v[186:189], v[120:123]
	v_mfma_f32_16x16x32_bf16 v[108:111], v[146:149], v[194:197], v[108:111]
	v_mfma_f32_16x16x32_bf16 v[104:107], v[162:165], v[194:197], v[104:107]
	v_mfma_f32_16x16x32_bf16 v[92:95], v[146:149], v[202:205], v[92:95]
	v_mfma_f32_16x16x32_bf16 v[88:91], v[162:165], v[202:205], v[88:91]
	v_mfma_f32_16x16x32_bf16 v[76:79], v[146:149], v[212:215], v[76:79]
	v_mfma_f32_16x16x32_bf16 v[72:75], v[162:165], v[212:215], v[72:75]
	v_mfma_f32_16x16x32_bf16 v[124:127], v[158:161], v[190:193], v[124:127]
	v_mfma_f32_16x16x32_bf16 v[120:123], v[166:169], v[190:193], v[120:123]
	v_mfma_f32_16x16x32_bf16 v[108:111], v[158:161], v[198:201], v[108:111]
	v_mfma_f32_16x16x32_bf16 v[104:107], v[166:169], v[198:201], v[104:107]
	v_mfma_f32_16x16x32_bf16 v[92:95], v[158:161], v[206:209], v[92:95]
	v_mfma_f32_16x16x32_bf16 v[88:91], v[166:169], v[206:209], v[88:91]
	v_mfma_f32_16x16x32_bf16 v[76:79], v[158:161], v[216:219], v[76:79]
	v_mfma_f32_16x16x32_bf16 v[72:75], v[166:169], v[216:219], v[72:75]
	s_setprio 0
	s_setprio 1
	v_mfma_f32_16x16x32_bf16 v[116:119], v[170:173], v[186:189], v[116:119]
	v_mfma_f32_16x16x32_bf16 v[112:115], v[178:181], v[186:189], v[112:115]
	v_mfma_f32_16x16x32_bf16 v[100:103], v[170:173], v[194:197], v[100:103]
	v_mfma_f32_16x16x32_bf16 v[96:99], v[178:181], v[194:197], v[96:99]
	v_mfma_f32_16x16x32_bf16 v[84:87], v[170:173], v[202:205], v[84:87]
	v_mfma_f32_16x16x32_bf16 v[80:83], v[178:181], v[202:205], v[80:83]
	v_mfma_f32_16x16x32_bf16 v[68:71], v[170:173], v[212:215], v[68:71]
	v_mfma_f32_16x16x32_bf16 v[64:67], v[178:181], v[212:215], v[64:67]
	v_mfma_f32_16x16x32_bf16 v[116:119], v[174:177], v[190:193], v[116:119]
	v_mfma_f32_16x16x32_bf16 v[112:115], v[182:185], v[190:193], v[112:115]
	v_mfma_f32_16x16x32_bf16 v[100:103], v[174:177], v[198:201], v[100:103]
	v_mfma_f32_16x16x32_bf16 v[96:99], v[182:185], v[198:201], v[96:99]
	v_mfma_f32_16x16x32_bf16 v[84:87], v[174:177], v[206:209], v[84:87]
	v_mfma_f32_16x16x32_bf16 v[80:83], v[182:185], v[206:209], v[80:83]
	v_mfma_f32_16x16x32_bf16 v[68:71], v[174:177], v[216:219], v[68:71]
	v_mfma_f32_16x16x32_bf16 v[64:67], v[182:185], v[216:219], v[64:67]
	s_setprio 0
	s_barrier
; #define PG8_STAGE(bufoff, gbase, voff) do { _Pragma("unroll") for (int _i = 0; _i < 2; ++_i) \
;         __builtin_amdgcn_global_load_lds((const unsigned*)((const char*)(gbase) + (voff)[_i]), (PG8_LAS unsigned*)(lds + (bufoff) + ldsw + _i * 8192), 16, 0, 0); } while (0)
; #define PG8_LDA(dst, b, h) do { _Pragma("unroll") for (int m = 0; m < 4; ++m) _Pragma("unroll") for (int k = 0; k < 2; ++k) dst[m][k] = *(const PG8_LAS bf16x8*)(lds + PG8_SA(b, h) + aoff + m * 2048 + k * 1024); } while (0)
; #define PG8_MMA(ai, bj, At, Bt) do { __builtin_amdgcn_s_setprio(1); _Pragma("unroll") for (int m = 0; m < 4; ++m) _Pragma("unroll") for (int n = 0; n < 2; ++n) _Pragma("unroll") for (int k = 0; k < 2; ++k) \
;         acc[ai][bj][m][n] = __builtin_amdgcn_mfma_f32_16x16x32_bf16(Bt[n][k], At[m][k], acc[ai][bj][m][n], 0, 0, 0); __builtin_amdgcn_s_setprio(0); } while (0)
; #define PG8_WAIT_V(n) asm volatile("s_waitcnt vmcnt(" #n ")" ::: "memory")
; #define PG8_WAIT_L(n) asm volatile("s_waitcnt lgkmcnt(" #n ")" ::: "memory")
; #define PG8_BAR __builtin_amdgcn_s_barrier()
; #define PG8_SCHED __builtin_amdgcn_sched_barrier(0)
; template <class Epi, class Sched, bool ALIGN_EPI = false, bool SP2 = false>
; __device__ __forceinline__ void gemm_phase(PG8_LAS unsigned char* lds, const Gemm g, const Sched& S, const Epi& E, int tid_in) {
;     ...
;             PG8_LDA(At, 1, 1); PG8_STAGE(PG8_SB(1, 0), b3, voffB); PG8_STAGE(PG8_SB(1, 1), b3 + hstepB, voffB); PG8_STAGE(PG8_SA(1, 0), a3, voffA);
;             PG8_WAIT_V(8); PG8_WAIT_L(0); PG8_BAR; PG8_MMA(1, 0, At, B0); PG8_MMA(1, 1, At, B1); PG8_BAR; PG8_SCHED;
	s_add_i32 s26, s33, s64
	s_add_i32 m0, s26, 0xffffff80
	ds_read_b128 v[186:189], v155 offset:49152
	ds_read_b128 v[190:193], v155 offset:50176
	ds_read_b128 v[194:197], v155 offset:51200
	ds_read_b128 v[198:201], v155 offset:52224
	ds_read_b128 v[202:205], v155 offset:53248
	ds_read_b128 v[206:209], v155 offset:54272
	ds_read_b128 v[212:215], v155 offset:55296
	ds_read_b128 v[216:219], v155 offset:56320
	global_load_lds_dwordx4 v130, s[58:59] offset:128
	s_add_i32 m0, s26, 0x1f80
	s_add_u32 s26, s58, 0x80080
	s_addc_u32 s27, s59, 0
	s_add_i32 s33, s56, s64
	global_load_lds_dwordx4 v134, s[58:59] offset:128
	s_mov_b32 m0, s33
	s_nop 0
	global_load_lds_dwordx4 v130, s[26:27]
	s_add_i32 m0, s33, 0x2000
	s_nop 0
	global_load_lds_dwordx4 v134, s[26:27]
	s_add_i32 m0, s69, 0xffffff80
	s_nop 0
	global_load_lds_dwordx4 v128, s[60:61] offset:128
	s_add_i32 m0, s70, 0xffffff80
	s_nop 0
	global_load_lds_dwordx4 v132, s[60:61] offset:128
	s_waitcnt vmcnt(8)
	s_waitcnt lgkmcnt(0)
	s_barrier
	s_setprio 1
	s_waitcnt lgkmcnt(0)
	v_mfma_f32_16x16x32_bf16 v[60:63], v[146:149], v[186:189], v[60:63]
	v_mfma_f32_16x16x32_bf16 v[56:59], v[162:165], v[186:189], v[56:59]
	v_mfma_f32_16x16x32_bf16 v[44:47], v[146:149], v[194:197], v[44:47]
	v_mfma_f32_16x16x32_bf16 v[40:43], v[162:165], v[194:197], v[40:43]
	v_mfma_f32_16x16x32_bf16 v[28:31], v[146:149], v[202:205], v[28:31]
	v_mfma_f32_16x16x32_bf16 v[24:27], v[162:165], v[202:205], v[24:27]
	v_mfma_f32_16x16x32_bf16 v[12:15], v[146:149], v[212:215], v[12:15]
	v_mfma_f32_16x16x32_bf16 v[8:11], v[162:165], v[212:215], v[8:11]
	v_mfma_f32_16x16x32_bf16 v[60:63], v[158:161], v[190:193], v[60:63]
	v_mfma_f32_16x16x32_bf16 v[56:59], v[166:169], v[190:193], v[56:59]
	v_mfma_f32_16x16x32_bf16 v[44:47], v[158:161], v[198:201], v[44:47]
	v_mfma_f32_16x16x32_bf16 v[40:43], v[166:169], v[198:201], v[40:43]
	v_mfma_f32_16x16x32_bf16 v[28:31], v[158:161], v[206:209], v[28:31]
	v_mfma_f32_16x16x32_bf16 v[24:27], v[166:169], v[206:209], v[24:27]
	v_mfma_f32_16x16x32_bf16 v[12:15], v[158:161], v[216:219], v[12:15]
	v_mfma_f32_16x16x32_bf16 v[8:11], v[166:169], v[216:219], v[8:11]
	s_setprio 0
	s_setprio 1
	v_mfma_f32_16x16x32_bf16 v[52:55], v[170:173], v[186:189], v[52:55]
	v_mfma_f32_16x16x32_bf16 v[48:51], v[178:181], v[186:189], v[48:51]
	v_mfma_f32_16x16x32_bf16 v[36:39], v[170:173], v[194:197], v[36:39]
	v_mfma_f32_16x16x32_bf16 v[32:35], v[178:181], v[194:197], v[32:35]
	v_mfma_f32_16x16x32_bf16 v[20:23], v[170:173], v[202:205], v[20:23]
	v_mfma_f32_16x16x32_bf16 v[16:19], v[178:181], v[202:205], v[16:19]
	v_mfma_f32_16x16x32_bf16 v[4:7], v[170:173], v[212:215], v[4:7]
	v_mfma_f32_16x16x32_bf16 v[0:3], v[178:181], v[212:215], v[0:3]
	v_mfma_f32_16x16x32_bf16 v[52:55], v[174:177], v[190:193], v[52:55]
	v_mfma_f32_16x16x32_bf16 v[48:51], v[182:185], v[190:193], v[48:51]
	v_mfma_f32_16x16x32_bf16 v[36:39], v[174:177], v[198:201], v[36:39]
	v_mfma_f32_16x16x32_bf16 v[32:35], v[182:185], v[198:201], v[32:35]
	v_mfma_f32_16x16x32_bf16 v[20:23], v[174:177], v[206:209], v[20:23]
	v_mfma_f32_16x16x32_bf16 v[16:19], v[182:185], v[206:209], v[16:19]
	v_mfma_f32_16x16x32_bf16 v[4:7], v[174:177], v[216:219], v[4:7]
	v_mfma_f32_16x16x32_bf16 v[0:3], v[182:185], v[216:219], v[0:3]
	s_setprio 0
	s_barrier
	s_add_i32 s79, s79, 2
	s_add_u32 s76, s76, 0x100
	s_addc_u32 s77, s77, 0
	s_cmpk_gt_u32 s79, 0x7d
	s_mov_b64 s[56:57], s[12:13]

; #define PG8_STAGE(bufoff, gbase, voff) do { _Pragma("unroll") for (int _i = 0; _i < 2; ++_i) \
;         __builtin_amdgcn_global_load_lds((const unsigned*)((const char*)(gbase) + (voff)[_i]), (PG8_LAS unsigned*)(lds + (bufoff) + ldsw + _i * 8192), 16, 0, 0); } while (0)
; #define PG8_LDA(dst, b, h) do { _Pragma("unroll") for (int m = 0; m < 4; ++m) _Pragma("unroll") for (int k = 0; k < 2; ++k) dst[m][k] = *(const PG8_LAS bf16x8*)(lds + PG8_SA(b, h) + aoff + m * 2048 + k * 1024); } while (0)
; #define PG8_LDB(dst, b, h) do { _Pragma("unroll") for (int n = 0; n < 2; ++n) _Pragma("unroll") for (int k = 0; k < 2; ++k) dst[n][k] = *(const PG8_LAS bf16x8*)(lds + PG8_SB(b, h) + boff + n * 2048 + k * 1024); } while (0)
; #define PG8_MMA(ai, bj, At, Bt) do { __builtin_amdgcn_s_setprio(1); _Pragma("unroll") for (int m = 0; m < 4; ++m) _Pragma("unroll") for (int n = 0; n < 2; ++n) _Pragma("unroll") for (int k = 0; k < 2; ++k) \
;         acc[ai][bj][m][n] = __builtin_amdgcn_mfma_f32_16x16x32_bf16(Bt[n][k], At[m][k], acc[ai][bj][m][n], 0, 0, 0); __builtin_amdgcn_s_setprio(0); } while (0)
; #define PG8_WAIT_V(n) asm volatile("s_waitcnt vmcnt(" #n ")" ::: "memory")
; template <class Epi, class Sched, bool ALIGN_EPI = false, bool SP2 = false>
; __device__ __forceinline__ void gemm_phase(PG8_LAS unsigned char* lds, const Gemm g, const Sched& S, const Epi& E, int tid_in) {
;     ...
;         const char* nA = has_next ? (const char*)g.A + (size_t)nxt.pm * tstep : cA; const char* nB = has_next ? (const char*)g.Bt + (size_t)nxt.pn * tstepB : cB;
;         for (int t = 0; t < nt; t += 2) {
;             const bool last = (t == nt - 2);
;             const char* a1 = cA + (size_t)(t + 1) * kstep;
;             const char* a2 = last ? nA : cA + (size_t)(t + 2) * kstep; const char* b2 = last ? nB : cB + (size_t)(t + 2) * kstep;
;             const char* a3 = a2 + kstep; const char* b3 = b2 + kstep;
;             if (last && has_next) S.a_ready(nxt);
;             if constexpr (SP2) {
;             PG8_LDB(B0, 0, 0); PG8_LDB(B1, 0, 1); PG8_SCHED; PG8_LDA(At, 0, 0); PG8_STAGE(PG8_SA(1, 1), a1 + hstep, voffA);
;             PG8_WAIT_V(8); PG8_WAIT_L(0); PG8_BAR; PG8_MMA(0, 0, At, B0); PG8_MMA(0, 1, At, B1); PG8_BAR; PG8_SCHED;
;             PG8_LDA(At, 0, 1); PG8_STAGE(PG8_SB(0, 0), b2, voffB); PG8_STAGE(PG8_SB(0, 1), b2 + hstepB, voffB); PG8_STAGE(PG8_SA(0, 0), a2, voffA);
.LBB0_596:
	s_ashr_i32 s53, s52, 31
	s_lshl_b64 s[26:27], s[52:53], 20
	s_add_u32 s54, s28, s26
	s_addc_u32 s55, s29, s27
	s_and_b64 s[26:27], s[8:9], exec
	s_cselect_b32 s11, s55, s61
	s_cselect_b32 s53, s54, s60
	s_ashr_i32 s51, s50, 31
	s_lshl_b64 s[26:27], s[50:51], 20
	s_add_u32 s56, s66, s26
	s_addc_u32 s57, s67, s27
	s_and_b64 s[26:27], s[8:9], exec
	s_cselect_b32 s51, s57, s63
	s_cselect_b32 s85, s56, s62
	s_add_u32 s60, s60, 0x80080
	s_addc_u32 s61, s61, 0
	s_add_u32 s86, s62, 0x100
	s_addc_u32 s87, s63, 0
	s_mov_b32 s88, -2
	s_waitcnt vmcnt(0)
	ds_read_b128 v[128:131], v171
	ds_read_b128 v[132:135], v171 offset:1024
	ds_read_b128 v[136:139], v171 offset:2048
	ds_read_b128 v[184:187], v171 offset:3072
	ds_read_b128 v[188:191], v172
	ds_read_b128 v[192:195], v172 offset:1024
	ds_read_b128 v[196:199], v172 offset:2048
	ds_read_b128 v[200:203], v172 offset:3072
	s_add_u32 s26, s60, 0xfff80080
	s_addc_u32 s27, s61, -1
	s_cmp_eq_u32 s88, 28
	s_cselect_b32 s65, s11, s27
	s_cselect_b32 s64, s53, s26
	s_cselect_b32 s63, s51, s87
	s_cselect_b32 s62, s85, s86
	s_add_i32 m0, s59, 0xc000
	ds_read_b128 v[204:207], v173
	ds_read_b128 v[212:215], v173 offset:1024
	ds_read_b128 v[216:219], v173 offset:2048
	ds_read_b128 v[220:223], v173 offset:3072
	ds_read_b128 v[224:227], v173 offset:4096
	ds_read_b128 v[228:231], v173 offset:5120
	ds_read_b128 v[232:235], v173 offset:6144
	ds_read_b128 v[236:239], v173 offset:7168
	global_load_lds_dwordx4 v158, s[60:61]
	s_add_i32 m0, s59, 0xe000
	s_nop 0
	global_load_lds_dwordx4 v160, s[60:61]
	s_waitcnt vmcnt(8)
	s_waitcnt lgkmcnt(0)
	s_cmp_eq_u32 s98, 1
	s_cbranch_scc0 .Lkb_skip_4
	s_mov_b32 s98, 0
	s_barrier
.Lkb_skip_4:
	s_barrier
	s_setprio 1
	s_waitcnt lgkmcnt(0)
	v_mfma_f32_16x16x32_bf16 v[124:127], v[128:131], v[204:207], 0
	v_mfma_f32_16x16x32_bf16 v[120:123], v[136:139], v[204:207], 0
	v_mfma_f32_16x16x32_bf16 v[108:111], v[128:131], v[216:219], 0
	v_mfma_f32_16x16x32_bf16 v[104:107], v[136:139], v[216:219], 0
	v_mfma_f32_16x16x32_bf16 v[92:95], v[128:131], v[224:227], 0
	v_mfma_f32_16x16x32_bf16 v[88:91], v[136:139], v[224:227], 0
	v_mfma_f32_16x16x32_bf16 v[76:79], v[128:131], v[232:235], 0
	v_mfma_f32_16x16x32_bf16 v[72:75], v[136:139], v[232:235], 0
	v_mfma_f32_16x16x32_bf16 v[124:127], v[132:135], v[212:215], v[124:127]
	v_mfma_f32_16x16x32_bf16 v[120:123], v[184:187], v[212:215], v[120:123]
	v_mfma_f32_16x16x32_bf16 v[108:111], v[132:135], v[220:223], v[108:111]
	v_mfma_f32_16x16x32_bf16 v[104:107], v[184:187], v[220:223], v[104:107]
	v_mfma_f32_16x16x32_bf16 v[92:95], v[132:135], v[228:231], v[92:95]
	v_mfma_f32_16x16x32_bf16 v[88:91], v[184:187], v[228:231], v[88:91]
	v_mfma_f32_16x16x32_bf16 v[76:79], v[132:135], v[236:239], v[76:79]
	v_mfma_f32_16x16x32_bf16 v[72:75], v[184:187], v[236:239], v[72:75]
	s_setprio 0
	s_setprio 1
	v_mfma_f32_16x16x32_bf16 v[116:119], v[188:191], v[204:207], 0
	v_mfma_f32_16x16x32_bf16 v[112:115], v[196:199], v[204:207], 0
	v_mfma_f32_16x16x32_bf16 v[100:103], v[188:191], v[216:219], 0
	v_mfma_f32_16x16x32_bf16 v[96:99], v[196:199], v[216:219], 0
	v_mfma_f32_16x16x32_bf16 v[84:87], v[188:191], v[224:227], 0
	v_mfma_f32_16x16x32_bf16 v[80:83], v[196:199], v[224:227], 0
	v_mfma_f32_16x16x32_bf16 v[68:71], v[188:191], v[232:235], 0
	v_mfma_f32_16x16x32_bf16 v[64:67], v[196:199], v[232:235], 0
	v_mfma_f32_16x16x32_bf16 v[116:119], v[192:195], v[212:215], v[116:119]
	v_mfma_f32_16x16x32_bf16 v[112:115], v[200:203], v[212:215], v[112:115]
	v_mfma_f32_16x16x32_bf16 v[100:103], v[192:195], v[220:223], v[100:103]
	v_mfma_f32_16x16x32_bf16 v[96:99], v[200:203], v[220:223], v[96:99]
	v_mfma_f32_16x16x32_bf16 v[84:87], v[192:195], v[228:231], v[84:87]
	v_mfma_f32_16x16x32_bf16 v[80:83], v[200:203], v[228:231], v[80:83]
	v_mfma_f32_16x16x32_bf16 v[68:71], v[192:195], v[236:239], v[68:71]
	v_mfma_f32_16x16x32_bf16 v[64:67], v[200:203], v[236:239], v[64:67]
	s_setprio 0
	s_barrier
	s_add_i32 s26, s78, s68
	s_mov_b32 m0, s26
	ds_read_b128 v[204:207], v173 offset:16384
	ds_read_b128 v[212:215], v173 offset:17408
	ds_read_b128 v[216:219], v173 offset:18432
	ds_read_b128 v[220:223], v173 offset:19456
	ds_read_b128 v[224:227], v173 offset:20480
	ds_read_b128 v[228:231], v173 offset:21504
	ds_read_b128 v[232:235], v173 offset:22528
	ds_read_b128 v[236:239], v173 offset:23552
	global_load_lds_dwordx4 v144, s[62:63]
	s_add_i32 m0, s26, 0x2000
	s_add_u32 s26, s62, 0x20000
	s_addc_u32 s27, s63, 0
	s_add_i32 s33, s79, s68
	global_load_lds_dwordx4 v148, s[62:63]
	s_mov_b32 m0, s33
	s_nop 0
	global_load_lds_dwordx4 v144, s[26:27]
	s_add_i32 m0, s33, 0x2000
	s_nop 0
	global_load_lds_dwordx4 v148, s[26:27]
	s_mov_b32 m0, s59
	s_nop 0
	global_load_lds_dwordx4 v142, s[64:65]
	s_mov_b32 m0, s69
	s_nop 0
	global_load_lds_dwordx4 v146, s[64:65]
	s_waitcnt vmcnt(8)
	s_waitcnt lgkmcnt(0)
	s_barrier
; #define PG8_STAGE(bufoff, gbase, voff) do { _Pragma("unroll") for (int _i = 0; _i < 2; ++_i) \
;         __builtin_amdgcn_global_load_lds((const unsigned*)((const char*)(gbase) + (voff)[_i]), (PG8_LAS unsigned*)(lds + (bufoff) + ldsw + _i * 8192), 16, 0, 0); } while (0)
; #define PG8_LDA(dst, b, h) do { _Pragma("unroll") for (int m = 0; m < 4; ++m) _Pragma("unroll") for (int k = 0; k < 2; ++k) dst[m][k] = *(const PG8_LAS bf16x8*)(lds + PG8_SA(b, h) + aoff + m * 2048 + k * 1024); } while (0)
; #define PG8_LDB(dst, b, h) do { _Pragma("unroll") for (int n = 0; n < 2; ++n) _Pragma("unroll") for (int k = 0; k < 2; ++k) dst[n][k] = *(const PG8_LAS bf16x8*)(lds + PG8_SB(b, h) + boff + n * 2048 + k * 1024); } while (0)
; #define PG8_MMA(ai, bj, At, Bt) do { __builtin_amdgcn_s_setprio(1); _Pragma("unroll") for (int m = 0; m < 4; ++m) _Pragma("unroll") for (int n = 0; n < 2; ++n) _Pragma("unroll") for (int k = 0; k < 2; ++k) \
;         acc[ai][bj][m][n] = __builtin_amdgcn_mfma_f32_16x16x32_bf16(Bt[n][k], At[m][k], acc[ai][bj][m][n], 0, 0, 0); __builtin_amdgcn_s_setprio(0); } while (0)
; #define PG8_WAIT_V(n) asm volatile("s_waitcnt vmcnt(" #n ")" ::: "memory")
; #define PG8_WAIT_L(n) asm volatile("s_waitcnt lgkmcnt(" #n ")" ::: "memory")
; #define PG8_BAR __builtin_amdgcn_s_barrier()
; #define PG8_SCHED __builtin_amdgcn_sched_barrier(0)
; template <class Epi, class Sched, bool ALIGN_EPI = false, bool SP2 = false>
; __device__ __forceinline__ void gemm_phase(PG8_LAS unsigned char* lds, const Gemm g, const Sched& S, const Epi& E, int tid_in) {
;     ...
;             PG8_WAIT_V(8); PG8_WAIT_L(0); PG8_BAR; PG8_MMA(0, 0, At, B0); PG8_MMA(0, 1, At, B1); PG8_BAR; PG8_SCHED;
;             PG8_LDA(At, 0, 1); PG8_STAGE(PG8_SB(0, 0), b2, voffB); PG8_STAGE(PG8_SB(0, 1), b2 + hstepB, voffB); PG8_STAGE(PG8_SA(0, 0), a2, voffA);
;             PG8_WAIT_V(8); PG8_WAIT_L(0); PG8_BAR; PG8_MMA(1, 0, At, B0); PG8_MMA(1, 1, At, B1); PG8_BAR; PG8_SCHED;
;             PG8_LDB(B0, 1, 0); PG8_LDB(B1, 1, 1); PG8_SCHED; PG8_LDA(At, 1, 0); PG8_STAGE(PG8_SA(0, 1), a2 + hstep, voffA);
;             PG8_WAIT_V(8); PG8_WAIT_L(0); PG8_BAR; PG8_MMA(0, 0, At, B0); PG8_MMA(0, 1, At, B1); PG8_BAR; PG8_SCHED;
;             PG8_LDA(At, 1, 1); PG8_STAGE(PG8_SB(1, 0), b3, voffB); PG8_STAGE(PG8_SB(1, 1), b3 + hstepB, voffB); PG8_STAGE(PG8_SA(1, 0), a3, voffA);
	s_setprio 1
	s_waitcnt lgkmcnt(0)
	v_mfma_f32_16x16x32_bf16 v[60:63], v[128:131], v[204:207], 0
	v_mfma_f32_16x16x32_bf16 v[56:59], v[136:139], v[204:207], 0
	v_mfma_f32_16x16x32_bf16 v[44:47], v[128:131], v[216:219], 0
	v_mfma_f32_16x16x32_bf16 v[40:43], v[136:139], v[216:219], 0
	v_mfma_f32_16x16x32_bf16 v[28:31], v[128:131], v[224:227], 0
	v_mfma_f32_16x16x32_bf16 v[24:27], v[136:139], v[224:227], 0
	v_mfma_f32_16x16x32_bf16 v[12:15], v[128:131], v[232:235], 0
	v_mfma_f32_16x16x32_bf16 v[8:11], v[136:139], v[232:235], 0
	v_mfma_f32_16x16x32_bf16 v[60:63], v[132:135], v[212:215], v[60:63]
	v_mfma_f32_16x16x32_bf16 v[56:59], v[184:187], v[212:215], v[56:59]
	v_mfma_f32_16x16x32_bf16 v[44:47], v[132:135], v[220:223], v[44:47]
	v_mfma_f32_16x16x32_bf16 v[40:43], v[184:187], v[220:223], v[40:43]
	v_mfma_f32_16x16x32_bf16 v[28:31], v[132:135], v[228:231], v[28:31]
	v_mfma_f32_16x16x32_bf16 v[24:27], v[184:187], v[228:231], v[24:27]
	v_mfma_f32_16x16x32_bf16 v[12:15], v[132:135], v[236:239], v[12:15]
	v_mfma_f32_16x16x32_bf16 v[8:11], v[184:187], v[236:239], v[8:11]
	s_setprio 0
	s_setprio 1
	v_mfma_f32_16x16x32_bf16 v[52:55], v[188:191], v[204:207], 0
	v_mfma_f32_16x16x32_bf16 v[48:51], v[196:199], v[204:207], 0
	v_mfma_f32_16x16x32_bf16 v[36:39], v[188:191], v[216:219], 0
	v_mfma_f32_16x16x32_bf16 v[32:35], v[196:199], v[216:219], 0
	v_mfma_f32_16x16x32_bf16 v[20:23], v[188:191], v[224:227], 0
	v_mfma_f32_16x16x32_bf16 v[16:19], v[196:199], v[224:227], 0
	v_mfma_f32_16x16x32_bf16 v[4:7], v[188:191], v[232:235], 0
	v_mfma_f32_16x16x32_bf16 v[0:3], v[196:199], v[232:235], 0
	v_mfma_f32_16x16x32_bf16 v[52:55], v[192:195], v[212:215], v[52:55]
	v_mfma_f32_16x16x32_bf16 v[48:51], v[200:203], v[212:215], v[48:51]
	v_mfma_f32_16x16x32_bf16 v[36:39], v[192:195], v[220:223], v[36:39]
	v_mfma_f32_16x16x32_bf16 v[32:35], v[200:203], v[220:223], v[32:35]
	v_mfma_f32_16x16x32_bf16 v[20:23], v[192:195], v[228:231], v[20:23]
	v_mfma_f32_16x16x32_bf16 v[16:19], v[200:203], v[228:231], v[16:19]
	v_mfma_f32_16x16x32_bf16 v[4:7], v[192:195], v[236:239], v[4:7]
	v_mfma_f32_16x16x32_bf16 v[0:3], v[200:203], v[236:239], v[0:3]
	s_setprio 0
	s_barrier
	s_add_i32 s33, 0, 0x18000
	v_add_u32_e32 v150, s33, v167
	s_add_i32 s89, 0, 0x1c000
	ds_read_b128 v[128:131], v150
	ds_read_b128 v[132:135], v150 offset:1024
	ds_read_b128 v[136:139], v150 offset:2048
	ds_read_b128 v[184:187], v150 offset:3072
	v_add_u32_e32 v150, s89, v167
	ds_read_b128 v[188:191], v150
	ds_read_b128 v[192:195], v150 offset:1024
	ds_read_b128 v[196:199], v150 offset:2048
	ds_read_b128 v[200:203], v150 offset:3072
	s_add_u32 s26, s64, 0x80000
	s_addc_u32 s27, s65, 0
	s_mov_b32 m0, s70
	ds_read_b128 v[204:207], v173 offset:32768
	ds_read_b128 v[212:215], v173 offset:33792
	ds_read_b128 v[216:219], v173 offset:34816
	ds_read_b128 v[220:223], v173 offset:35840
	ds_read_b128 v[224:227], v173 offset:36864
	ds_read_b128 v[228:231], v173 offset:37888
	ds_read_b128 v[232:235], v173 offset:38912
	ds_read_b128 v[236:239], v173 offset:39936
	global_load_lds_dwordx4 v142, s[26:27]
	s_mov_b32 m0, s71
	s_nop 0
	global_load_lds_dwordx4 v146, s[26:27]
	s_waitcnt vmcnt(8)
	s_waitcnt lgkmcnt(0)
	s_barrier
	s_setprio 1
	s_waitcnt lgkmcnt(0)
	v_mfma_f32_16x16x32_bf16 v[124:127], v[128:131], v[204:207], v[124:127]
	v_mfma_f32_16x16x32_bf16 v[120:123], v[136:139], v[204:207], v[120:123]
	v_mfma_f32_16x16x32_bf16 v[108:111], v[128:131], v[216:219], v[108:111]
	v_mfma_f32_16x16x32_bf16 v[104:107], v[136:139], v[216:219], v[104:107]
	v_mfma_f32_16x16x32_bf16 v[92:95], v[128:131], v[224:227], v[92:95]
	v_mfma_f32_16x16x32_bf16 v[88:91], v[136:139], v[224:227], v[88:91]
	v_mfma_f32_16x16x32_bf16 v[76:79], v[128:131], v[232:235], v[76:79]
	v_mfma_f32_16x16x32_bf16 v[72:75], v[136:139], v[232:235], v[72:75]
	v_mfma_f32_16x16x32_bf16 v[124:127], v[132:135], v[212:215], v[124:127]
	v_mfma_f32_16x16x32_bf16 v[120:123], v[184:187], v[212:215], v[120:123]
	v_mfma_f32_16x16x32_bf16 v[108:111], v[132:135], v[220:223], v[108:111]
	v_mfma_f32_16x16x32_bf16 v[104:107], v[184:187], v[220:223], v[104:107]
	v_mfma_f32_16x16x32_bf16 v[92:95], v[132:135], v[228:231], v[92:95]
	v_mfma_f32_16x16x32_bf16 v[88:91], v[184:187], v[228:231], v[88:91]
	v_mfma_f32_16x16x32_bf16 v[76:79], v[132:135], v[236:239], v[76:79]
	v_mfma_f32_16x16x32_bf16 v[72:75], v[184:187], v[236:239], v[72:75]
	s_setprio 0
	s_setprio 1
	v_mfma_f32_16x16x32_bf16 v[116:119], v[188:191], v[204:207], v[116:119]
	v_mfma_f32_16x16x32_bf16 v[112:115], v[196:199], v[204:207], v[112:115]
	v_mfma_f32_16x16x32_bf16 v[100:103], v[188:191], v[216:219], v[100:103]
	v_mfma_f32_16x16x32_bf16 v[96:99], v[196:199], v[216:219], v[96:99]
	v_mfma_f32_16x16x32_bf16 v[84:87], v[188:191], v[224:227], v[84:87]
	v_mfma_f32_16x16x32_bf16 v[80:83], v[196:199], v[224:227], v[80:83]
	v_mfma_f32_16x16x32_bf16 v[68:71], v[188:191], v[232:235], v[68:71]
	v_mfma_f32_16x16x32_bf16 v[64:67], v[196:199], v[232:235], v[64:67]
	v_mfma_f32_16x16x32_bf16 v[116:119], v[192:195], v[212:215], v[116:119]
	v_mfma_f32_16x16x32_bf16 v[112:115], v[200:203], v[212:215], v[112:115]
	v_mfma_f32_16x16x32_bf16 v[100:103], v[192:195], v[220:223], v[100:103]
	v_mfma_f32_16x16x32_bf16 v[96:99], v[200:203], v[220:223], v[96:99]
	v_mfma_f32_16x16x32_bf16 v[84:87], v[192:195], v[228:231], v[84:87]
	v_mfma_f32_16x16x32_bf16 v[80:83], v[200:203], v[228:231], v[80:83]
	v_mfma_f32_16x16x32_bf16 v[68:71], v[192:195], v[236:239], v[68:71]
	v_mfma_f32_16x16x32_bf16 v[64:67], v[200:203], v[236:239], v[64:67]
	s_setprio 0
	s_barrier
; #define PG8_STAGE(bufoff, gbase, voff) do { _Pragma("unroll") for (int _i = 0; _i < 2; ++_i) \
;         __builtin_amdgcn_global_load_lds((const unsigned*)((const char*)(gbase) + (voff)[_i]), (PG8_LAS unsigned*)(lds + (bufoff) + ldsw + _i * 8192), 16, 0, 0); } while (0)
; #define PG8_LDA(dst, b, h) do { _Pragma("unroll") for (int m = 0; m < 4; ++m) _Pragma("unroll") for (int k = 0; k < 2; ++k) dst[m][k] = *(const PG8_LAS bf16x8*)(lds + PG8_SA(b, h) + aoff + m * 2048 + k * 1024); } while (0)
; #define PG8_MMA(ai, bj, At, Bt) do { __builtin_amdgcn_s_setprio(1); _Pragma("unroll") for (int m = 0; m < 4; ++m) _Pragma("unroll") for (int n = 0; n < 2; ++n) _Pragma("unroll") for (int k = 0; k < 2; ++k) \
;         acc[ai][bj][m][n] = __builtin_amdgcn_mfma_f32_16x16x32_bf16(Bt[n][k], At[m][k], acc[ai][bj][m][n], 0, 0, 0); __builtin_amdgcn_s_setprio(0); } while (0)
; #define PG8_WAIT_V(n) asm volatile("s_waitcnt vmcnt(" #n ")" ::: "memory")
; #define PG8_WAIT_L(n) asm volatile("s_waitcnt lgkmcnt(" #n ")" ::: "memory")
; #define PG8_BAR __builtin_amdgcn_s_barrier()
; #define PG8_SCHED __builtin_amdgcn_sched_barrier(0)
; template <class Epi, class Sched, bool ALIGN_EPI = false, bool SP2 = false>
; __device__ __forceinline__ void gemm_phase(PG8_LAS unsigned char* lds, const Gemm g, const Sched& S, const Epi& E, int tid_in) {
;     ...
;             PG8_LDA(At, 1, 1); PG8_STAGE(PG8_SB(1, 0), b3, voffB); PG8_STAGE(PG8_SB(1, 1), b3 + hstepB, voffB); PG8_STAGE(PG8_SA(1, 0), a3, voffA);
;             PG8_WAIT_V(8); PG8_WAIT_L(0); PG8_BAR; PG8_MMA(1, 0, At, B0); PG8_MMA(1, 1, At, B1); PG8_BAR; PG8_SCHED;
	s_add_i32 s26, s33, s68
	s_add_i32 m0, s26, 0xffffff80
	ds_read_b128 v[204:207], v173 offset:49152
	ds_read_b128 v[212:215], v173 offset:50176
	ds_read_b128 v[216:219], v173 offset:51200
	ds_read_b128 v[220:223], v173 offset:52224
	ds_read_b128 v[224:227], v173 offset:53248
	ds_read_b128 v[228:231], v173 offset:54272
	ds_read_b128 v[232:235], v173 offset:55296
	ds_read_b128 v[236:239], v173 offset:56320
	global_load_lds_dwordx4 v144, s[62:63] offset:128
	s_add_i32 m0, s26, 0x1f80
	s_add_u32 s26, s62, 0x20080
	s_addc_u32 s27, s63, 0
	s_add_i32 s33, s89, s68
	global_load_lds_dwordx4 v148, s[62:63] offset:128
	s_mov_b32 m0, s33
	s_nop 0
	global_load_lds_dwordx4 v144, s[26:27]
	s_add_i32 m0, s33, 0x2000
	s_nop 0
	global_load_lds_dwordx4 v148, s[26:27]
	s_add_i32 m0, s74, 0xffffff80
	s_nop 0
	global_load_lds_dwordx4 v142, s[64:65] offset:128
	s_add_i32 m0, s75, 0xffffff80
	s_nop 0
	global_load_lds_dwordx4 v146, s[64:65] offset:128
	s_waitcnt vmcnt(8)
	s_waitcnt lgkmcnt(0)
	s_barrier
	s_setprio 1
	s_waitcnt lgkmcnt(0)
	v_mfma_f32_16x16x32_bf16 v[60:63], v[128:131], v[204:207], v[60:63]
	v_mfma_f32_16x16x32_bf16 v[56:59], v[136:139], v[204:207], v[56:59]
	v_mfma_f32_16x16x32_bf16 v[44:47], v[128:131], v[216:219], v[44:47]
	v_mfma_f32_16x16x32_bf16 v[40:43], v[136:139], v[216:219], v[40:43]
	v_mfma_f32_16x16x32_bf16 v[28:31], v[128:131], v[224:227], v[28:31]
	v_mfma_f32_16x16x32_bf16 v[24:27], v[136:139], v[224:227], v[24:27]
	v_mfma_f32_16x16x32_bf16 v[12:15], v[128:131], v[232:235], v[12:15]
	v_mfma_f32_16x16x32_bf16 v[8:11], v[136:139], v[232:235], v[8:11]
	v_mfma_f32_16x16x32_bf16 v[60:63], v[132:135], v[212:215], v[60:63]
	v_mfma_f32_16x16x32_bf16 v[56:59], v[184:187], v[212:215], v[56:59]
	v_mfma_f32_16x16x32_bf16 v[44:47], v[132:135], v[220:223], v[44:47]
	v_mfma_f32_16x16x32_bf16 v[40:43], v[184:187], v[220:223], v[40:43]
	v_mfma_f32_16x16x32_bf16 v[28:31], v[132:135], v[228:231], v[28:31]
	v_mfma_f32_16x16x32_bf16 v[24:27], v[184:187], v[228:231], v[24:27]
	v_mfma_f32_16x16x32_bf16 v[12:15], v[132:135], v[236:239], v[12:15]
	v_mfma_f32_16x16x32_bf16 v[8:11], v[184:187], v[236:239], v[8:11]
	s_setprio 0
	s_setprio 1
	v_mfma_f32_16x16x32_bf16 v[52:55], v[188:191], v[204:207], v[52:55]
	v_mfma_f32_16x16x32_bf16 v[48:51], v[196:199], v[204:207], v[48:51]
	v_mfma_f32_16x16x32_bf16 v[36:39], v[188:191], v[216:219], v[36:39]
	v_mfma_f32_16x16x32_bf16 v[32:35], v[196:199], v[216:219], v[32:35]
	v_mfma_f32_16x16x32_bf16 v[20:23], v[188:191], v[224:227], v[20:23]
	v_mfma_f32_16x16x32_bf16 v[16:19], v[196:199], v[224:227], v[16:19]
	v_mfma_f32_16x16x32_bf16 v[4:7], v[188:191], v[232:235], v[4:7]
	v_mfma_f32_16x16x32_bf16 v[0:3], v[196:199], v[232:235], v[0:3]
	v_mfma_f32_16x16x32_bf16 v[52:55], v[192:195], v[212:215], v[52:55]
	v_mfma_f32_16x16x32_bf16 v[48:51], v[200:203], v[212:215], v[48:51]
	v_mfma_f32_16x16x32_bf16 v[36:39], v[192:195], v[220:223], v[36:39]
	v_mfma_f32_16x16x32_bf16 v[32:35], v[200:203], v[220:223], v[32:35]
	v_mfma_f32_16x16x32_bf16 v[20:23], v[192:195], v[228:231], v[20:23]
	v_mfma_f32_16x16x32_bf16 v[16:19], v[200:203], v[228:231], v[16:19]
	v_mfma_f32_16x16x32_bf16 v[4:7], v[192:195], v[236:239], v[4:7]
	v_mfma_f32_16x16x32_bf16 v[0:3], v[200:203], v[236:239], v[0:3]
	s_setprio 0
	s_barrier
	s_add_i32 s88, s88, 2
	s_add_u32 s60, s60, 0x100
	s_addc_u32 s61, s61, 0
	s_add_u32 s86, s86, 0x100
	s_addc_u32 s87, s87, 0
	s_cmp_gt_u32 s88, 29

; #define PG8_STAGE(bufoff, gbase, voff) do { _Pragma("unroll") for (int _i = 0; _i < 2; ++_i) \
;         __builtin_amdgcn_global_load_lds((const unsigned*)((const char*)(gbase) + (voff)[_i]), (PG8_LAS unsigned*)(lds + (bufoff) + ldsw + _i * 8192), 16, 0, 0); } while (0)
; #define PG8_LDA(dst, b, h) do { _Pragma("unroll") for (int m = 0; m < 4; ++m) _Pragma("unroll") for (int k = 0; k < 2; ++k) dst[m][k] = *(const PG8_LAS bf16x8*)(lds + PG8_SA(b, h) + aoff + m * 2048 + k * 1024); } while (0)
; #define PG8_LDB(dst, b, h) do { _Pragma("unroll") for (int n = 0; n < 2; ++n) _Pragma("unroll") for (int k = 0; k < 2; ++k) dst[n][k] = *(const PG8_LAS bf16x8*)(lds + PG8_SB(b, h) + boff + n * 2048 + k * 1024); } while (0)
; #define PG8_MMA(ai, bj, At, Bt) do { __builtin_amdgcn_s_setprio(1); _Pragma("unroll") for (int m = 0; m < 4; ++m) _Pragma("unroll") for (int n = 0; n < 2; ++n) _Pragma("unroll") for (int k = 0; k < 2; ++k) \
;         acc[ai][bj][m][n] = __builtin_amdgcn_mfma_f32_16x16x32_bf16(Bt[n][k], At[m][k], acc[ai][bj][m][n], 0, 0, 0); __builtin_amdgcn_s_setprio(0); } while (0)
; #define PG8_WAIT_V(n) asm volatile("s_waitcnt vmcnt(" #n ")" ::: "memory")
; template <class Epi, class Sched, bool ALIGN_EPI = false, bool SP2 = false>
; __device__ __forceinline__ void gemm_phase(PG8_LAS unsigned char* lds, const Gemm g, const Sched& S, const Epi& E, int tid_in) {
;     ...
;         const char* nA = has_next ? (const char*)g.A + (size_t)nxt.pm * tstep : cA; const char* nB = has_next ? (const char*)g.Bt + (size_t)nxt.pn * tstepB : cB;
;         for (int t = 0; t < nt; t += 2) {
;             const bool last = (t == nt - 2);
;             const char* a1 = cA + (size_t)(t + 1) * kstep;
;             const char* a2 = last ? nA : cA + (size_t)(t + 2) * kstep; const char* b2 = last ? nB : cB + (size_t)(t + 2) * kstep;
;             const char* a3 = a2 + kstep; const char* b3 = b2 + kstep;
;             if (last && has_next) S.a_ready(nxt);
;             if constexpr (SP2) {
;             PG8_LDB(B0, 0, 0); PG8_LDB(B1, 0, 1); PG8_SCHED; PG8_LDA(At, 0, 0); PG8_STAGE(PG8_SA(1, 1), a1 + hstep, voffA);
;             PG8_WAIT_V(8); PG8_WAIT_L(0); PG8_BAR; PG8_MMA(0, 0, At, B0); PG8_MMA(0, 1, At, B1); PG8_BAR; PG8_SCHED;
;             PG8_LDA(At, 0, 1); PG8_STAGE(PG8_SB(0, 0), b2, voffB); PG8_STAGE(PG8_SB(0, 1), b2 + hstepB, voffB); PG8_STAGE(PG8_SA(0, 0), a2, voffA);
.LBB0_766:
	s_ashr_i32 s53, s52, 31
	s_lshl_b64 s[26:27], s[52:53], 19
	s_add_u32 s54, s38, s26
	s_addc_u32 s55, s39, s27
	s_and_b64 s[26:27], s[10:11], exec
	s_cselect_b32 s53, s55, s63
	s_cselect_b32 s59, s54, s62
	s_ashr_i32 s51, s50, 31
	s_lshl_b64 s[26:27], s[50:51], 19
	s_add_u32 s56, s36, s26
	s_addc_u32 s57, s37, s27
	s_and_b64 s[26:27], s[10:11], exec
	s_cselect_b32 s51, s57, s65
	s_cselect_b32 s77, s56, s64
	s_add_u32 s62, s62, 0x40080
	s_addc_u32 s63, s63, 0
	s_add_u32 s78, s64, 0x100
	s_addc_u32 s79, s65, 0
	s_mov_b32 s83, -2
	s_waitcnt lgkmcnt(0)
	ds_read_b128 v[146:149], v153
	ds_read_b128 v[158:161], v153 offset:1024
	ds_read_b128 v[162:165], v153 offset:2048
	ds_read_b128 v[166:169], v153 offset:3072
	ds_read_b128 v[170:173], v154
	ds_read_b128 v[174:177], v154 offset:1024
	ds_read_b128 v[178:181], v154 offset:2048
	ds_read_b128 v[182:185], v154 offset:3072
	s_add_u32 s26, s62, 0xfffc0080
	s_addc_u32 s27, s63, -1
	s_cmp_eq_u32 s83, 12
	s_cselect_b32 s67, s53, s27
	s_cselect_b32 s66, s59, s26
	s_cselect_b32 s65, s51, s79
	s_cselect_b32 s64, s77, s78
	s_add_i32 m0, s61, 0xc000
	ds_read_b128 v[186:189], v155
	ds_read_b128 v[190:193], v155 offset:1024
	ds_read_b128 v[194:197], v155 offset:2048
	ds_read_b128 v[198:201], v155 offset:3072
	ds_read_b128 v[202:205], v155 offset:4096
	ds_read_b128 v[206:209], v155 offset:5120
	ds_read_b128 v[210:213], v155 offset:6144
	ds_read_b128 v[214:217], v155 offset:7168
	global_load_lds_dwordx4 v138, s[62:63]
	s_add_i32 m0, s61, 0xe000
	s_nop 0
	global_load_lds_dwordx4 v140, s[62:63]
	s_waitcnt vmcnt(8)
	s_waitcnt lgkmcnt(0)
	s_cmp_eq_u32 s98, 1
	s_cbranch_scc0 .Lkb_skip_5
	s_mov_b32 s98, 0
	s_barrier
.Lkb_skip_5:
	s_barrier
	s_setprio 1
	s_waitcnt lgkmcnt(0)
	v_mfma_f32_16x16x32_bf16 v[124:127], v[146:149], v[186:189], 0
	v_mfma_f32_16x16x32_bf16 v[120:123], v[162:165], v[186:189], 0
	v_mfma_f32_16x16x32_bf16 v[108:111], v[146:149], v[194:197], 0
	v_mfma_f32_16x16x32_bf16 v[104:107], v[162:165], v[194:197], 0
	v_mfma_f32_16x16x32_bf16 v[92:95], v[146:149], v[202:205], 0
	v_mfma_f32_16x16x32_bf16 v[88:91], v[162:165], v[202:205], 0
	v_mfma_f32_16x16x32_bf16 v[76:79], v[146:149], v[210:213], 0
	v_mfma_f32_16x16x32_bf16 v[72:75], v[162:165], v[210:213], 0
	v_mfma_f32_16x16x32_bf16 v[124:127], v[158:161], v[190:193], v[124:127]
	v_mfma_f32_16x16x32_bf16 v[120:123], v[166:169], v[190:193], v[120:123]
	v_mfma_f32_16x16x32_bf16 v[108:111], v[158:161], v[198:201], v[108:111]
	v_mfma_f32_16x16x32_bf16 v[104:107], v[166:169], v[198:201], v[104:107]
	v_mfma_f32_16x16x32_bf16 v[92:95], v[158:161], v[206:209], v[92:95]
	v_mfma_f32_16x16x32_bf16 v[88:91], v[166:169], v[206:209], v[88:91]
	v_mfma_f32_16x16x32_bf16 v[76:79], v[158:161], v[214:217], v[76:79]
	v_mfma_f32_16x16x32_bf16 v[72:75], v[166:169], v[214:217], v[72:75]
	s_setprio 0
	s_setprio 1
	v_mfma_f32_16x16x32_bf16 v[116:119], v[170:173], v[186:189], 0
	v_mfma_f32_16x16x32_bf16 v[112:115], v[178:181], v[186:189], 0
	v_mfma_f32_16x16x32_bf16 v[100:103], v[170:173], v[194:197], 0
	v_mfma_f32_16x16x32_bf16 v[96:99], v[178:181], v[194:197], 0
	v_mfma_f32_16x16x32_bf16 v[84:87], v[170:173], v[202:205], 0
	v_mfma_f32_16x16x32_bf16 v[80:83], v[178:181], v[202:205], 0
	v_mfma_f32_16x16x32_bf16 v[68:71], v[170:173], v[210:213], 0
	v_mfma_f32_16x16x32_bf16 v[64:67], v[178:181], v[210:213], 0
	v_mfma_f32_16x16x32_bf16 v[116:119], v[174:177], v[190:193], v[116:119]
	v_mfma_f32_16x16x32_bf16 v[112:115], v[182:185], v[190:193], v[112:115]
	v_mfma_f32_16x16x32_bf16 v[100:103], v[174:177], v[198:201], v[100:103]
	v_mfma_f32_16x16x32_bf16 v[96:99], v[182:185], v[198:201], v[96:99]
	v_mfma_f32_16x16x32_bf16 v[84:87], v[174:177], v[206:209], v[84:87]
	v_mfma_f32_16x16x32_bf16 v[80:83], v[182:185], v[206:209], v[80:83]
	v_mfma_f32_16x16x32_bf16 v[68:71], v[174:177], v[214:217], v[68:71]
	v_mfma_f32_16x16x32_bf16 v[64:67], v[182:185], v[214:217], v[64:67]
	s_setprio 0
	s_barrier
	s_add_i32 s26, s75, s68
	s_mov_b32 m0, s26
	ds_read_b128 v[186:189], v155 offset:16384
	ds_read_b128 v[190:193], v155 offset:17408
	ds_read_b128 v[194:197], v155 offset:18432
	ds_read_b128 v[198:201], v155 offset:19456
	ds_read_b128 v[202:205], v155 offset:20480
	ds_read_b128 v[206:209], v155 offset:21504
	ds_read_b128 v[210:213], v155 offset:22528
	ds_read_b128 v[214:217], v155 offset:23552
	global_load_lds_dwordx4 v130, s[64:65]
	s_add_i32 m0, s26, 0x2000
	s_add_u32 s26, s64, 0x10000
	s_addc_u32 s27, s65, 0
	s_add_i32 s33, s76, s68
	global_load_lds_dwordx4 v134, s[64:65]
	s_mov_b32 m0, s33
	s_nop 0
	global_load_lds_dwordx4 v130, s[26:27]
	s_add_i32 m0, s33, 0x2000
	s_nop 0
	global_load_lds_dwordx4 v134, s[26:27]
	s_mov_b32 m0, s61
	s_nop 0
	global_load_lds_dwordx4 v128, s[66:67]
	s_mov_b32 m0, s69
	s_nop 0
	global_load_lds_dwordx4 v132, s[66:67]
	s_waitcnt vmcnt(8)
	s_waitcnt lgkmcnt(0)
	s_barrier
; #define PG8_STAGE(bufoff, gbase, voff) do { _Pragma("unroll") for (int _i = 0; _i < 2; ++_i) \
;         __builtin_amdgcn_global_load_lds((const unsigned*)((const char*)(gbase) + (voff)[_i]), (PG8_LAS unsigned*)(lds + (bufoff) + ldsw + _i * 8192), 16, 0, 0); } while (0)
; #define PG8_LDA(dst, b, h) do { _Pragma("unroll") for (int m = 0; m < 4; ++m) _Pragma("unroll") for (int k = 0; k < 2; ++k) dst[m][k] = *(const PG8_LAS bf16x8*)(lds + PG8_SA(b, h) + aoff + m * 2048 + k * 1024); } while (0)
; #define PG8_LDB(dst, b, h) do { _Pragma("unroll") for (int n = 0; n < 2; ++n) _Pragma("unroll") for (int k = 0; k < 2; ++k) dst[n][k] = *(const PG8_LAS bf16x8*)(lds + PG8_SB(b, h) + boff + n * 2048 + k * 1024); } while (0)
; #define PG8_MMA(ai, bj, At, Bt) do { __builtin_amdgcn_s_setprio(1); _Pragma("unroll") for (int m = 0; m < 4; ++m) _Pragma("unroll") for (int n = 0; n < 2; ++n) _Pragma("unroll") for (int k = 0; k < 2; ++k) \
;         acc[ai][bj][m][n] = __builtin_amdgcn_mfma_f32_16x16x32_bf16(Bt[n][k], At[m][k], acc[ai][bj][m][n], 0, 0, 0); __builtin_amdgcn_s_setprio(0); } while (0)
; #define PG8_WAIT_V(n) asm volatile("s_waitcnt vmcnt(" #n ")" ::: "memory")
; #define PG8_WAIT_L(n) asm volatile("s_waitcnt lgkmcnt(" #n ")" ::: "memory")
; #define PG8_BAR __builtin_amdgcn_s_barrier()
; #define PG8_SCHED __builtin_amdgcn_sched_barrier(0)
; template <class Epi, class Sched, bool ALIGN_EPI = false, bool SP2 = false>
; __device__ __forceinline__ void gemm_phase(PG8_LAS unsigned char* lds, const Gemm g, const Sched& S, const Epi& E, int tid_in) {
;     ...
;             PG8_WAIT_V(8); PG8_WAIT_L(0); PG8_BAR; PG8_MMA(0, 0, At, B0); PG8_MMA(0, 1, At, B1); PG8_BAR; PG8_SCHED;
;             PG8_LDA(At, 0, 1); PG8_STAGE(PG8_SB(0, 0), b2, voffB); PG8_STAGE(PG8_SB(0, 1), b2 + hstepB, voffB); PG8_STAGE(PG8_SA(0, 0), a2, voffA);
;             PG8_WAIT_V(8); PG8_WAIT_L(0); PG8_BAR; PG8_MMA(1, 0, At, B0); PG8_MMA(1, 1, At, B1); PG8_BAR; PG8_SCHED;
;             PG8_LDB(B0, 1, 0); PG8_LDB(B1, 1, 1); PG8_SCHED; PG8_LDA(At, 1, 0); PG8_STAGE(PG8_SA(0, 1), a2 + hstep, voffA);
;             PG8_WAIT_V(8); PG8_WAIT_L(0); PG8_BAR; PG8_MMA(0, 0, At, B0); PG8_MMA(0, 1, At, B1); PG8_BAR; PG8_SCHED;
;             PG8_LDA(At, 1, 1); PG8_STAGE(PG8_SB(1, 0), b3, voffB); PG8_STAGE(PG8_SB(1, 1), b3 + hstepB, voffB); PG8_STAGE(PG8_SA(1, 0), a3, voffA);
	s_setprio 1
	s_waitcnt lgkmcnt(0)
	v_mfma_f32_16x16x32_bf16 v[60:63], v[146:149], v[186:189], 0
	v_mfma_f32_16x16x32_bf16 v[56:59], v[162:165], v[186:189], 0
	v_mfma_f32_16x16x32_bf16 v[44:47], v[146:149], v[194:197], 0
	v_mfma_f32_16x16x32_bf16 v[40:43], v[162:165], v[194:197], 0
	v_mfma_f32_16x16x32_bf16 v[28:31], v[146:149], v[202:205], 0
	v_mfma_f32_16x16x32_bf16 v[24:27], v[162:165], v[202:205], 0
	v_mfma_f32_16x16x32_bf16 v[12:15], v[146:149], v[210:213], 0
	v_mfma_f32_16x16x32_bf16 v[8:11], v[162:165], v[210:213], 0
	v_mfma_f32_16x16x32_bf16 v[60:63], v[158:161], v[190:193], v[60:63]
	v_mfma_f32_16x16x32_bf16 v[56:59], v[166:169], v[190:193], v[56:59]
	v_mfma_f32_16x16x32_bf16 v[44:47], v[158:161], v[198:201], v[44:47]
	v_mfma_f32_16x16x32_bf16 v[40:43], v[166:169], v[198:201], v[40:43]
	v_mfma_f32_16x16x32_bf16 v[28:31], v[158:161], v[206:209], v[28:31]
	v_mfma_f32_16x16x32_bf16 v[24:27], v[166:169], v[206:209], v[24:27]
	v_mfma_f32_16x16x32_bf16 v[12:15], v[158:161], v[214:217], v[12:15]
	v_mfma_f32_16x16x32_bf16 v[8:11], v[166:169], v[214:217], v[8:11]
	s_setprio 0
	s_setprio 1
	v_mfma_f32_16x16x32_bf16 v[52:55], v[170:173], v[186:189], 0
	v_mfma_f32_16x16x32_bf16 v[48:51], v[178:181], v[186:189], 0
	v_mfma_f32_16x16x32_bf16 v[36:39], v[170:173], v[194:197], 0
	v_mfma_f32_16x16x32_bf16 v[32:35], v[178:181], v[194:197], 0
	v_mfma_f32_16x16x32_bf16 v[20:23], v[170:173], v[202:205], 0
	v_mfma_f32_16x16x32_bf16 v[16:19], v[178:181], v[202:205], 0
	v_mfma_f32_16x16x32_bf16 v[4:7], v[170:173], v[210:213], 0
	v_mfma_f32_16x16x32_bf16 v[0:3], v[178:181], v[210:213], 0
	v_mfma_f32_16x16x32_bf16 v[52:55], v[174:177], v[190:193], v[52:55]
	v_mfma_f32_16x16x32_bf16 v[48:51], v[182:185], v[190:193], v[48:51]
	v_mfma_f32_16x16x32_bf16 v[36:39], v[174:177], v[198:201], v[36:39]
	v_mfma_f32_16x16x32_bf16 v[32:35], v[182:185], v[198:201], v[32:35]
	v_mfma_f32_16x16x32_bf16 v[20:23], v[174:177], v[206:209], v[20:23]
	v_mfma_f32_16x16x32_bf16 v[16:19], v[182:185], v[206:209], v[16:19]
	v_mfma_f32_16x16x32_bf16 v[4:7], v[174:177], v[214:217], v[4:7]
	v_mfma_f32_16x16x32_bf16 v[0:3], v[182:185], v[214:217], v[0:3]
	s_setprio 0
	s_barrier
	s_add_i32 s33, 0, 0x18000
	s_add_i32 s84, 0, 0x1c000
	v_add_u32_e32 v166, s33, v137
	v_add_u32_e32 v182, s84, v137
	ds_read_b128 v[146:149], v166
	ds_read_b128 v[158:161], v166 offset:1024
	ds_read_b128 v[162:165], v166 offset:2048
	ds_read_b128 v[166:169], v166 offset:3072
	ds_read_b128 v[170:173], v182
	ds_read_b128 v[174:177], v182 offset:1024
	ds_read_b128 v[178:181], v182 offset:2048
	ds_read_b128 v[182:185], v182 offset:3072
	s_add_u32 s26, s66, 0x40000
	s_addc_u32 s27, s67, 0
	s_mov_b32 m0, s70
	ds_read_b128 v[186:189], v155 offset:32768
	ds_read_b128 v[190:193], v155 offset:33792
	ds_read_b128 v[194:197], v155 offset:34816
	ds_read_b128 v[198:201], v155 offset:35840
	ds_read_b128 v[202:205], v155 offset:36864
	ds_read_b128 v[206:209], v155 offset:37888
	ds_read_b128 v[210:213], v155 offset:38912
	ds_read_b128 v[214:217], v155 offset:39936
	global_load_lds_dwordx4 v128, s[26:27]
	s_mov_b32 m0, s71
	s_nop 0
	global_load_lds_dwordx4 v132, s[26:27]
	s_waitcnt vmcnt(8)
	s_waitcnt lgkmcnt(0)
	s_barrier
	s_setprio 1
	s_waitcnt lgkmcnt(0)
	v_mfma_f32_16x16x32_bf16 v[124:127], v[146:149], v[186:189], v[124:127]
	v_mfma_f32_16x16x32_bf16 v[120:123], v[162:165], v[186:189], v[120:123]
	v_mfma_f32_16x16x32_bf16 v[108:111], v[146:149], v[194:197], v[108:111]
	v_mfma_f32_16x16x32_bf16 v[104:107], v[162:165], v[194:197], v[104:107]
	v_mfma_f32_16x16x32_bf16 v[92:95], v[146:149], v[202:205], v[92:95]
	v_mfma_f32_16x16x32_bf16 v[88:91], v[162:165], v[202:205], v[88:91]
	v_mfma_f32_16x16x32_bf16 v[76:79], v[146:149], v[210:213], v[76:79]
	v_mfma_f32_16x16x32_bf16 v[72:75], v[162:165], v[210:213], v[72:75]
	v_mfma_f32_16x16x32_bf16 v[124:127], v[158:161], v[190:193], v[124:127]
	v_mfma_f32_16x16x32_bf16 v[120:123], v[166:169], v[190:193], v[120:123]
	v_mfma_f32_16x16x32_bf16 v[108:111], v[158:161], v[198:201], v[108:111]
	v_mfma_f32_16x16x32_bf16 v[104:107], v[166:169], v[198:201], v[104:107]
	v_mfma_f32_16x16x32_bf16 v[92:95], v[158:161], v[206:209], v[92:95]
	v_mfma_f32_16x16x32_bf16 v[88:91], v[166:169], v[206:209], v[88:91]
	v_mfma_f32_16x16x32_bf16 v[76:79], v[158:161], v[214:217], v[76:79]
	v_mfma_f32_16x16x32_bf16 v[72:75], v[166:169], v[214:217], v[72:75]
	s_setprio 0
	s_setprio 1
	v_mfma_f32_16x16x32_bf16 v[116:119], v[170:173], v[186:189], v[116:119]
	v_mfma_f32_16x16x32_bf16 v[112:115], v[178:181], v[186:189], v[112:115]
	v_mfma_f32_16x16x32_bf16 v[100:103], v[170:173], v[194:197], v[100:103]
	v_mfma_f32_16x16x32_bf16 v[96:99], v[178:181], v[194:197], v[96:99]
	v_mfma_f32_16x16x32_bf16 v[84:87], v[170:173], v[202:205], v[84:87]
	v_mfma_f32_16x16x32_bf16 v[80:83], v[178:181], v[202:205], v[80:83]
	v_mfma_f32_16x16x32_bf16 v[68:71], v[170:173], v[210:213], v[68:71]
	v_mfma_f32_16x16x32_bf16 v[64:67], v[178:181], v[210:213], v[64:67]
	v_mfma_f32_16x16x32_bf16 v[116:119], v[174:177], v[190:193], v[116:119]
	v_mfma_f32_16x16x32_bf16 v[112:115], v[182:185], v[190:193], v[112:115]
	v_mfma_f32_16x16x32_bf16 v[100:103], v[174:177], v[198:201], v[100:103]
	v_mfma_f32_16x16x32_bf16 v[96:99], v[182:185], v[198:201], v[96:99]
	v_mfma_f32_16x16x32_bf16 v[84:87], v[174:177], v[206:209], v[84:87]
	v_mfma_f32_16x16x32_bf16 v[80:83], v[182:185], v[206:209], v[80:83]
	v_mfma_f32_16x16x32_bf16 v[68:71], v[174:177], v[214:217], v[68:71]
	v_mfma_f32_16x16x32_bf16 v[64:67], v[182:185], v[214:217], v[64:67]
	s_setprio 0
	s_barrier
; #define PG8_STAGE(bufoff, gbase, voff) do { _Pragma("unroll") for (int _i = 0; _i < 2; ++_i) \
;         __builtin_amdgcn_global_load_lds((const unsigned*)((const char*)(gbase) + (voff)[_i]), (PG8_LAS unsigned*)(lds + (bufoff) + ldsw + _i * 8192), 16, 0, 0); } while (0)
; #define PG8_LDA(dst, b, h) do { _Pragma("unroll") for (int m = 0; m < 4; ++m) _Pragma("unroll") for (int k = 0; k < 2; ++k) dst[m][k] = *(const PG8_LAS bf16x8*)(lds + PG8_SA(b, h) + aoff + m * 2048 + k * 1024); } while (0)
; #define PG8_MMA(ai, bj, At, Bt) do { __builtin_amdgcn_s_setprio(1); _Pragma("unroll") for (int m = 0; m < 4; ++m) _Pragma("unroll") for (int n = 0; n < 2; ++n) _Pragma("unroll") for (int k = 0; k < 2; ++k) \
;         acc[ai][bj][m][n] = __builtin_amdgcn_mfma_f32_16x16x32_bf16(Bt[n][k], At[m][k], acc[ai][bj][m][n], 0, 0, 0); __builtin_amdgcn_s_setprio(0); } while (0)
; #define PG8_WAIT_V(n) asm volatile("s_waitcnt vmcnt(" #n ")" ::: "memory")
; #define PG8_WAIT_L(n) asm volatile("s_waitcnt lgkmcnt(" #n ")" ::: "memory")
; #define PG8_BAR __builtin_amdgcn_s_barrier()
; #define PG8_SCHED __builtin_amdgcn_sched_barrier(0)
; template <class Epi, class Sched, bool ALIGN_EPI = false, bool SP2 = false>
; __device__ __forceinline__ void gemm_phase(PG8_LAS unsigned char* lds, const Gemm g, const Sched& S, const Epi& E, int tid_in) {
;     ...
;             PG8_LDA(At, 1, 1); PG8_STAGE(PG8_SB(1, 0), b3, voffB); PG8_STAGE(PG8_SB(1, 1), b3 + hstepB, voffB); PG8_STAGE(PG8_SA(1, 0), a3, voffA);
;             PG8_WAIT_V(8); PG8_WAIT_L(0); PG8_BAR; PG8_MMA(1, 0, At, B0); PG8_MMA(1, 1, At, B1); PG8_BAR; PG8_SCHED;
	s_add_i32 s26, s33, s68
	s_add_i32 m0, s26, 0xffffff80
	ds_read_b128 v[186:189], v155 offset:49152
	ds_read_b128 v[190:193], v155 offset:50176
	ds_read_b128 v[194:197], v155 offset:51200
	ds_read_b128 v[198:201], v155 offset:52224
	ds_read_b128 v[202:205], v155 offset:53248
	ds_read_b128 v[206:209], v155 offset:54272
	ds_read_b128 v[210:213], v155 offset:55296
	ds_read_b128 v[214:217], v155 offset:56320
	global_load_lds_dwordx4 v130, s[64:65] offset:128
	s_add_i32 m0, s26, 0x1f80
	s_add_u32 s26, s64, 0x10080
	s_addc_u32 s27, s65, 0
	s_add_i32 s33, s84, s68
	global_load_lds_dwordx4 v134, s[64:65] offset:128
	s_mov_b32 m0, s33
	s_nop 0
	global_load_lds_dwordx4 v130, s[26:27]
	s_add_i32 m0, s33, 0x2000
	s_nop 0
	global_load_lds_dwordx4 v134, s[26:27]
	s_add_i32 m0, s73, 0xffffff80
	s_nop 0
	global_load_lds_dwordx4 v128, s[66:67] offset:128
	s_add_i32 m0, s74, 0xffffff80
	s_nop 0
	global_load_lds_dwordx4 v132, s[66:67] offset:128
	s_waitcnt vmcnt(8)
	s_waitcnt lgkmcnt(0)
	s_barrier
	s_setprio 1
	s_waitcnt lgkmcnt(0)
	v_mfma_f32_16x16x32_bf16 v[60:63], v[146:149], v[186:189], v[60:63]
	v_mfma_f32_16x16x32_bf16 v[56:59], v[162:165], v[186:189], v[56:59]
	v_mfma_f32_16x16x32_bf16 v[44:47], v[146:149], v[194:197], v[44:47]
	v_mfma_f32_16x16x32_bf16 v[40:43], v[162:165], v[194:197], v[40:43]
	v_mfma_f32_16x16x32_bf16 v[28:31], v[146:149], v[202:205], v[28:31]
	v_mfma_f32_16x16x32_bf16 v[24:27], v[162:165], v[202:205], v[24:27]
	v_mfma_f32_16x16x32_bf16 v[12:15], v[146:149], v[210:213], v[12:15]
	v_mfma_f32_16x16x32_bf16 v[8:11], v[162:165], v[210:213], v[8:11]
	v_mfma_f32_16x16x32_bf16 v[60:63], v[158:161], v[190:193], v[60:63]
	v_mfma_f32_16x16x32_bf16 v[56:59], v[166:169], v[190:193], v[56:59]
	v_mfma_f32_16x16x32_bf16 v[44:47], v[158:161], v[198:201], v[44:47]
	v_mfma_f32_16x16x32_bf16 v[40:43], v[166:169], v[198:201], v[40:43]
	v_mfma_f32_16x16x32_bf16 v[28:31], v[158:161], v[206:209], v[28:31]
	v_mfma_f32_16x16x32_bf16 v[24:27], v[166:169], v[206:209], v[24:27]
	v_mfma_f32_16x16x32_bf16 v[12:15], v[158:161], v[214:217], v[12:15]
	v_mfma_f32_16x16x32_bf16 v[8:11], v[166:169], v[214:217], v[8:11]
	s_setprio 0
	s_setprio 1
	v_mfma_f32_16x16x32_bf16 v[52:55], v[170:173], v[186:189], v[52:55]
	v_mfma_f32_16x16x32_bf16 v[48:51], v[178:181], v[186:189], v[48:51]
	v_mfma_f32_16x16x32_bf16 v[36:39], v[170:173], v[194:197], v[36:39]
	v_mfma_f32_16x16x32_bf16 v[32:35], v[178:181], v[194:197], v[32:35]
	v_mfma_f32_16x16x32_bf16 v[20:23], v[170:173], v[202:205], v[20:23]
	v_mfma_f32_16x16x32_bf16 v[16:19], v[178:181], v[202:205], v[16:19]
	v_mfma_f32_16x16x32_bf16 v[4:7], v[170:173], v[210:213], v[4:7]
	v_mfma_f32_16x16x32_bf16 v[0:3], v[178:181], v[210:213], v[0:3]
	v_mfma_f32_16x16x32_bf16 v[52:55], v[174:177], v[190:193], v[52:55]
	v_mfma_f32_16x16x32_bf16 v[48:51], v[182:185], v[190:193], v[48:51]
	v_mfma_f32_16x16x32_bf16 v[36:39], v[174:177], v[198:201], v[36:39]
	v_mfma_f32_16x16x32_bf16 v[32:35], v[182:185], v[198:201], v[32:35]
	v_mfma_f32_16x16x32_bf16 v[20:23], v[174:177], v[206:209], v[20:23]
	v_mfma_f32_16x16x32_bf16 v[16:19], v[182:185], v[206:209], v[16:19]
	v_mfma_f32_16x16x32_bf16 v[4:7], v[174:177], v[214:217], v[4:7]
	v_mfma_f32_16x16x32_bf16 v[0:3], v[182:185], v[214:217], v[0:3]
	s_setprio 0
	s_barrier
	s_add_i32 s83, s83, 2
	s_add_u32 s62, s62, 0x100
	s_addc_u32 s63, s63, 0
	s_add_u32 s78, s78, 0x100
	s_addc_u32 s79, s79, 0
	s_cmp_gt_u32 s83, 13

; #define PG8_STAGE(bufoff, gbase, voff) do { _Pragma("unroll") for (int _i = 0; _i < 2; ++_i) \
;         __builtin_amdgcn_global_load_lds((const unsigned*)((const char*)(gbase) + (voff)[_i]), (PG8_LAS unsigned*)(lds + (bufoff) + ldsw + _i * 8192), 16, 0, 0); } while (0)
; #define PG8_LDA(dst, b, h) do { _Pragma("unroll") for (int m = 0; m < 4; ++m) _Pragma("unroll") for (int k = 0; k < 2; ++k) dst[m][k] = *(const PG8_LAS bf16x8*)(lds + PG8_SA(b, h) + aoff + m * 2048 + k * 1024); } while (0)
; #define PG8_LDB(dst, b, h) do { _Pragma("unroll") for (int n = 0; n < 2; ++n) _Pragma("unroll") for (int k = 0; k < 2; ++k) dst[n][k] = *(const PG8_LAS bf16x8*)(lds + PG8_SB(b, h) + boff + n * 2048 + k * 1024); } while (0)
; #define PG8_WAIT_V(n) asm volatile("s_waitcnt vmcnt(" #n ")" ::: "memory")
; #define PG8_WAIT_L(n) asm volatile("s_waitcnt lgkmcnt(" #n ")" ::: "memory")
; #define PG8_BAR __builtin_amdgcn_s_barrier()
; #define PG8_SCHED __builtin_amdgcn_sched_barrier(0)
; template <class Epi, class Sched, bool ALIGN_EPI = false, bool SP2 = false>
; __device__ __forceinline__ void gemm_phase(PG8_LAS unsigned char* lds, const Gemm g, const Sched& S, const Epi& E, int tid_in) {
;     ...
;         const bool has_next = S.next(ui + 1, nxt);
;         const char* nA = has_next ? (const char*)g.A + (size_t)nxt.pm * tstep : cA; const char* nB = has_next ? (const char*)g.Bt + (size_t)nxt.pn * tstepB : cB;
;         for (int t = 0; t < nt; t += 2) {
;             const bool last = (t == nt - 2);
;             const char* a1 = cA + (size_t)(t + 1) * kstep;
;             const char* a2 = last ? nA : cA + (size_t)(t + 2) * kstep; const char* b2 = last ? nB : cB + (size_t)(t + 2) * kstep;
;             const char* a3 = a2 + kstep; const char* b3 = b2 + kstep;
;             if (last && has_next) S.a_ready(nxt);
;             if constexpr (SP2) {
;             PG8_LDB(B0, 0, 0); PG8_LDB(B1, 0, 1); PG8_SCHED; PG8_LDA(At, 0, 0); PG8_STAGE(PG8_SA(1, 1), a1 + hstep, voffA);
;             PG8_WAIT_V(8); PG8_WAIT_L(0); PG8_BAR; PG8_MMA(0, 0, At, B0); PG8_MMA(0, 1, At, B1); PG8_BAR; PG8_SCHED;
;             PG8_LDA(At, 0, 1); PG8_STAGE(PG8_SB(0, 0), b2, voffB); PG8_STAGE(PG8_SB(0, 1), b2 + hstepB, voffB); PG8_STAGE(PG8_SA(0, 0), a2, voffA);
;             PG8_WAIT_V(8); PG8_WAIT_L(0); PG8_BAR; PG8_MMA(1, 0, At, B0); PG8_MMA(1, 1, At, B1); PG8_BAR; PG8_SCHED;
.LBB0_868:
	s_ashr_i32 s41, s40, 31
	s_lshl_b64 s[26:27], s[40:41], 20
	s_add_u32 s44, s28, s26
	s_addc_u32 s45, s29, s27
	s_and_b64 s[26:27], s[8:9], exec
	s_cselect_b32 s41, s45, s51
	s_cselect_b32 s68, s44, s50
	s_ashr_i32 s39, s38, 31
	s_lshl_b64 s[26:27], s[38:39], 20
	s_add_u32 s46, s42, s26
	s_addc_u32 s47, s43, s27
	s_and_b64 s[26:27], s[8:9], exec
	s_cselect_b32 s39, s47, s53
	s_cselect_b32 s69, s46, s52
	s_add_u32 s50, s50, 0x80080
	s_addc_u32 s51, s51, 0
	s_add_u32 s70, s52, 0x100
	s_addc_u32 s71, s53, 0
	s_mov_b32 s72, -2
	ds_read_b128 v[156:159], v150
	ds_read_b128 v[160:163], v150 offset:1024
	ds_read_b128 v[164:167], v150 offset:2048
	ds_read_b128 v[168:171], v150 offset:3072
	ds_read_b128 v[172:175], v151
	ds_read_b128 v[176:179], v151 offset:1024
	ds_read_b128 v[180:183], v151 offset:2048
	ds_read_b128 v[184:187], v151 offset:3072
	s_add_u32 s26, s50, 0xfff80080
	s_addc_u32 s27, s51, -1
	s_cmp_eq_u32 s72, 28
	s_cselect_b32 s55, s41, s27
	s_cselect_b32 s54, s68, s26
	s_cselect_b32 s53, s39, s71
	s_cselect_b32 s52, s69, s70
	s_add_i32 m0, s49, 0xc000
	ds_read_b128 v[188:191], v152
	ds_read_b128 v[192:195], v152 offset:1024
	ds_read_b128 v[196:199], v152 offset:2048
	ds_read_b128 v[200:203], v152 offset:3072
	ds_read_b128 v[204:207], v152 offset:4096
	ds_read_b128 v[208:211], v152 offset:5120
	ds_read_b128 v[212:215], v152 offset:6144
	ds_read_b128 v[216:219], v152 offset:7168
	global_load_lds_dwordx4 v138, s[50:51]
	s_add_i32 m0, s49, 0xe000
	s_nop 0
	global_load_lds_dwordx4 v140, s[50:51]
	s_waitcnt vmcnt(8)
	s_waitcnt lgkmcnt(0)
	s_cmp_eq_u32 s98, 1
	s_cbranch_scc0 .Lkb_skip_6
	s_mov_b32 s98, 0
	s_barrier
.Lkb_skip_6:
	s_barrier
	s_setprio 1
	s_waitcnt lgkmcnt(0)
	v_mfma_f32_16x16x32_bf16 v[124:127], v[156:159], v[188:191], 0
	v_mfma_f32_16x16x32_bf16 v[120:123], v[164:167], v[188:191], 0
	v_mfma_f32_16x16x32_bf16 v[108:111], v[156:159], v[196:199], 0
	v_mfma_f32_16x16x32_bf16 v[104:107], v[164:167], v[196:199], 0
	v_mfma_f32_16x16x32_bf16 v[92:95], v[156:159], v[204:207], 0
	v_mfma_f32_16x16x32_bf16 v[88:91], v[164:167], v[204:207], 0
	v_mfma_f32_16x16x32_bf16 v[76:79], v[156:159], v[212:215], 0
	v_mfma_f32_16x16x32_bf16 v[72:75], v[164:167], v[212:215], 0
	v_mfma_f32_16x16x32_bf16 v[124:127], v[160:163], v[192:195], v[124:127]
	v_mfma_f32_16x16x32_bf16 v[120:123], v[168:171], v[192:195], v[120:123]
	v_mfma_f32_16x16x32_bf16 v[108:111], v[160:163], v[200:203], v[108:111]
	v_mfma_f32_16x16x32_bf16 v[104:107], v[168:171], v[200:203], v[104:107]
	v_mfma_f32_16x16x32_bf16 v[92:95], v[160:163], v[208:211], v[92:95]
	v_mfma_f32_16x16x32_bf16 v[88:91], v[168:171], v[208:211], v[88:91]
	v_mfma_f32_16x16x32_bf16 v[76:79], v[160:163], v[216:219], v[76:79]
	v_mfma_f32_16x16x32_bf16 v[72:75], v[168:171], v[216:219], v[72:75]
	s_setprio 0
	s_setprio 1
	v_mfma_f32_16x16x32_bf16 v[116:119], v[172:175], v[188:191], 0
	v_mfma_f32_16x16x32_bf16 v[112:115], v[180:183], v[188:191], 0
	v_mfma_f32_16x16x32_bf16 v[100:103], v[172:175], v[196:199], 0
	v_mfma_f32_16x16x32_bf16 v[96:99], v[180:183], v[196:199], 0
	v_mfma_f32_16x16x32_bf16 v[84:87], v[172:175], v[204:207], 0
	v_mfma_f32_16x16x32_bf16 v[80:83], v[180:183], v[204:207], 0
	v_mfma_f32_16x16x32_bf16 v[68:71], v[172:175], v[212:215], 0
	v_mfma_f32_16x16x32_bf16 v[64:67], v[180:183], v[212:215], 0
	v_mfma_f32_16x16x32_bf16 v[116:119], v[176:179], v[192:195], v[116:119]
	v_mfma_f32_16x16x32_bf16 v[112:115], v[184:187], v[192:195], v[112:115]
	v_mfma_f32_16x16x32_bf16 v[100:103], v[176:179], v[200:203], v[100:103]
	v_mfma_f32_16x16x32_bf16 v[96:99], v[184:187], v[200:203], v[96:99]
	v_mfma_f32_16x16x32_bf16 v[84:87], v[176:179], v[208:211], v[84:87]
	v_mfma_f32_16x16x32_bf16 v[80:83], v[184:187], v[208:211], v[80:83]
	v_mfma_f32_16x16x32_bf16 v[68:71], v[176:179], v[216:219], v[68:71]
	v_mfma_f32_16x16x32_bf16 v[64:67], v[184:187], v[216:219], v[64:67]
	s_setprio 0
	s_barrier
	s_add_i32 s26, s64, s56
	s_mov_b32 m0, s26
	ds_read_b128 v[188:191], v152 offset:16384
	ds_read_b128 v[192:195], v152 offset:17408
	ds_read_b128 v[196:199], v152 offset:18432
	ds_read_b128 v[200:203], v152 offset:19456
	ds_read_b128 v[204:207], v152 offset:20480
	ds_read_b128 v[208:211], v152 offset:21504
	ds_read_b128 v[212:215], v152 offset:22528
	ds_read_b128 v[216:219], v152 offset:23552
	global_load_lds_dwordx4 v130, s[52:53]
	s_add_i32 m0, s26, 0x2000
	s_add_u32 s26, s52, 0x20000
	s_addc_u32 s27, s53, 0
	s_add_i32 s33, s65, s56
	global_load_lds_dwordx4 v134, s[52:53]
	s_mov_b32 m0, s33
	s_nop 0
	global_load_lds_dwordx4 v130, s[26:27]
	s_add_i32 m0, s33, 0x2000
	s_nop 0
	global_load_lds_dwordx4 v134, s[26:27]
	s_mov_b32 m0, s49
	s_nop 0
	global_load_lds_dwordx4 v128, s[54:55]
	s_mov_b32 m0, s57
	s_nop 0
	global_load_lds_dwordx4 v132, s[54:55]
	s_waitcnt vmcnt(8)
	s_waitcnt lgkmcnt(0)
	s_barrier
; #define PG8_STAGE(bufoff, gbase, voff) do { _Pragma("unroll") for (int _i = 0; _i < 2; ++_i) \
;         __builtin_amdgcn_global_load_lds((const unsigned*)((const char*)(gbase) + (voff)[_i]), (PG8_LAS unsigned*)(lds + (bufoff) + ldsw + _i * 8192), 16, 0, 0); } while (0)
; #define PG8_LDA(dst, b, h) do { _Pragma("unroll") for (int m = 0; m < 4; ++m) _Pragma("unroll") for (int k = 0; k < 2; ++k) dst[m][k] = *(const PG8_LAS bf16x8*)(lds + PG8_SA(b, h) + aoff + m * 2048 + k * 1024); } while (0)
; #define PG8_LDB(dst, b, h) do { _Pragma("unroll") for (int n = 0; n < 2; ++n) _Pragma("unroll") for (int k = 0; k < 2; ++k) dst[n][k] = *(const PG8_LAS bf16x8*)(lds + PG8_SB(b, h) + boff + n * 2048 + k * 1024); } while (0)
; #define PG8_MMA(ai, bj, At, Bt) do { __builtin_amdgcn_s_setprio(1); _Pragma("unroll") for (int m = 0; m < 4; ++m) _Pragma("unroll") for (int n = 0; n < 2; ++n) _Pragma("unroll") for (int k = 0; k < 2; ++k) \
;         acc[ai][bj][m][n] = __builtin_amdgcn_mfma_f32_16x16x32_bf16(Bt[n][k], At[m][k], acc[ai][bj][m][n], 0, 0, 0); __builtin_amdgcn_s_setprio(0); } while (0)
; #define PG8_WAIT_V(n) asm volatile("s_waitcnt vmcnt(" #n ")" ::: "memory")
; #define PG8_WAIT_L(n) asm volatile("s_waitcnt lgkmcnt(" #n ")" ::: "memory")
; #define PG8_BAR __builtin_amdgcn_s_barrier()
; #define PG8_SCHED __builtin_amdgcn_sched_barrier(0)
; template <class Epi, class Sched, bool ALIGN_EPI = false, bool SP2 = false>
; __device__ __forceinline__ void gemm_phase(PG8_LAS unsigned char* lds, const Gemm g, const Sched& S, const Epi& E, int tid_in) {
;     ...
;             PG8_WAIT_V(8); PG8_WAIT_L(0); PG8_BAR; PG8_MMA(1, 0, At, B0); PG8_MMA(1, 1, At, B1); PG8_BAR; PG8_SCHED;
;             PG8_LDB(B0, 1, 0); PG8_LDB(B1, 1, 1); PG8_SCHED; PG8_LDA(At, 1, 0); PG8_STAGE(PG8_SA(0, 1), a2 + hstep, voffA);
;             PG8_WAIT_V(8); PG8_WAIT_L(0); PG8_BAR; PG8_MMA(0, 0, At, B0); PG8_MMA(0, 1, At, B1); PG8_BAR; PG8_SCHED;
	s_setprio 1
	s_waitcnt lgkmcnt(0)
	v_mfma_f32_16x16x32_bf16 v[60:63], v[156:159], v[188:191], 0
	v_mfma_f32_16x16x32_bf16 v[56:59], v[164:167], v[188:191], 0
	v_mfma_f32_16x16x32_bf16 v[44:47], v[156:159], v[196:199], 0
	v_mfma_f32_16x16x32_bf16 v[40:43], v[164:167], v[196:199], 0
	v_mfma_f32_16x16x32_bf16 v[28:31], v[156:159], v[204:207], 0
	v_mfma_f32_16x16x32_bf16 v[24:27], v[164:167], v[204:207], 0
	v_mfma_f32_16x16x32_bf16 v[12:15], v[156:159], v[212:215], 0
	v_mfma_f32_16x16x32_bf16 v[8:11], v[164:167], v[212:215], 0
	v_mfma_f32_16x16x32_bf16 v[60:63], v[160:163], v[192:195], v[60:63]
	v_mfma_f32_16x16x32_bf16 v[56:59], v[168:171], v[192:195], v[56:59]
	v_mfma_f32_16x16x32_bf16 v[44:47], v[160:163], v[200:203], v[44:47]
	v_mfma_f32_16x16x32_bf16 v[40:43], v[168:171], v[200:203], v[40:43]
	v_mfma_f32_16x16x32_bf16 v[28:31], v[160:163], v[208:211], v[28:31]
	v_mfma_f32_16x16x32_bf16 v[24:27], v[168:171], v[208:211], v[24:27]
	v_mfma_f32_16x16x32_bf16 v[12:15], v[160:163], v[216:219], v[12:15]
	v_mfma_f32_16x16x32_bf16 v[8:11], v[168:171], v[216:219], v[8:11]
	s_setprio 0
	s_setprio 1
	v_mfma_f32_16x16x32_bf16 v[52:55], v[172:175], v[188:191], 0
	v_mfma_f32_16x16x32_bf16 v[48:51], v[180:183], v[188:191], 0
	v_mfma_f32_16x16x32_bf16 v[36:39], v[172:175], v[196:199], 0
	v_mfma_f32_16x16x32_bf16 v[32:35], v[180:183], v[196:199], 0
	v_mfma_f32_16x16x32_bf16 v[20:23], v[172:175], v[204:207], 0
	v_mfma_f32_16x16x32_bf16 v[16:19], v[180:183], v[204:207], 0
	v_mfma_f32_16x16x32_bf16 v[4:7], v[172:175], v[212:215], 0
	v_mfma_f32_16x16x32_bf16 v[0:3], v[180:183], v[212:215], 0
	v_mfma_f32_16x16x32_bf16 v[52:55], v[176:179], v[192:195], v[52:55]
	v_mfma_f32_16x16x32_bf16 v[48:51], v[184:187], v[192:195], v[48:51]
	v_mfma_f32_16x16x32_bf16 v[36:39], v[176:179], v[200:203], v[36:39]
	v_mfma_f32_16x16x32_bf16 v[32:35], v[184:187], v[200:203], v[32:35]
	v_mfma_f32_16x16x32_bf16 v[20:23], v[176:179], v[208:211], v[20:23]
	v_mfma_f32_16x16x32_bf16 v[16:19], v[184:187], v[208:211], v[16:19]
	v_mfma_f32_16x16x32_bf16 v[4:7], v[176:179], v[216:219], v[4:7]
	v_mfma_f32_16x16x32_bf16 v[0:3], v[184:187], v[216:219], v[0:3]
	s_setprio 0
	s_barrier
	s_add_i32 s33, 0, 0x18000
	v_add_u32_e32 v155, s33, v146
	s_add_i32 s73, 0, 0x1c000
	ds_read_b128 v[156:159], v155
	ds_read_b128 v[160:163], v155 offset:1024
	ds_read_b128 v[164:167], v155 offset:2048
	ds_read_b128 v[168:171], v155 offset:3072
	v_add_u32_e32 v155, s73, v146
	ds_read_b128 v[172:175], v155
	ds_read_b128 v[176:179], v155 offset:1024
	ds_read_b128 v[180:183], v155 offset:2048
	ds_read_b128 v[184:187], v155 offset:3072
	s_add_u32 s26, s54, 0x80000
	s_addc_u32 s27, s55, 0
	s_mov_b32 m0, s58
	ds_read_b128 v[188:191], v152 offset:32768
	ds_read_b128 v[192:195], v152 offset:33792
	ds_read_b128 v[196:199], v152 offset:34816
	ds_read_b128 v[200:203], v152 offset:35840
	ds_read_b128 v[204:207], v152 offset:36864
	ds_read_b128 v[208:211], v152 offset:37888
	ds_read_b128 v[212:215], v152 offset:38912
	ds_read_b128 v[216:219], v152 offset:39936
	global_load_lds_dwordx4 v128, s[26:27]
	s_mov_b32 m0, s59
	s_nop 0
	global_load_lds_dwordx4 v132, s[26:27]
	s_waitcnt vmcnt(8)
	s_waitcnt lgkmcnt(0)
	s_barrier
	s_setprio 1
	s_waitcnt lgkmcnt(0)
	v_mfma_f32_16x16x32_bf16 v[124:127], v[156:159], v[188:191], v[124:127]
	v_mfma_f32_16x16x32_bf16 v[120:123], v[164:167], v[188:191], v[120:123]
	v_mfma_f32_16x16x32_bf16 v[108:111], v[156:159], v[196:199], v[108:111]
	v_mfma_f32_16x16x32_bf16 v[104:107], v[164:167], v[196:199], v[104:107]
	v_mfma_f32_16x16x32_bf16 v[92:95], v[156:159], v[204:207], v[92:95]
	v_mfma_f32_16x16x32_bf16 v[88:91], v[164:167], v[204:207], v[88:91]
	v_mfma_f32_16x16x32_bf16 v[76:79], v[156:159], v[212:215], v[76:79]
	v_mfma_f32_16x16x32_bf16 v[72:75], v[164:167], v[212:215], v[72:75]
	v_mfma_f32_16x16x32_bf16 v[124:127], v[160:163], v[192:195], v[124:127]
	v_mfma_f32_16x16x32_bf16 v[120:123], v[168:171], v[192:195], v[120:123]
	v_mfma_f32_16x16x32_bf16 v[108:111], v[160:163], v[200:203], v[108:111]
	v_mfma_f32_16x16x32_bf16 v[104:107], v[168:171], v[200:203], v[104:107]
	v_mfma_f32_16x16x32_bf16 v[92:95], v[160:163], v[208:211], v[92:95]
	v_mfma_f32_16x16x32_bf16 v[88:91], v[168:171], v[208:211], v[88:91]
	v_mfma_f32_16x16x32_bf16 v[76:79], v[160:163], v[216:219], v[76:79]
	v_mfma_f32_16x16x32_bf16 v[72:75], v[168:171], v[216:219], v[72:75]
	s_setprio 0
	s_setprio 1
	v_mfma_f32_16x16x32_bf16 v[116:119], v[172:175], v[188:191], v[116:119]
	v_mfma_f32_16x16x32_bf16 v[112:115], v[180:183], v[188:191], v[112:115]
	v_mfma_f32_16x16x32_bf16 v[100:103], v[172:175], v[196:199], v[100:103]
	v_mfma_f32_16x16x32_bf16 v[96:99], v[180:183], v[196:199], v[96:99]
	v_mfma_f32_16x16x32_bf16 v[84:87], v[172:175], v[204:207], v[84:87]
	v_mfma_f32_16x16x32_bf16 v[80:83], v[180:183], v[204:207], v[80:83]
	v_mfma_f32_16x16x32_bf16 v[68:71], v[172:175], v[212:215], v[68:71]
	v_mfma_f32_16x16x32_bf16 v[64:67], v[180:183], v[212:215], v[64:67]
	v_mfma_f32_16x16x32_bf16 v[116:119], v[176:179], v[192:195], v[116:119]
	v_mfma_f32_16x16x32_bf16 v[112:115], v[184:187], v[192:195], v[112:115]
	v_mfma_f32_16x16x32_bf16 v[100:103], v[176:179], v[200:203], v[100:103]
	v_mfma_f32_16x16x32_bf16 v[96:99], v[184:187], v[200:203], v[96:99]
	v_mfma_f32_16x16x32_bf16 v[84:87], v[176:179], v[208:211], v[84:87]
	v_mfma_f32_16x16x32_bf16 v[80:83], v[184:187], v[208:211], v[80:83]
	v_mfma_f32_16x16x32_bf16 v[68:71], v[176:179], v[216:219], v[68:71]
	v_mfma_f32_16x16x32_bf16 v[64:67], v[184:187], v[216:219], v[64:67]
	s_setprio 0
	s_barrier
; #define PG8_STAGE(bufoff, gbase, voff) do { _Pragma("unroll") for (int _i = 0; _i < 2; ++_i) \
;         __builtin_amdgcn_global_load_lds((const unsigned*)((const char*)(gbase) + (voff)[_i]), (PG8_LAS unsigned*)(lds + (bufoff) + ldsw + _i * 8192), 16, 0, 0); } while (0)
; #define PG8_LDA(dst, b, h) do { _Pragma("unroll") for (int m = 0; m < 4; ++m) _Pragma("unroll") for (int k = 0; k < 2; ++k) dst[m][k] = *(const PG8_LAS bf16x8*)(lds + PG8_SA(b, h) + aoff + m * 2048 + k * 1024); } while (0)
; #define PG8_MMA(ai, bj, At, Bt) do { __builtin_amdgcn_s_setprio(1); _Pragma("unroll") for (int m = 0; m < 4; ++m) _Pragma("unroll") for (int n = 0; n < 2; ++n) _Pragma("unroll") for (int k = 0; k < 2; ++k) \
;         acc[ai][bj][m][n] = __builtin_amdgcn_mfma_f32_16x16x32_bf16(Bt[n][k], At[m][k], acc[ai][bj][m][n], 0, 0, 0); __builtin_amdgcn_s_setprio(0); } while (0)
; #define PG8_WAIT_V(n) asm volatile("s_waitcnt vmcnt(" #n ")" ::: "memory")
; #define PG8_WAIT_L(n) asm volatile("s_waitcnt lgkmcnt(" #n ")" ::: "memory")
; #define PG8_BAR __builtin_amdgcn_s_barrier()
; #define PG8_SCHED __builtin_amdgcn_sched_barrier(0)
; template <class Epi, class Sched, bool ALIGN_EPI = false, bool SP2 = false>
; __device__ __forceinline__ void gemm_phase(PG8_LAS unsigned char* lds, const Gemm g, const Sched& S, const Epi& E, int tid_in) {
;     ...
;         for (int t = 0; t < nt; t += 2) {
;             const bool last = (t == nt - 2);
;             const char* a1 = cA + (size_t)(t + 1) * kstep;
;             const char* a2 = last ? nA : cA + (size_t)(t + 2) * kstep; const char* b2 = last ? nB : cB + (size_t)(t + 2) * kstep;
;     ...
;             PG8_LDA(At, 1, 1); PG8_STAGE(PG8_SB(1, 0), b3, voffB); PG8_STAGE(PG8_SB(1, 1), b3 + hstepB, voffB); PG8_STAGE(PG8_SA(1, 0), a3, voffA);
;             PG8_WAIT_V(8); PG8_WAIT_L(0); PG8_BAR; PG8_MMA(1, 0, At, B0); PG8_MMA(1, 1, At, B1); PG8_BAR; PG8_SCHED;
	s_add_i32 s26, s33, s56
	s_add_i32 m0, s26, 0xffffff80
	ds_read_b128 v[188:191], v152 offset:49152
	ds_read_b128 v[192:195], v152 offset:50176
	ds_read_b128 v[196:199], v152 offset:51200
	ds_read_b128 v[200:203], v152 offset:52224
	ds_read_b128 v[204:207], v152 offset:53248
	ds_read_b128 v[208:211], v152 offset:54272
	ds_read_b128 v[212:215], v152 offset:55296
	ds_read_b128 v[216:219], v152 offset:56320
	global_load_lds_dwordx4 v130, s[52:53] offset:128
	s_add_i32 m0, s26, 0x1f80
	s_add_u32 s26, s52, 0x20080
	s_addc_u32 s27, s53, 0
	s_add_i32 s33, s73, s56
	global_load_lds_dwordx4 v134, s[52:53] offset:128
	s_mov_b32 m0, s33
	s_nop 0
	global_load_lds_dwordx4 v130, s[26:27]
	s_add_i32 m0, s33, 0x2000
	s_nop 0
	global_load_lds_dwordx4 v134, s[26:27]
	s_add_i32 m0, s62, 0xffffff80
	s_nop 0
	global_load_lds_dwordx4 v128, s[54:55] offset:128
	s_add_i32 m0, s63, 0xffffff80
	s_nop 0
	global_load_lds_dwordx4 v132, s[54:55] offset:128
	s_waitcnt vmcnt(8)
	s_waitcnt lgkmcnt(0)
	s_barrier
	s_setprio 1
	s_waitcnt lgkmcnt(0)
	v_mfma_f32_16x16x32_bf16 v[60:63], v[156:159], v[188:191], v[60:63]
	v_mfma_f32_16x16x32_bf16 v[56:59], v[164:167], v[188:191], v[56:59]
	v_mfma_f32_16x16x32_bf16 v[44:47], v[156:159], v[196:199], v[44:47]
	v_mfma_f32_16x16x32_bf16 v[40:43], v[164:167], v[196:199], v[40:43]
	v_mfma_f32_16x16x32_bf16 v[28:31], v[156:159], v[204:207], v[28:31]
	v_mfma_f32_16x16x32_bf16 v[24:27], v[164:167], v[204:207], v[24:27]
	v_mfma_f32_16x16x32_bf16 v[12:15], v[156:159], v[212:215], v[12:15]
	v_mfma_f32_16x16x32_bf16 v[8:11], v[164:167], v[212:215], v[8:11]
	v_mfma_f32_16x16x32_bf16 v[60:63], v[160:163], v[192:195], v[60:63]
	v_mfma_f32_16x16x32_bf16 v[56:59], v[168:171], v[192:195], v[56:59]
	v_mfma_f32_16x16x32_bf16 v[44:47], v[160:163], v[200:203], v[44:47]
	v_mfma_f32_16x16x32_bf16 v[40:43], v[168:171], v[200:203], v[40:43]
	v_mfma_f32_16x16x32_bf16 v[28:31], v[160:163], v[208:211], v[28:31]
	v_mfma_f32_16x16x32_bf16 v[24:27], v[168:171], v[208:211], v[24:27]
	v_mfma_f32_16x16x32_bf16 v[12:15], v[160:163], v[216:219], v[12:15]
	v_mfma_f32_16x16x32_bf16 v[8:11], v[168:171], v[216:219], v[8:11]
	s_setprio 0
	s_setprio 1
	v_mfma_f32_16x16x32_bf16 v[52:55], v[172:175], v[188:191], v[52:55]
	v_mfma_f32_16x16x32_bf16 v[48:51], v[180:183], v[188:191], v[48:51]
	v_mfma_f32_16x16x32_bf16 v[36:39], v[172:175], v[196:199], v[36:39]
	v_mfma_f32_16x16x32_bf16 v[32:35], v[180:183], v[196:199], v[32:35]
	v_mfma_f32_16x16x32_bf16 v[20:23], v[172:175], v[204:207], v[20:23]
	v_mfma_f32_16x16x32_bf16 v[16:19], v[180:183], v[204:207], v[16:19]
	v_mfma_f32_16x16x32_bf16 v[4:7], v[172:175], v[212:215], v[4:7]
	v_mfma_f32_16x16x32_bf16 v[0:3], v[180:183], v[212:215], v[0:3]
	v_mfma_f32_16x16x32_bf16 v[52:55], v[176:179], v[192:195], v[52:55]
	v_mfma_f32_16x16x32_bf16 v[48:51], v[184:187], v[192:195], v[48:51]
	v_mfma_f32_16x16x32_bf16 v[36:39], v[176:179], v[200:203], v[36:39]
	v_mfma_f32_16x16x32_bf16 v[32:35], v[184:187], v[200:203], v[32:35]
	v_mfma_f32_16x16x32_bf16 v[20:23], v[176:179], v[208:211], v[20:23]
	v_mfma_f32_16x16x32_bf16 v[16:19], v[184:187], v[208:211], v[16:19]
	v_mfma_f32_16x16x32_bf16 v[4:7], v[176:179], v[216:219], v[4:7]
	v_mfma_f32_16x16x32_bf16 v[0:3], v[184:187], v[216:219], v[0:3]
	s_setprio 0
	s_barrier
	s_add_i32 s72, s72, 2
	s_add_u32 s50, s50, 0x100
	s_addc_u32 s51, s51, 0
	s_add_u32 s70, s70, 0x100
	s_addc_u32 s71, s71, 0
	s_cmp_gt_u32 s72, 29

; #define PG8_STAGE(bufoff, gbase, voff) do { _Pragma("unroll") for (int _i = 0; _i < 2; ++_i) \
;         __builtin_amdgcn_global_load_lds((const unsigned*)((const char*)(gbase) + (voff)[_i]), (PG8_LAS unsigned*)(lds + (bufoff) + ldsw + _i * 8192), 16, 0, 0); } while (0)
; #define PG8_LDA(dst, b, h) do { _Pragma("unroll") for (int m = 0; m < 4; ++m) _Pragma("unroll") for (int k = 0; k < 2; ++k) dst[m][k] = *(const PG8_LAS bf16x8*)(lds + PG8_SA(b, h) + aoff + m * 2048 + k * 1024); } while (0)
; #define PG8_LDB(dst, b, h) do { _Pragma("unroll") for (int n = 0; n < 2; ++n) _Pragma("unroll") for (int k = 0; k < 2; ++k) dst[n][k] = *(const PG8_LAS bf16x8*)(lds + PG8_SB(b, h) + boff + n * 2048 + k * 1024); } while (0)
; #define PG8_WAIT_V(n) asm volatile("s_waitcnt vmcnt(" #n ")" ::: "memory")
; #define PG8_WAIT_L(n) asm volatile("s_waitcnt lgkmcnt(" #n ")" ::: "memory")
; #define PG8_BAR __builtin_amdgcn_s_barrier()
; #define PG8_SCHED __builtin_amdgcn_sched_barrier(0)
; template <class Epi, class Sched, bool ALIGN_EPI = false, bool SP2 = false>
; __device__ __forceinline__ void gemm_phase(PG8_LAS unsigned char* lds, const Gemm g, const Sched& S, const Epi& E, int tid_in) {
;     ...
;         const bool has_next = S.next(ui + 1, nxt);
;         const char* nA = has_next ? (const char*)g.A + (size_t)nxt.pm * tstep : cA; const char* nB = has_next ? (const char*)g.Bt + (size_t)nxt.pn * tstepB : cB;
;         for (int t = 0; t < nt; t += 2) {
;             const bool last = (t == nt - 2);
;             const char* a1 = cA + (size_t)(t + 1) * kstep;
;             const char* a2 = last ? nA : cA + (size_t)(t + 2) * kstep; const char* b2 = last ? nB : cB + (size_t)(t + 2) * kstep;
;             const char* a3 = a2 + kstep; const char* b3 = b2 + kstep;
;             if (last && has_next) S.a_ready(nxt);
;             if constexpr (SP2) {
;             PG8_LDB(B0, 0, 0); PG8_LDB(B1, 0, 1); PG8_SCHED; PG8_LDA(At, 0, 0); PG8_STAGE(PG8_SA(1, 1), a1 + hstep, voffA);
;             PG8_WAIT_V(8); PG8_WAIT_L(0); PG8_BAR; PG8_MMA(0, 0, At, B0); PG8_MMA(0, 1, At, B1); PG8_BAR; PG8_SCHED;
;             PG8_LDA(At, 0, 1); PG8_STAGE(PG8_SB(0, 0), b2, voffB); PG8_STAGE(PG8_SB(0, 1), b2 + hstepB, voffB); PG8_STAGE(PG8_SA(0, 0), a2, voffA);
;             PG8_WAIT_V(8); PG8_WAIT_L(0); PG8_BAR; PG8_MMA(1, 0, At, B0); PG8_MMA(1, 1, At, B1); PG8_BAR; PG8_SCHED;
.LBB0_948:
	s_ashr_i32 s43, s42, 31
	s_lshl_b64 s[26:27], s[42:43], 22
	s_add_u32 s46, s14, s26
	s_addc_u32 s47, s15, s27
	s_and_b64 s[10:11], s[10:11], exec
	s_cselect_b32 s43, s47, s53
	s_cselect_b32 s67, s46, s52
	s_add_u32 s68, s52, 0x100
	s_addc_u32 s69, s53, 0
	s_mov_b32 s70, -2
	s_waitcnt lgkmcnt(0)
	ds_read_b128 v[146:149], v153
	ds_read_b128 v[158:161], v153 offset:1024
	ds_read_b128 v[162:165], v153 offset:2048
	ds_read_b128 v[166:169], v153 offset:3072
	ds_read_b128 v[170:173], v154
	ds_read_b128 v[174:177], v154 offset:1024
	ds_read_b128 v[178:181], v154 offset:2048
	ds_read_b128 v[182:185], v154 offset:3072
	s_add_u32 s10, s50, 0x100
	s_addc_u32 s11, s51, 0
	s_cmpk_eq_i32 s70, 0x7c
	s_cselect_b32 s55, s45, s11
	s_cselect_b32 s54, s44, s10
	s_cselect_b32 s53, s43, s69
	s_cselect_b32 s52, s67, s68
	s_add_i32 m0, s49, 0xc000
	ds_read_b128 v[186:189], v155
	ds_read_b128 v[190:193], v155 offset:1024
	ds_read_b128 v[194:197], v155 offset:2048
	ds_read_b128 v[198:201], v155 offset:3072
	ds_read_b128 v[202:205], v155 offset:4096
	ds_read_b128 v[206:209], v155 offset:5120
	ds_read_b128 v[210:213], v155 offset:6144
	ds_read_b128 v[214:217], v155 offset:7168
	global_load_lds_dwordx4 v138, s[50:51]
	s_add_i32 m0, s49, 0xe000
	s_nop 0
	global_load_lds_dwordx4 v140, s[50:51]
	s_waitcnt vmcnt(8)
	s_waitcnt lgkmcnt(0)
	s_cmp_eq_u32 s98, 1
	s_cbranch_scc0 .Lkb_skip_7
	s_mov_b32 s98, 0
	s_barrier
.Lkb_skip_7:
	s_barrier
	s_setprio 1
	s_waitcnt lgkmcnt(0)
	v_mfma_f32_16x16x32_bf16 v[124:127], v[146:149], v[186:189], 0
	v_mfma_f32_16x16x32_bf16 v[120:123], v[162:165], v[186:189], 0
	v_mfma_f32_16x16x32_bf16 v[108:111], v[146:149], v[194:197], 0
	v_mfma_f32_16x16x32_bf16 v[104:107], v[162:165], v[194:197], 0
	v_mfma_f32_16x16x32_bf16 v[92:95], v[146:149], v[202:205], 0
	v_mfma_f32_16x16x32_bf16 v[88:91], v[162:165], v[202:205], 0
	v_mfma_f32_16x16x32_bf16 v[76:79], v[146:149], v[210:213], 0
	v_mfma_f32_16x16x32_bf16 v[72:75], v[162:165], v[210:213], 0
	v_mfma_f32_16x16x32_bf16 v[124:127], v[158:161], v[190:193], v[124:127]
	v_mfma_f32_16x16x32_bf16 v[120:123], v[166:169], v[190:193], v[120:123]
	v_mfma_f32_16x16x32_bf16 v[108:111], v[158:161], v[198:201], v[108:111]
	v_mfma_f32_16x16x32_bf16 v[104:107], v[166:169], v[198:201], v[104:107]
	v_mfma_f32_16x16x32_bf16 v[92:95], v[158:161], v[206:209], v[92:95]
	v_mfma_f32_16x16x32_bf16 v[88:91], v[166:169], v[206:209], v[88:91]
	v_mfma_f32_16x16x32_bf16 v[76:79], v[158:161], v[214:217], v[76:79]
	v_mfma_f32_16x16x32_bf16 v[72:75], v[166:169], v[214:217], v[72:75]
	s_setprio 0
	s_setprio 1
	v_mfma_f32_16x16x32_bf16 v[116:119], v[170:173], v[186:189], 0
	v_mfma_f32_16x16x32_bf16 v[112:115], v[178:181], v[186:189], 0
	v_mfma_f32_16x16x32_bf16 v[100:103], v[170:173], v[194:197], 0
	v_mfma_f32_16x16x32_bf16 v[96:99], v[178:181], v[194:197], 0
	v_mfma_f32_16x16x32_bf16 v[84:87], v[170:173], v[202:205], 0
	v_mfma_f32_16x16x32_bf16 v[80:83], v[178:181], v[202:205], 0
	v_mfma_f32_16x16x32_bf16 v[68:71], v[170:173], v[210:213], 0
	v_mfma_f32_16x16x32_bf16 v[64:67], v[178:181], v[210:213], 0
	v_mfma_f32_16x16x32_bf16 v[116:119], v[174:177], v[190:193], v[116:119]
	v_mfma_f32_16x16x32_bf16 v[112:115], v[182:185], v[190:193], v[112:115]
	v_mfma_f32_16x16x32_bf16 v[100:103], v[174:177], v[198:201], v[100:103]
	v_mfma_f32_16x16x32_bf16 v[96:99], v[182:185], v[198:201], v[96:99]
	v_mfma_f32_16x16x32_bf16 v[84:87], v[174:177], v[206:209], v[84:87]
	v_mfma_f32_16x16x32_bf16 v[80:83], v[182:185], v[206:209], v[80:83]
	v_mfma_f32_16x16x32_bf16 v[68:71], v[174:177], v[214:217], v[68:71]
	v_mfma_f32_16x16x32_bf16 v[64:67], v[182:185], v[214:217], v[64:67]
	s_setprio 0
	s_barrier
	s_add_i32 s26, s63, s56
	s_mov_b32 m0, s26
	ds_read_b128 v[186:189], v155 offset:16384
	ds_read_b128 v[190:193], v155 offset:17408
	ds_read_b128 v[194:197], v155 offset:18432
	ds_read_b128 v[198:201], v155 offset:19456
	ds_read_b128 v[202:205], v155 offset:20480
	ds_read_b128 v[206:209], v155 offset:21504
	ds_read_b128 v[210:213], v155 offset:22528
	ds_read_b128 v[214:217], v155 offset:23552
	global_load_lds_dwordx4 v130, s[52:53]
	s_add_i32 m0, s26, 0x2000
	s_add_u32 s26, s52, 0x80000
	s_addc_u32 s27, s53, 0
	s_add_i32 s33, s64, s56
	global_load_lds_dwordx4 v134, s[52:53]
	s_mov_b32 m0, s33
	s_nop 0
	global_load_lds_dwordx4 v130, s[26:27]
	s_add_i32 m0, s33, 0x2000
	s_nop 0
	global_load_lds_dwordx4 v134, s[26:27]
	s_mov_b32 m0, s49
	s_nop 0
	global_load_lds_dwordx4 v128, s[54:55]
	s_mov_b32 m0, s57
	s_nop 0
	global_load_lds_dwordx4 v132, s[54:55]
	s_waitcnt vmcnt(8)
	s_waitcnt lgkmcnt(0)
	s_barrier
; #define PG8_STAGE(bufoff, gbase, voff) do { _Pragma("unroll") for (int _i = 0; _i < 2; ++_i) \
;         __builtin_amdgcn_global_load_lds((const unsigned*)((const char*)(gbase) + (voff)[_i]), (PG8_LAS unsigned*)(lds + (bufoff) + ldsw + _i * 8192), 16, 0, 0); } while (0)
; #define PG8_LDA(dst, b, h) do { _Pragma("unroll") for (int m = 0; m < 4; ++m) _Pragma("unroll") for (int k = 0; k < 2; ++k) dst[m][k] = *(const PG8_LAS bf16x8*)(lds + PG8_SA(b, h) + aoff + m * 2048 + k * 1024); } while (0)
; #define PG8_LDB(dst, b, h) do { _Pragma("unroll") for (int n = 0; n < 2; ++n) _Pragma("unroll") for (int k = 0; k < 2; ++k) dst[n][k] = *(const PG8_LAS bf16x8*)(lds + PG8_SB(b, h) + boff + n * 2048 + k * 1024); } while (0)
; #define PG8_MMA(ai, bj, At, Bt) do { __builtin_amdgcn_s_setprio(1); _Pragma("unroll") for (int m = 0; m < 4; ++m) _Pragma("unroll") for (int n = 0; n < 2; ++n) _Pragma("unroll") for (int k = 0; k < 2; ++k) \
;         acc[ai][bj][m][n] = __builtin_amdgcn_mfma_f32_16x16x32_bf16(Bt[n][k], At[m][k], acc[ai][bj][m][n], 0, 0, 0); __builtin_amdgcn_s_setprio(0); } while (0)
; #define PG8_WAIT_V(n) asm volatile("s_waitcnt vmcnt(" #n ")" ::: "memory")
; #define PG8_WAIT_L(n) asm volatile("s_waitcnt lgkmcnt(" #n ")" ::: "memory")
; #define PG8_BAR __builtin_amdgcn_s_barrier()
; #define PG8_SCHED __builtin_amdgcn_sched_barrier(0)
; template <class Epi, class Sched, bool ALIGN_EPI = false, bool SP2 = false>
; __device__ __forceinline__ void gemm_phase(PG8_LAS unsigned char* lds, const Gemm g, const Sched& S, const Epi& E, int tid_in) {
;     ...
;             PG8_WAIT_V(8); PG8_WAIT_L(0); PG8_BAR; PG8_MMA(1, 0, At, B0); PG8_MMA(1, 1, At, B1); PG8_BAR; PG8_SCHED;
;             PG8_LDB(B0, 1, 0); PG8_LDB(B1, 1, 1); PG8_SCHED; PG8_LDA(At, 1, 0); PG8_STAGE(PG8_SA(0, 1), a2 + hstep, voffA);
;             PG8_WAIT_V(8); PG8_WAIT_L(0); PG8_BAR; PG8_MMA(0, 0, At, B0); PG8_MMA(0, 1, At, B1); PG8_BAR; PG8_SCHED;
	s_setprio 1
	s_waitcnt lgkmcnt(0)
	v_mfma_f32_16x16x32_bf16 v[60:63], v[146:149], v[186:189], 0
	v_mfma_f32_16x16x32_bf16 v[56:59], v[162:165], v[186:189], 0
	v_mfma_f32_16x16x32_bf16 v[44:47], v[146:149], v[194:197], 0
	v_mfma_f32_16x16x32_bf16 v[40:43], v[162:165], v[194:197], 0
	v_mfma_f32_16x16x32_bf16 v[28:31], v[146:149], v[202:205], 0
	v_mfma_f32_16x16x32_bf16 v[24:27], v[162:165], v[202:205], 0
	v_mfma_f32_16x16x32_bf16 v[12:15], v[146:149], v[210:213], 0
	v_mfma_f32_16x16x32_bf16 v[8:11], v[162:165], v[210:213], 0
	v_mfma_f32_16x16x32_bf16 v[60:63], v[158:161], v[190:193], v[60:63]
	v_mfma_f32_16x16x32_bf16 v[56:59], v[166:169], v[190:193], v[56:59]
	v_mfma_f32_16x16x32_bf16 v[44:47], v[158:161], v[198:201], v[44:47]
	v_mfma_f32_16x16x32_bf16 v[40:43], v[166:169], v[198:201], v[40:43]
	v_mfma_f32_16x16x32_bf16 v[28:31], v[158:161], v[206:209], v[28:31]
	v_mfma_f32_16x16x32_bf16 v[24:27], v[166:169], v[206:209], v[24:27]
	v_mfma_f32_16x16x32_bf16 v[12:15], v[158:161], v[214:217], v[12:15]
	v_mfma_f32_16x16x32_bf16 v[8:11], v[166:169], v[214:217], v[8:11]
	s_setprio 0
	s_setprio 1
	v_mfma_f32_16x16x32_bf16 v[52:55], v[170:173], v[186:189], 0
	v_mfma_f32_16x16x32_bf16 v[48:51], v[178:181], v[186:189], 0
	v_mfma_f32_16x16x32_bf16 v[36:39], v[170:173], v[194:197], 0
	v_mfma_f32_16x16x32_bf16 v[32:35], v[178:181], v[194:197], 0
	v_mfma_f32_16x16x32_bf16 v[20:23], v[170:173], v[202:205], 0
	v_mfma_f32_16x16x32_bf16 v[16:19], v[178:181], v[202:205], 0
	v_mfma_f32_16x16x32_bf16 v[4:7], v[170:173], v[210:213], 0
	v_mfma_f32_16x16x32_bf16 v[0:3], v[178:181], v[210:213], 0
	v_mfma_f32_16x16x32_bf16 v[52:55], v[174:177], v[190:193], v[52:55]
	v_mfma_f32_16x16x32_bf16 v[48:51], v[182:185], v[190:193], v[48:51]
	v_mfma_f32_16x16x32_bf16 v[36:39], v[174:177], v[198:201], v[36:39]
	v_mfma_f32_16x16x32_bf16 v[32:35], v[182:185], v[198:201], v[32:35]
	v_mfma_f32_16x16x32_bf16 v[20:23], v[174:177], v[206:209], v[20:23]
	v_mfma_f32_16x16x32_bf16 v[16:19], v[182:185], v[206:209], v[16:19]
	v_mfma_f32_16x16x32_bf16 v[4:7], v[174:177], v[214:217], v[4:7]
	v_mfma_f32_16x16x32_bf16 v[0:3], v[182:185], v[214:217], v[0:3]
	s_setprio 0
	s_barrier
	s_add_i32 s33, 0, 0x18000
	s_add_i32 s50, 0, 0x1c000
	v_add_u32_e32 v166, s33, v137
	v_add_u32_e32 v182, s50, v137
	ds_read_b128 v[146:149], v166
	ds_read_b128 v[158:161], v166 offset:1024
	ds_read_b128 v[162:165], v166 offset:2048
	ds_read_b128 v[166:169], v166 offset:3072
	ds_read_b128 v[170:173], v182
	ds_read_b128 v[174:177], v182 offset:1024
	ds_read_b128 v[178:181], v182 offset:2048
	ds_read_b128 v[182:185], v182 offset:3072
	s_add_u32 s26, s54, 0x204000
	s_addc_u32 s27, s55, 0
	s_mov_b32 m0, s58
	ds_read_b128 v[186:189], v155 offset:32768
	ds_read_b128 v[190:193], v155 offset:33792
	ds_read_b128 v[194:197], v155 offset:34816
	ds_read_b128 v[198:201], v155 offset:35840
	ds_read_b128 v[202:205], v155 offset:36864
	ds_read_b128 v[206:209], v155 offset:37888
	ds_read_b128 v[210:213], v155 offset:38912
	ds_read_b128 v[214:217], v155 offset:39936
	global_load_lds_dwordx4 v128, s[26:27]
	s_mov_b32 m0, s59
	s_nop 0
	global_load_lds_dwordx4 v132, s[26:27]
	s_waitcnt vmcnt(8)
	s_waitcnt lgkmcnt(0)
	s_barrier
	s_setprio 1
	s_waitcnt lgkmcnt(0)
	v_mfma_f32_16x16x32_bf16 v[124:127], v[146:149], v[186:189], v[124:127]
	v_mfma_f32_16x16x32_bf16 v[120:123], v[162:165], v[186:189], v[120:123]
	v_mfma_f32_16x16x32_bf16 v[108:111], v[146:149], v[194:197], v[108:111]
	v_mfma_f32_16x16x32_bf16 v[104:107], v[162:165], v[194:197], v[104:107]
	v_mfma_f32_16x16x32_bf16 v[92:95], v[146:149], v[202:205], v[92:95]
	v_mfma_f32_16x16x32_bf16 v[88:91], v[162:165], v[202:205], v[88:91]
	v_mfma_f32_16x16x32_bf16 v[76:79], v[146:149], v[210:213], v[76:79]
	v_mfma_f32_16x16x32_bf16 v[72:75], v[162:165], v[210:213], v[72:75]
	v_mfma_f32_16x16x32_bf16 v[124:127], v[158:161], v[190:193], v[124:127]
	v_mfma_f32_16x16x32_bf16 v[120:123], v[166:169], v[190:193], v[120:123]
	v_mfma_f32_16x16x32_bf16 v[108:111], v[158:161], v[198:201], v[108:111]
	v_mfma_f32_16x16x32_bf16 v[104:107], v[166:169], v[198:201], v[104:107]
	v_mfma_f32_16x16x32_bf16 v[92:95], v[158:161], v[206:209], v[92:95]
	v_mfma_f32_16x16x32_bf16 v[88:91], v[166:169], v[206:209], v[88:91]
	v_mfma_f32_16x16x32_bf16 v[76:79], v[158:161], v[214:217], v[76:79]
	v_mfma_f32_16x16x32_bf16 v[72:75], v[166:169], v[214:217], v[72:75]
	s_setprio 0
	s_setprio 1
	v_mfma_f32_16x16x32_bf16 v[116:119], v[170:173], v[186:189], v[116:119]
	v_mfma_f32_16x16x32_bf16 v[112:115], v[178:181], v[186:189], v[112:115]
	v_mfma_f32_16x16x32_bf16 v[100:103], v[170:173], v[194:197], v[100:103]
	v_mfma_f32_16x16x32_bf16 v[96:99], v[178:181], v[194:197], v[96:99]
	v_mfma_f32_16x16x32_bf16 v[84:87], v[170:173], v[202:205], v[84:87]
	v_mfma_f32_16x16x32_bf16 v[80:83], v[178:181], v[202:205], v[80:83]
	v_mfma_f32_16x16x32_bf16 v[68:71], v[170:173], v[210:213], v[68:71]
	v_mfma_f32_16x16x32_bf16 v[64:67], v[178:181], v[210:213], v[64:67]
	v_mfma_f32_16x16x32_bf16 v[116:119], v[174:177], v[190:193], v[116:119]
	v_mfma_f32_16x16x32_bf16 v[112:115], v[182:185], v[190:193], v[112:115]
	v_mfma_f32_16x16x32_bf16 v[100:103], v[174:177], v[198:201], v[100:103]
	v_mfma_f32_16x16x32_bf16 v[96:99], v[182:185], v[198:201], v[96:99]
	v_mfma_f32_16x16x32_bf16 v[84:87], v[174:177], v[206:209], v[84:87]
	v_mfma_f32_16x16x32_bf16 v[80:83], v[182:185], v[206:209], v[80:83]
	v_mfma_f32_16x16x32_bf16 v[68:71], v[174:177], v[214:217], v[68:71]
	v_mfma_f32_16x16x32_bf16 v[64:67], v[182:185], v[214:217], v[64:67]
	s_setprio 0
	s_barrier
; #define PG8_STAGE(bufoff, gbase, voff) do { _Pragma("unroll") for (int _i = 0; _i < 2; ++_i) \
;         __builtin_amdgcn_global_load_lds((const unsigned*)((const char*)(gbase) + (voff)[_i]), (PG8_LAS unsigned*)(lds + (bufoff) + ldsw + _i * 8192), 16, 0, 0); } while (0)
; #define PG8_LDA(dst, b, h) do { _Pragma("unroll") for (int m = 0; m < 4; ++m) _Pragma("unroll") for (int k = 0; k < 2; ++k) dst[m][k] = *(const PG8_LAS bf16x8*)(lds + PG8_SA(b, h) + aoff + m * 2048 + k * 1024); } while (0)
; #define PG8_MMA(ai, bj, At, Bt) do { __builtin_amdgcn_s_setprio(1); _Pragma("unroll") for (int m = 0; m < 4; ++m) _Pragma("unroll") for (int n = 0; n < 2; ++n) _Pragma("unroll") for (int k = 0; k < 2; ++k) \
;         acc[ai][bj][m][n] = __builtin_amdgcn_mfma_f32_16x16x32_bf16(Bt[n][k], At[m][k], acc[ai][bj][m][n], 0, 0, 0); __builtin_amdgcn_s_setprio(0); } while (0)
; #define PG8_WAIT_V(n) asm volatile("s_waitcnt vmcnt(" #n ")" ::: "memory")
; #define PG8_WAIT_L(n) asm volatile("s_waitcnt lgkmcnt(" #n ")" ::: "memory")
; #define PG8_BAR __builtin_amdgcn_s_barrier()
; #define PG8_SCHED __builtin_amdgcn_sched_barrier(0)
; template <class Epi, class Sched, bool ALIGN_EPI = false, bool SP2 = false>
; __device__ __forceinline__ void gemm_phase(PG8_LAS unsigned char* lds, const Gemm g, const Sched& S, const Epi& E, int tid_in) {
;     ...
;         for (int t = 0; t < nt; t += 2) {
;             const bool last = (t == nt - 2);
;             const char* a1 = cA + (size_t)(t + 1) * kstep;
;             const char* a2 = last ? nA : cA + (size_t)(t + 2) * kstep; const char* b2 = last ? nB : cB + (size_t)(t + 2) * kstep;
;     ...
;             PG8_LDA(At, 1, 1); PG8_STAGE(PG8_SB(1, 0), b3, voffB); PG8_STAGE(PG8_SB(1, 1), b3 + hstepB, voffB); PG8_STAGE(PG8_SA(1, 0), a3, voffA);
;             PG8_WAIT_V(8); PG8_WAIT_L(0); PG8_BAR; PG8_MMA(1, 0, At, B0); PG8_MMA(1, 1, At, B1); PG8_BAR; PG8_SCHED;
	s_add_i32 s26, s33, s56
	s_add_i32 m0, s26, 0xffffff80
	ds_read_b128 v[186:189], v155 offset:49152
	ds_read_b128 v[190:193], v155 offset:50176
	ds_read_b128 v[194:197], v155 offset:51200
	ds_read_b128 v[198:201], v155 offset:52224
	ds_read_b128 v[202:205], v155 offset:53248
	ds_read_b128 v[206:209], v155 offset:54272
	ds_read_b128 v[210:213], v155 offset:55296
	ds_read_b128 v[214:217], v155 offset:56320
	global_load_lds_dwordx4 v130, s[52:53] offset:128
	s_add_i32 m0, s26, 0x1f80
	s_add_u32 s26, s52, 0x80080
	s_addc_u32 s27, s53, 0
	s_add_i32 s33, s50, s56
	global_load_lds_dwordx4 v134, s[52:53] offset:128
	s_mov_b32 m0, s33
	s_nop 0
	global_load_lds_dwordx4 v130, s[26:27]
	s_add_i32 m0, s33, 0x2000
	s_nop 0
	global_load_lds_dwordx4 v134, s[26:27]
	s_add_i32 m0, s61, 0xffffff80
	s_nop 0
	global_load_lds_dwordx4 v128, s[54:55] offset:128
	s_add_i32 m0, s62, 0xffffff80
	s_nop 0
	global_load_lds_dwordx4 v132, s[54:55] offset:128
	s_waitcnt vmcnt(8)
	s_waitcnt lgkmcnt(0)
	s_barrier
	s_setprio 1
	s_waitcnt lgkmcnt(0)
	v_mfma_f32_16x16x32_bf16 v[60:63], v[146:149], v[186:189], v[60:63]
	v_mfma_f32_16x16x32_bf16 v[56:59], v[162:165], v[186:189], v[56:59]
	v_mfma_f32_16x16x32_bf16 v[44:47], v[146:149], v[194:197], v[44:47]
	v_mfma_f32_16x16x32_bf16 v[40:43], v[162:165], v[194:197], v[40:43]
	v_mfma_f32_16x16x32_bf16 v[28:31], v[146:149], v[202:205], v[28:31]
	v_mfma_f32_16x16x32_bf16 v[24:27], v[162:165], v[202:205], v[24:27]
	v_mfma_f32_16x16x32_bf16 v[12:15], v[146:149], v[210:213], v[12:15]
	v_mfma_f32_16x16x32_bf16 v[8:11], v[162:165], v[210:213], v[8:11]
	v_mfma_f32_16x16x32_bf16 v[60:63], v[158:161], v[190:193], v[60:63]
	v_mfma_f32_16x16x32_bf16 v[56:59], v[166:169], v[190:193], v[56:59]
	v_mfma_f32_16x16x32_bf16 v[44:47], v[158:161], v[198:201], v[44:47]
	v_mfma_f32_16x16x32_bf16 v[40:43], v[166:169], v[198:201], v[40:43]
	v_mfma_f32_16x16x32_bf16 v[28:31], v[158:161], v[206:209], v[28:31]
	v_mfma_f32_16x16x32_bf16 v[24:27], v[166:169], v[206:209], v[24:27]
	v_mfma_f32_16x16x32_bf16 v[12:15], v[158:161], v[214:217], v[12:15]
	v_mfma_f32_16x16x32_bf16 v[8:11], v[166:169], v[214:217], v[8:11]
	s_setprio 0
	s_setprio 1
	v_mfma_f32_16x16x32_bf16 v[52:55], v[170:173], v[186:189], v[52:55]
	v_mfma_f32_16x16x32_bf16 v[48:51], v[178:181], v[186:189], v[48:51]
	v_mfma_f32_16x16x32_bf16 v[36:39], v[170:173], v[194:197], v[36:39]
	v_mfma_f32_16x16x32_bf16 v[32:35], v[178:181], v[194:197], v[32:35]
	v_mfma_f32_16x16x32_bf16 v[20:23], v[170:173], v[202:205], v[20:23]
	v_mfma_f32_16x16x32_bf16 v[16:19], v[178:181], v[202:205], v[16:19]
	v_mfma_f32_16x16x32_bf16 v[4:7], v[170:173], v[210:213], v[4:7]
	v_mfma_f32_16x16x32_bf16 v[0:3], v[178:181], v[210:213], v[0:3]
	v_mfma_f32_16x16x32_bf16 v[52:55], v[174:177], v[190:193], v[52:55]
	v_mfma_f32_16x16x32_bf16 v[48:51], v[182:185], v[190:193], v[48:51]
	v_mfma_f32_16x16x32_bf16 v[36:39], v[174:177], v[198:201], v[36:39]
	v_mfma_f32_16x16x32_bf16 v[32:35], v[182:185], v[198:201], v[32:35]
	v_mfma_f32_16x16x32_bf16 v[20:23], v[174:177], v[206:209], v[20:23]
	v_mfma_f32_16x16x32_bf16 v[16:19], v[182:185], v[206:209], v[16:19]
	v_mfma_f32_16x16x32_bf16 v[4:7], v[174:177], v[214:217], v[4:7]
	v_mfma_f32_16x16x32_bf16 v[0:3], v[182:185], v[214:217], v[0:3]
	s_setprio 0
	s_barrier
	s_add_i32 s70, s70, 2
	s_add_u32 s68, s68, 0x100
	s_addc_u32 s69, s69, 0
	s_cmpk_gt_u32 s70, 0x7d
	s_mov_b64 s[50:51], s[10:11]
